# lever 7 instruction selection: 363 64-bit address adds in the scan phases as s_mov + v_lshl_add_u64 instead of v_add_co / s_nop / v_addc_co
# speedup vs baseline: 1.0052x; 1.0052x over previous
.LBB0_1041:
	v_ashrrev_i32_e32 v0, 31, v92
	v_lshrrev_b32_e32 v1, 30, v0
	v_add_u32_e32 v1, v92, v1
	v_lshrrev_b32_e32 v0, 27, v0
	v_bfe_u32 v34, v1, 2, 3
	v_add_u32_e32 v0, v92, v0
	v_ashrrev_i32_e32 v32, 5, v0
	v_lshlrev_b32_e32 v0, 2, v34
	global_load_dword v0, v0, s[84:85] offset:32
	v_and_b32_e32 v2, 0x3fffffc, v1
	v_sub_u32_e32 v2, v92, v2
	s_mov_b32 s50, 0x3fb8aa3b
	v_lshlrev_b32_e32 v78, 6, v2
	v_readlane_b32 s80, v241, 18
	v_readlane_b32 s88, v241, 26
	v_readlane_b32 s89, v241, 27
	v_ashrrev_i32_e32 v79, 31, v78
	s_waitcnt vmcnt(0)
	v_mov_b32_e32 v67, v65
	v_mov_b32_e32 v69, v65
	v_mov_b32_e32 v71, v65
	v_readlane_b32 s81, v241, 19
	v_readlane_b32 s82, v241, 20
	v_readlane_b32 s83, v241, 21
	v_readlane_b32 s84, v241, 22
	v_readlane_b32 s85, v241, 23
	v_readlane_b32 s86, v241, 24
	v_readlane_b32 s87, v241, 25
	v_readlane_b32 s90, v241, 28
	v_readlane_b32 s91, v241, 29
	v_readlane_b32 s92, v241, 30
	v_readlane_b32 s93, v241, 31
	v_readlane_b32 s94, v241, 32
	v_readlane_b32 s95, v241, 33
	s_waitcnt vmcnt(0)
	v_mul_f32_e32 v1, 0x3fb8aa3b, v0
	v_fma_f32 v2, v0, s50, -v1
	v_rndne_f32_e32 v3, v1
	v_fmac_f32_e32 v2, 0x32a5705f, v0
	v_sub_f32_e32 v1, v1, v3
	v_add_f32_e32 v1, v1, v2
	v_exp_f32_e32 v1, v1
	v_cvt_i32_f32_e32 v2, v3
	s_mov_b32 s50, 0xc2ce8ed0
	v_cmp_ngt_f32_e32 vcc, s50, v0
	s_mov_b32 s50, 0x42b17218
	v_ldexp_f32 v1, v1, v2
	v_cndmask_b32_e32 v1, 0, v1, vcc
	v_cmp_nlt_f32_e32 vcc, s50, v0
	s_mov_b32 s50, 0x3f2aaaab
	s_nop 0
	v_cndmask_b32_e32 v2, v129, v1, vcc
	v_sub_f32_e32 v3, 1.0, v2
	v_add_f32_e32 v0, -1.0, v3
	v_sub_f32_e32 v1, v0, v3
	v_add_f32_e32 v1, 1.0, v1
	v_sub_f32_e64 v0, -v2, v0
	v_add_f32_e32 v4, v0, v1
	v_frexp_mant_f32_e32 v0, v3
	v_cmp_gt_f32_e32 vcc, s50, v0
	v_cvt_f64_f32_e32 v[0:1], v3
	v_frexp_exp_i32_f64_e32 v0, v[0:1]
	v_subbrev_co_u32_e32 v0, vcc, 0, v0, vcc
	v_sub_u32_e32 v1, 0, v0
	v_ldexp_f32 v3, v3, v1
	v_ldexp_f32 v1, v4, v1
	v_add_f32_e32 v4, -1.0, v3
	v_add_f32_e32 v5, 1.0, v4
	v_sub_f32_e32 v5, v3, v5
	v_add_f32_e32 v5, v1, v5
	v_add_f32_e32 v6, v4, v5
	v_sub_f32_e32 v4, v6, v4
	v_sub_f32_e32 v4, v5, v4
	v_add_f32_e32 v5, 1.0, v3
	v_add_f32_e32 v7, -1.0, v5
	v_sub_f32_e32 v3, v3, v7
	v_add_f32_e32 v1, v1, v3
	v_add_f32_e32 v3, v5, v1
	v_sub_f32_e32 v5, v3, v5
	v_sub_f32_e32 v1, v1, v5
	v_rcp_f32_e32 v5, v3
	v_cvt_f32_i32_e32 v0, v0
	s_mov_b32 s50, 0x3f317218
	v_cmp_nlt_f32_e32 vcc, 1.0, v2
	v_mul_f32_e32 v7, v6, v5
	v_mul_f32_e32 v8, v3, v7
	v_fma_f32 v9, v7, v3, -v8
	v_fmac_f32_e32 v9, v7, v1
	v_add_f32_e32 v10, v8, v9
	v_sub_f32_e32 v11, v6, v10
	v_sub_f32_e32 v6, v6, v11
	v_sub_f32_e32 v8, v10, v8
	v_sub_f32_e32 v6, v6, v10
	v_add_f32_e32 v4, v4, v6
	v_sub_f32_e32 v6, v8, v9
	v_add_f32_e32 v4, v6, v4
	v_add_f32_e32 v6, v11, v4
	v_mul_f32_e32 v8, v5, v6
	v_mul_f32_e32 v9, v3, v8
	v_fma_f32 v3, v8, v3, -v9
	v_fmac_f32_e32 v3, v8, v1
	v_sub_f32_e32 v1, v11, v6
	v_add_f32_e32 v1, v4, v1
	v_add_f32_e32 v4, v9, v3
	v_sub_f32_e32 v10, v6, v4
	v_sub_f32_e32 v6, v6, v10
	v_sub_f32_e32 v9, v4, v9
	v_sub_f32_e32 v4, v6, v4
	v_add_f32_e32 v1, v1, v4
	v_sub_f32_e32 v3, v9, v3
	v_add_f32_e32 v1, v3, v1
	v_add_f32_e32 v3, v7, v8
	v_add_f32_e32 v1, v10, v1
	v_sub_f32_e32 v4, v3, v7
	v_mul_f32_e32 v1, v5, v1
	v_sub_f32_e32 v4, v8, v4
	v_add_f32_e32 v1, v4, v1
	v_mul_f32_e32 v7, 0x3f317218, v0
	v_add_f32_e32 v4, v3, v1
	v_fma_f32 v8, v0, s50, -v7
	v_mul_f32_e32 v5, v4, v4
	v_fmac_f32_e32 v8, 0xb102e308, v0
	v_sub_f32_e32 v0, v4, v3
	v_fmamk_f32 v6, v5, 0x3e9b6dac, v104
	v_sub_f32_e32 v0, v1, v0
	v_add_f32_e32 v1, v7, v8
	v_fmaak_f32 v6, v5, v6, 0x3f2aaada
	v_sub_f32_e32 v3, v1, v7
	v_ldexp_f32 v7, v4, 1
	v_mul_f32_e32 v4, v4, v5
	v_mul_f32_e32 v4, v4, v6
	v_add_f32_e32 v5, v7, v4
	v_sub_f32_e32 v6, v5, v7
	v_ldexp_f32 v0, v0, 1
	v_sub_f32_e32 v4, v4, v6
	v_add_f32_e32 v0, v0, v4
	v_add_f32_e32 v4, v5, v0
	v_sub_f32_e32 v5, v4, v5
	v_sub_f32_e32 v0, v0, v5
	v_add_f32_e32 v5, v1, v4
	v_sub_f32_e32 v6, v5, v1
	v_sub_f32_e32 v7, v5, v6
	v_sub_f32_e32 v3, v8, v3
	v_sub_f32_e32 v1, v1, v7
	v_sub_f32_e32 v4, v4, v6
	v_add_f32_e32 v1, v4, v1
	v_add_f32_e32 v4, v3, v0
	v_sub_f32_e32 v6, v4, v3
	v_sub_f32_e32 v7, v4, v6
	v_sub_f32_e32 v3, v3, v7
	v_sub_f32_e32 v0, v0, v6
	v_add_f32_e32 v1, v4, v1
	v_add_f32_e32 v0, v0, v3
	v_add_f32_e32 v3, v5, v1
	v_sub_f32_e32 v4, v3, v5
	v_sub_f32_e32 v1, v1, v4
	v_add_f32_e32 v0, v0, v1
	v_add_f32_e32 v0, v3, v0
	v_cndmask_b32_e32 v0, v130, v0, vcc
	v_cmp_neq_f32_e32 vcc, 1.0, v2
	s_mov_b32 s50, 0x33800000
	v_cmp_lt_f32_e64 s[54:55], |v2|, s50
	v_cndmask_b32_e32 v0, v131, v0, vcc
	s_mov_b32 s50, 0x8000
	v_cndmask_b32_e64 v0, v0, -v2, s[54:55]
	v_mul_f32_e32 v33, 0x3fb8aa3b, v0
	v_lshlrev_b32_e32 v0, 4, v32
	v_or3_b32 v0, v0, v34, 8
	v_ashrrev_i32_e32 v1, 31, v0
	v_lshlrev_b64 v[0:1], 17, v[0:1]
	v_lshl_add_u64 v[0:1], s[88:89], 0, v[0:1]
	v_lshl_add_u64 v[0:1], v[78:79], 2, v[0:1]
	v_lshl_add_u64 v[0:1], v[0:1], 0, v[66:67]
	v_lshl_add_u64 v[0:1], v[0:1], 0, v[68:69]
	v_lshl_add_u64 v[28:29], v[0:1], 0, v[70:71]
	global_load_dword v4, v[28:29], off
	global_load_dword v5, v[28:29], off offset:1024
	global_load_dword v6, v[28:29], off offset:2048
	global_load_dword v7, v[28:29], off offset:3072
	s_mov_b32 s98, s56
	s_mov_b32 s99, 0
	v_lshl_add_u64 v[8:9], v[28:29], 0, s[98:99]
	s_mov_b32 s98, s50
	s_mov_b32 s99, 0
	v_lshl_add_u64 v[12:13], v[28:29], 0, s[98:99]
	s_mov_b32 s50, 0xc000
	s_mov_b32 s98, s50
	s_mov_b32 s99, 0
	v_lshl_add_u64 v[16:17], v[28:29], 0, s[98:99]
	s_mov_b32 s50, 0x10000
	s_mov_b32 s98, s50
	s_mov_b32 s99, 0
	v_lshl_add_u64 v[20:21], v[28:29], 0, s[98:99]
	s_mov_b32 s50, 0x14000
	s_mov_b32 s98, s50
	s_mov_b32 s99, 0
	v_lshl_add_u64 v[24:25], v[28:29], 0, s[98:99]
	global_load_dword v0, v[8:9], off
	global_load_dword v1, v[8:9], off offset:1024
	global_load_dword v2, v[8:9], off offset:2048
	global_load_dword v3, v[8:9], off offset:3072
	s_mov_b64 s[98:99], 0x18000
	v_lshl_add_u64 v[30:31], v[28:29], 0, s[98:99]
	global_load_dword v8, v[12:13], off
	global_load_dword v9, v[12:13], off offset:1024
	global_load_dword v10, v[12:13], off offset:2048
	global_load_dword v11, v[12:13], off offset:3072
	v_add_co_u32_e32 v36, vcc, 0x1c000, v28
	global_load_dword v12, v[16:17], off
	global_load_dword v13, v[16:17], off offset:1024
	global_load_dword v14, v[16:17], off offset:2048
	global_load_dword v15, v[16:17], off offset:3072
	v_addc_co_u32_e32 v37, vcc, 0, v29, vcc
	global_load_dword v16, v[20:21], off
	global_load_dword v17, v[20:21], off offset:1024
	global_load_dword v18, v[20:21], off offset:2048
	global_load_dword v19, v[20:21], off offset:3072
	s_nop 0
	global_load_dword v20, v[24:25], off
	global_load_dword v21, v[24:25], off offset:1024
	global_load_dword v22, v[24:25], off offset:2048
	global_load_dword v23, v[24:25], off offset:3072
	s_nop 0
	global_load_dword v24, v[30:31], off
	global_load_dword v25, v[30:31], off offset:1024
	global_load_dword v26, v[30:31], off offset:2048
	global_load_dword v27, v[30:31], off offset:3072
	global_load_dword v28, v[36:37], off
	global_load_dword v29, v[36:37], off offset:1024
	s_nop 0
	global_load_dword v30, v[36:37], off offset:2048
	global_load_dword v31, v[36:37], off offset:3072
	s_and_saveexec_b64 s[54:55], s[40:41]
	s_cbranch_execz .LBB0_1043
	v_mul_f32_e32 v35, v33, v93
	v_exp_f32_e64 v37, -v35
	v_exp_f32_e32 v36, v35
	ds_write_b64 v105, v[36:37]

.LBB0_1045:
	s_or_b64 exec, exec, s[54:55]
	v_ashrrev_i32_e32 v33, 31, v32
	v_lshlrev_b64 v[36:37], 11, v[32:33]
	s_mov_b64 s[54:55], 0x2000
	v_lshl_add_u64 v[36:37], v[36:37], 0, s[54:55]
	v_lshlrev_b64 v[38:39], 11, v[36:37]
	v_lshlrev_b64 v[36:37], 12, v[36:37]
	v_lshlrev_b32_e32 v64, 8, v34
	v_lshl_add_u64 v[36:37], s[46:47], 0, v[36:37]
	v_lshlrev_b32_e32 v34, 9, v34
	v_mov_b32_e32 v35, v65
	v_lshl_add_u64 v[40:41], s[68:69], 0, v[38:39]
	v_lshl_add_u64 v[38:39], s[44:45], 0, v[38:39]
	v_lshl_add_u64 v[34:35], v[36:37], 0, v[34:35]
	v_lshl_add_u64 v[40:41], v[40:41], 0, v[64:65]
	v_lshl_add_u64 v[38:39], v[38:39], 0, v[64:65]
	v_lshl_add_u64 v[34:35], v[78:79], 1, v[34:35]
	v_mov_b32_e32 v73, v65
	v_mov_b32_e32 v75, v65
	v_lshl_add_u64 v[82:83], v[40:41], 0, v[72:73]
	v_lshl_add_u64 v[84:85], v[38:39], 0, v[72:73]
	v_lshl_add_u64 v[86:87], v[34:35], 0, v[74:75]
	s_mov_b64 s[54:55], 0x7c0000
	v_lshl_add_u64 v[36:37], v[82:83], 0, s[52:53]
	v_lshl_add_u64 v[38:39], v[84:85], 0, s[52:53]
	v_lshl_add_u64 v[34:35], v[86:87], 0, s[54:55]
	s_waitcnt lgkmcnt(0)
	s_barrier
	global_load_dword v67, v[36:37], off
	global_load_dword v71, v[36:37], off offset:2048
	global_load_dword v69, v[38:39], off
	global_load_dword v73, v[38:39], off offset:2048
	s_mov_b32 s98, s57
	s_mov_b32 s99, 0
	v_lshl_add_u64 v[40:41], v[36:37], 0, s[98:99]
	v_readlane_b32 s80, v241, 37
	s_nop 0
	s_mov_b32 s98, s57
	s_mov_b32 s99, 0
	v_lshl_add_u64 v[42:43], v[38:39], 0, s[98:99]
	s_mov_b32 s54, 0
	s_nop 0
	global_load_dword v75, v[40:41], off
	global_load_dword v136, v[40:41], off offset:2048
	global_load_dword v135, v[42:43], off
	global_load_dword v137, v[42:43], off offset:2048
	s_mov_b32 s98, s58
	s_mov_b32 s99, 0
	v_lshl_add_u64 v[40:41], v[36:37], 0, s[98:99]
	v_mov_b32_e32 v81, v80
	s_mov_b32 s98, s58
	s_mov_b32 s99, 0
	v_lshl_add_u64 v[42:43], v[38:39], 0, s[98:99]
	v_lshl_or_b32 v147, v32, 11, v132
	global_load_dword v138, v[40:41], off
	global_load_dword v140, v[40:41], off offset:2048
	global_load_dword v139, v[42:43], off
	global_load_dword v141, v[42:43], off offset:2048
	s_mov_b32 s98, s59
	s_mov_b32 s99, 0
	v_lshl_add_u64 v[40:41], v[36:37], 0, s[98:99]
	s_mov_b32 s50, 30
	s_mov_b32 s98, s59
	s_mov_b32 s99, 0
	v_lshl_add_u64 v[42:43], v[38:39], 0, s[98:99]
	v_lshlrev_b32_e32 v88, 1, v64
	global_load_dword v142, v[40:41], off
	global_load_dword v144, v[40:41], off offset:2048
	global_load_dword v143, v[42:43], off
	global_load_dword v145, v[42:43], off offset:2048
	s_mov_b32 s98, s56
	s_mov_b32 s99, 0
	v_lshl_add_u64 v[40:41], v[36:37], 0, s[98:99]
	v_mov_b32_e32 v148, v103
	s_nop 0
	s_mov_b32 s98, s56
	s_mov_b32 s99, 0
	v_lshl_add_u64 v[42:43], v[38:39], 0, s[98:99]
	v_readlane_b32 s84, v241, 41
	s_nop 0
	global_load_dword v146, v[40:41], off
	global_load_dword v150, v[40:41], off offset:2048
	global_load_dword v149, v[42:43], off
	global_load_dword v151, v[42:43], off offset:2048
	s_mov_b32 s98, s60
	s_mov_b32 s99, 0
	v_lshl_add_u64 v[40:41], v[36:37], 0, s[98:99]
	v_readlane_b32 s85, v241, 42
	s_nop 0
	s_mov_b32 s98, s60
	s_mov_b32 s99, 0
	v_lshl_add_u64 v[42:43], v[38:39], 0, s[98:99]
	v_readlane_b32 s86, v241, 43
	s_nop 0
	global_load_dword v152, v[40:41], off
	global_load_dword v154, v[40:41], off offset:2048
	global_load_dword v153, v[42:43], off
	global_load_dword v155, v[42:43], off offset:2048
	s_mov_b32 s98, s61
	s_mov_b32 s99, 0
	v_lshl_add_u64 v[40:41], v[36:37], 0, s[98:99]
	v_readlane_b32 s87, v241, 44
	s_nop 0
	s_mov_b32 s98, s61
	s_mov_b32 s99, 0
	v_lshl_add_u64 v[42:43], v[38:39], 0, s[98:99]
	v_readlane_b32 s88, v241, 45
	s_nop 0
	s_mov_b32 s98, s62
	s_mov_b32 s99, 0
	v_lshl_add_u64 v[36:37], v[36:37], 0, s[98:99]
	global_load_dword v156, v[40:41], off
	global_load_dword v158, v[40:41], off offset:2048
	global_load_dword v157, v[42:43], off
	global_load_dword v159, v[42:43], off offset:2048
	s_mov_b32 s98, s62
	s_mov_b32 s99, 0
	v_lshl_add_u64 v[38:39], v[38:39], 0, s[98:99]
	v_readlane_b32 s89, v241, 46
	s_nop 0
	global_load_dword v160, v[36:37], off
	global_load_dword v162, v[36:37], off offset:2048
	global_load_dword v161, v[38:39], off
	global_load_dword v163, v[38:39], off offset:2048
	global_load_dword v164, v[34:35], off
	s_mov_b32 s98, s57
	s_mov_b32 s99, 0
	v_lshl_add_u64 v[36:37], v[34:35], 0, s[98:99]
	v_readlane_b32 s92, v241, 49
	s_nop 0
	s_mov_b32 s98, s58
	s_mov_b32 s99, 0
	v_lshl_add_u64 v[38:39], v[34:35], 0, s[98:99]
	v_readlane_b32 s93, v241, 50
	s_nop 0
	s_mov_b32 s98, s59
	s_mov_b32 s99, 0
	v_lshl_add_u64 v[40:41], v[34:35], 0, s[98:99]
	v_readlane_b32 s94, v241, 51
	s_nop 0
	s_mov_b32 s98, s56
	s_mov_b32 s99, 0
	v_lshl_add_u64 v[42:43], v[34:35], 0, s[98:99]
	v_readlane_b32 s95, v241, 52
	s_nop 0
	s_mov_b32 s98, s60
	s_mov_b32 s99, 0
	v_lshl_add_u64 v[44:45], v[34:35], 0, s[98:99]
	v_readlane_b32 s81, v241, 38
	s_nop 0
	s_mov_b64 s[98:99], 0x6000
	v_lshl_add_u64 v[46:47], v[34:35], 0, s[98:99]
	v_readlane_b32 s82, v241, 39
	s_nop 0
	v_add_co_u32_e32 v34, vcc, 0x7000, v34
	v_readlane_b32 s83, v241, 40
	s_nop 0
	v_addc_co_u32_e32 v35, vcc, 0, v35, vcc
	global_load_dword v165, v[36:37], off
	global_load_dword v166, v[38:39], off
	global_load_dword v167, v[40:41], off
	global_load_dword v168, v[42:43], off
	global_load_dword v169, v[44:45], off
	global_load_dword v170, v[46:47], off
	global_load_dword v171, v[34:35], off
	v_readlane_b32 s90, v241, 47
	v_readlane_b32 s91, v241, 48
	s_waitcnt vmcnt(0)
	s_branch .LBB0_1047

.LBB0_1047:
	ds_read_b64 v[32:33], v102
	s_waitcnt vmcnt(4) lgkmcnt(0)
	v_lshlrev_b32_e32 v34, 16, v67
	v_and_b32_e32 v35, 0xffff0000, v67
	v_lshlrev_b32_e32 v36, 16, v69
	v_and_b32_e32 v37, 0xffff0000, v69
	v_pk_mul_f32 v[34:35], v[32:33], v[34:35] op_sel_hi:[0,1]
	v_cvt_pk_bf16_f32 v34, v34, v35
	v_pk_mul_f32 v[32:33], v[32:33], v[36:37] op_sel:[1,0]
	ds_write_b32 v106, v34
	v_cvt_pk_bf16_f32 v34, v32, v33
	ds_write_b32 v106, v34 offset:17408
	ds_read_b64 v[34:35], v107
	v_lshlrev_b32_e32 v36, 16, v71
	v_and_b32_e32 v37, 0xffff0000, v71
	v_lshlrev_b32_e32 v38, 16, v75
	v_and_b32_e32 v39, 0xffff0000, v75
	s_waitcnt lgkmcnt(0)
	v_pk_mul_f32 v[36:37], v[34:35], v[36:37] op_sel_hi:[0,1]
	v_cvt_pk_bf16_f32 v36, v36, v37
	ds_write_b32 v106, v36 offset:272
	v_lshlrev_b32_e32 v36, 16, v73
	v_and_b32_e32 v37, 0xffff0000, v73
	v_pk_mul_f32 v[34:35], v[34:35], v[36:37] op_sel:[1,0]
	v_lshlrev_b32_e32 v40, 16, v136
	v_cvt_pk_bf16_f32 v36, v34, v35
	ds_write_b32 v106, v36 offset:17680
	ds_read_b64 v[36:37], v108
	v_and_b32_e32 v41, 0xffff0000, v136
	v_lshlrev_b32_e32 v42, 16, v138
	v_and_b32_e32 v43, 0xffff0000, v138
	v_lshlrev_b32_e32 v44, 16, v140
	s_waitcnt lgkmcnt(0)
	v_pk_mul_f32 v[38:39], v[36:37], v[38:39] op_sel_hi:[0,1]
	v_cvt_pk_bf16_f32 v38, v38, v39
	ds_write_b32 v106, v38 offset:544
	v_lshlrev_b32_e32 v38, 16, v135
	v_and_b32_e32 v39, 0xffff0000, v135
	v_pk_mul_f32 v[38:39], v[36:37], v[38:39] op_sel:[1,0]
	v_and_b32_e32 v45, 0xffff0000, v140
	v_cvt_pk_bf16_f32 v36, v38, v39
	ds_write_b32 v106, v36 offset:17952
	ds_read_b64 v[36:37], v109
	v_lshlrev_b32_e32 v46, 16, v142
	v_and_b32_e32 v47, 0xffff0000, v142
	v_lshlrev_b32_e32 v48, 16, v144
	v_and_b32_e32 v49, 0xffff0000, v144
	s_waitcnt lgkmcnt(0)
	v_pk_mul_f32 v[40:41], v[36:37], v[40:41] op_sel_hi:[0,1]
	v_cvt_pk_bf16_f32 v40, v40, v41
	ds_write_b32 v106, v40 offset:816
	v_lshlrev_b32_e32 v40, 16, v137
	v_and_b32_e32 v41, 0xffff0000, v137
	v_pk_mul_f32 v[40:41], v[36:37], v[40:41] op_sel:[1,0]
	v_lshlrev_b32_e32 v50, 16, v146
	v_cvt_pk_bf16_f32 v36, v40, v41
	ds_write_b32 v106, v36 offset:18224
	ds_read_b64 v[36:37], v110
	v_and_b32_e32 v51, 0xffff0000, v146
	v_lshlrev_b32_e32 v52, 16, v150
	v_and_b32_e32 v53, 0xffff0000, v150
	v_lshlrev_b32_e32 v54, 16, v152
	s_waitcnt lgkmcnt(0)
	v_pk_mul_f32 v[42:43], v[36:37], v[42:43] op_sel_hi:[0,1]
	v_cvt_pk_bf16_f32 v42, v42, v43
	ds_write_b32 v106, v42 offset:1088
	v_lshlrev_b32_e32 v42, 16, v139
	v_and_b32_e32 v43, 0xffff0000, v139
	v_pk_mul_f32 v[42:43], v[36:37], v[42:43] op_sel:[1,0]
	v_and_b32_e32 v55, 0xffff0000, v152
	v_cvt_pk_bf16_f32 v36, v42, v43
	ds_write_b32 v106, v36 offset:18496
	ds_read_b64 v[36:37], v111
	v_lshlrev_b32_e32 v56, 16, v154
	v_and_b32_e32 v57, 0xffff0000, v154
	v_lshlrev_b32_e32 v58, 16, v156
	v_and_b32_e32 v59, 0xffff0000, v156
	s_waitcnt lgkmcnt(0)
	v_pk_mul_f32 v[44:45], v[36:37], v[44:45] op_sel_hi:[0,1]
	v_cvt_pk_bf16_f32 v44, v44, v45
	ds_write_b32 v106, v44 offset:1360
	v_lshlrev_b32_e32 v44, 16, v141
	v_and_b32_e32 v45, 0xffff0000, v141
	v_pk_mul_f32 v[44:45], v[36:37], v[44:45] op_sel:[1,0]
	v_lshlrev_b32_e32 v60, 16, v158
	v_cvt_pk_bf16_f32 v36, v44, v45
	ds_write_b32 v106, v36 offset:18768
	ds_read_b64 v[36:37], v112
	v_and_b32_e32 v61, 0xffff0000, v158
	v_lshlrev_b32_e32 v62, 16, v160
	v_and_b32_e32 v63, 0xffff0000, v160
	v_lshlrev_b32_e32 v90, 16, v162
	s_waitcnt lgkmcnt(0)
	v_pk_mul_f32 v[46:47], v[36:37], v[46:47] op_sel_hi:[0,1]
	v_cvt_pk_bf16_f32 v46, v46, v47
	ds_write_b32 v106, v46 offset:1632
	v_lshlrev_b32_e32 v46, 16, v143
	v_and_b32_e32 v47, 0xffff0000, v143
	v_pk_mul_f32 v[46:47], v[36:37], v[46:47] op_sel:[1,0]
	v_and_b32_e32 v91, 0xffff0000, v162
	v_cvt_pk_bf16_f32 v36, v46, v47
	ds_write_b32 v106, v36 offset:19040
	ds_read_b64 v[36:37], v113
	v_lshlrev_b32_e32 v77, 16, v169
	v_or_b32_sdwa v174, v168, v77 dst_sel:DWORD dst_unused:UNUSED_PAD src0_sel:WORD_0 src1_sel:DWORD
	s_cmp_gt_u32 s54, 30
	s_waitcnt lgkmcnt(0)
	v_pk_mul_f32 v[48:49], v[36:37], v[48:49] op_sel_hi:[0,1]
	v_cvt_pk_bf16_f32 v48, v48, v49
	ds_write_b32 v106, v48 offset:1904
	v_lshlrev_b32_e32 v48, 16, v145
	v_and_b32_e32 v49, 0xffff0000, v145
	v_pk_mul_f32 v[48:49], v[36:37], v[48:49] op_sel:[1,0]
	s_nop 0
	v_cvt_pk_bf16_f32 v36, v48, v49
	ds_write_b32 v106, v36 offset:19312
	ds_read_b64 v[36:37], v114
	s_waitcnt lgkmcnt(0)
	v_pk_mul_f32 v[50:51], v[36:37], v[50:51] op_sel_hi:[0,1]
	v_cvt_pk_bf16_f32 v50, v50, v51
	ds_write_b32 v106, v50 offset:2176
	v_lshlrev_b32_e32 v50, 16, v149
	v_and_b32_e32 v51, 0xffff0000, v149
	v_pk_mul_f32 v[50:51], v[36:37], v[50:51] op_sel:[1,0]
	s_nop 0
	v_cvt_pk_bf16_f32 v36, v50, v51
	ds_write_b32 v106, v36 offset:19584
	ds_read_b64 v[36:37], v115
	s_waitcnt lgkmcnt(0)
	v_pk_mul_f32 v[52:53], v[36:37], v[52:53] op_sel_hi:[0,1]
	v_cvt_pk_bf16_f32 v52, v52, v53
	ds_write_b32 v106, v52 offset:2448
	v_lshlrev_b32_e32 v52, 16, v151
	v_and_b32_e32 v53, 0xffff0000, v151
	v_pk_mul_f32 v[52:53], v[36:37], v[52:53] op_sel:[1,0]
	s_nop 0
	v_cvt_pk_bf16_f32 v36, v52, v53
	ds_write_b32 v106, v36 offset:19856
	ds_read_b64 v[36:37], v116
	s_waitcnt lgkmcnt(0)
	v_pk_mul_f32 v[54:55], v[36:37], v[54:55] op_sel_hi:[0,1]
	v_cvt_pk_bf16_f32 v54, v54, v55
	ds_write_b32 v106, v54 offset:2720
	v_lshlrev_b32_e32 v54, 16, v153
	v_and_b32_e32 v55, 0xffff0000, v153
	v_pk_mul_f32 v[54:55], v[36:37], v[54:55] op_sel:[1,0]
	s_nop 0
	v_cvt_pk_bf16_f32 v36, v54, v55
	ds_write_b32 v106, v36 offset:20128
	ds_read_b64 v[36:37], v117
	s_waitcnt lgkmcnt(0)
	v_pk_mul_f32 v[56:57], v[36:37], v[56:57] op_sel_hi:[0,1]
	v_cvt_pk_bf16_f32 v56, v56, v57
	ds_write_b32 v106, v56 offset:2992
	v_lshlrev_b32_e32 v56, 16, v155
	v_and_b32_e32 v57, 0xffff0000, v155
	v_pk_mul_f32 v[56:57], v[36:37], v[56:57] op_sel:[1,0]
	s_nop 0
	v_cvt_pk_bf16_f32 v36, v56, v57
	ds_write_b32 v106, v36 offset:20400
	ds_read_b64 v[36:37], v118
	s_waitcnt lgkmcnt(0)
	v_pk_mul_f32 v[58:59], v[36:37], v[58:59] op_sel_hi:[0,1]
	v_cvt_pk_bf16_f32 v58, v58, v59
	ds_write_b32 v106, v58 offset:3264
	v_lshlrev_b32_e32 v58, 16, v157
	v_and_b32_e32 v59, 0xffff0000, v157
	v_pk_mul_f32 v[58:59], v[36:37], v[58:59] op_sel:[1,0]
	s_nop 0
	v_cvt_pk_bf16_f32 v36, v58, v59
	ds_write_b32 v106, v36 offset:20672
	ds_read_b64 v[36:37], v119
	s_waitcnt lgkmcnt(0)
	v_pk_mul_f32 v[60:61], v[36:37], v[60:61] op_sel_hi:[0,1]
	v_cvt_pk_bf16_f32 v60, v60, v61
	ds_write_b32 v106, v60 offset:3536
	v_lshlrev_b32_e32 v60, 16, v159
	v_and_b32_e32 v61, 0xffff0000, v159
	v_pk_mul_f32 v[60:61], v[36:37], v[60:61] op_sel:[1,0]
	s_nop 0
	v_cvt_pk_bf16_f32 v36, v60, v61
	ds_write_b32 v106, v36 offset:20944
	ds_read_b64 v[36:37], v120
	s_waitcnt lgkmcnt(0)
	v_pk_mul_f32 v[62:63], v[36:37], v[62:63] op_sel_hi:[0,1]
	v_cvt_pk_bf16_f32 v62, v62, v63
	ds_write_b32 v106, v62 offset:3808
	v_lshlrev_b32_e32 v62, 16, v161
	v_and_b32_e32 v63, 0xffff0000, v161
	v_pk_mul_f32 v[62:63], v[36:37], v[62:63] op_sel:[1,0]
	s_nop 0
	v_cvt_pk_bf16_f32 v36, v62, v63
	ds_write_b32 v106, v36 offset:21216
	ds_read_b64 v[36:37], v121
	s_waitcnt lgkmcnt(0)
	v_pk_mul_f32 v[90:91], v[36:37], v[90:91] op_sel_hi:[0,1]
	v_cvt_pk_bf16_f32 v64, v90, v91
	v_lshlrev_b32_e32 v90, 16, v163
	v_and_b32_e32 v91, 0xffff0000, v163
	v_pk_mul_f32 v[90:91], v[36:37], v[90:91] op_sel:[1,0]
	ds_write_b32 v106, v64 offset:4080
	v_cvt_pk_bf16_f32 v36, v90, v91
	ds_write_b32 v106, v36 offset:21488
	v_lshlrev_b32_e32 v36, 16, v167
	v_lshlrev_b32_e32 v37, 16, v165
	v_lshlrev_b32_e32 v64, 16, v171
	v_or_b32_sdwa v173, v166, v36 dst_sel:DWORD dst_unused:UNUSED_PAD src0_sel:WORD_0 src1_sel:DWORD
	v_or_b32_sdwa v172, v164, v37 dst_sel:DWORD dst_unused:UNUSED_PAD src0_sel:WORD_0 src1_sel:DWORD
	v_or_b32_sdwa v175, v170, v64 dst_sel:DWORD dst_unused:UNUSED_PAD src0_sel:WORD_0 src1_sel:DWORD
	v_and_b32_e32 v36, 0xffff0000, v167
	v_and_b32_e32 v37, 0xffff0000, v165
	ds_write_b128 v122, v[172:175] offset:35840
	v_or_b32_sdwa v173, v166, v36 dst_sel:DWORD dst_unused:UNUSED_PAD src0_sel:WORD_1 src1_sel:DWORD
	v_or_b32_sdwa v172, v164, v37 dst_sel:DWORD dst_unused:UNUSED_PAD src0_sel:WORD_1 src1_sel:DWORD
	v_and_b32_e32 v36, 0xffff0000, v171
	v_and_b32_e32 v37, 0xffff0000, v169
	v_or_b32_sdwa v175, v170, v36 dst_sel:DWORD dst_unused:UNUSED_PAD src0_sel:WORD_1 src1_sel:DWORD
	v_or_b32_sdwa v174, v168, v37 dst_sel:DWORD dst_unused:UNUSED_PAD src0_sel:WORD_1 src1_sel:DWORD
	ds_write_b128 v122, v[172:175] offset:35984
	s_cbranch_scc1 .LBB0_1046
	s_lshl_b64 s[64:65], s[50:51], 17
	v_lshl_add_u64 v[160:161], v[82:83], 0, s[64:65]
	v_lshl_add_u64 v[162:163], v[84:85], 0, s[64:65]
	s_lshl_b64 s[64:65], s[50:51], 18
	v_lshl_add_u64 v[36:37], v[86:87], 0, s[64:65]
	global_load_dword v67, v[160:161], off
	global_load_dword v69, v[162:163], off
	global_load_dword v71, v[160:161], off offset:2048
	global_load_dword v73, v[162:163], off offset:2048
	s_mov_b64 s[98:99], 0x1000
	v_lshl_add_u64 v[136:137], v[160:161], 0, s[98:99]
	s_mov_b64 s[98:99], 0x1000
	v_lshl_add_u64 v[138:139], v[162:163], 0, s[98:99]
	global_load_dword v75, v[136:137], off
	s_mov_b64 s[98:99], 0x2000
	v_lshl_add_u64 v[140:141], v[160:161], 0, s[98:99]
	global_load_dword v135, v[138:139], off
	global_load_dword v136, v[136:137], off offset:2048
	global_load_dword v137, v[138:139], off offset:2048
	s_mov_b64 s[98:99], 0x2000
	v_lshl_add_u64 v[142:143], v[162:163], 0, s[98:99]
	global_load_dword v138, v[140:141], off
	s_mov_b64 s[98:99], 0x3000
	v_lshl_add_u64 v[144:145], v[160:161], 0, s[98:99]
	global_load_dword v139, v[142:143], off
	global_load_dword v140, v[140:141], off offset:2048
	global_load_dword v141, v[142:143], off offset:2048
	s_mov_b64 s[98:99], 0x3000
	v_lshl_add_u64 v[150:151], v[162:163], 0, s[98:99]
	global_load_dword v142, v[144:145], off
	global_load_dword v143, v[150:151], off
	s_nop 0
	global_load_dword v144, v[144:145], off offset:2048
	s_nop 0
	global_load_dword v145, v[150:151], off offset:2048
	s_mov_b32 s98, s56
	s_mov_b32 s99, 0
	v_lshl_add_u64 v[150:151], v[160:161], 0, s[98:99]
	s_mov_b32 s98, s56
	s_mov_b32 s99, 0
	v_lshl_add_u64 v[152:153], v[162:163], 0, s[98:99]
	global_load_dword v146, v[150:151], off
	s_mov_b32 s98, s60
	s_mov_b32 s99, 0
	v_lshl_add_u64 v[154:155], v[160:161], 0, s[98:99]
	global_load_dword v149, v[152:153], off
	global_load_dword v150, v[150:151], off offset:2048
	global_load_dword v151, v[152:153], off offset:2048
	s_mov_b32 s98, s60
	s_mov_b32 s99, 0
	v_lshl_add_u64 v[156:157], v[162:163], 0, s[98:99]
	global_load_dword v152, v[154:155], off
	s_mov_b32 s98, s61
	s_mov_b32 s99, 0
	v_lshl_add_u64 v[158:159], v[160:161], 0, s[98:99]
	global_load_dword v153, v[156:157], off
	global_load_dword v154, v[154:155], off offset:2048
	global_load_dword v155, v[156:157], off offset:2048
	s_mov_b32 s98, s61
	s_mov_b32 s99, 0
	v_lshl_add_u64 v[164:165], v[162:163], 0, s[98:99]
	global_load_dword v156, v[158:159], off
	global_load_dword v157, v[164:165], off
	s_nop 0
	global_load_dword v158, v[158:159], off offset:2048
	s_nop 0
	global_load_dword v159, v[164:165], off offset:2048
	s_mov_b64 s[98:99], 0x7000
	v_lshl_add_u64 v[164:165], v[160:161], 0, s[98:99]
	s_mov_b64 s[98:99], 0x7000
	v_lshl_add_u64 v[166:167], v[162:163], 0, s[98:99]
	global_load_dword v160, v[164:165], off
	global_load_dword v161, v[166:167], off
	global_load_dword v162, v[164:165], off offset:2048
	global_load_dword v163, v[166:167], off offset:2048
	s_nop 0
	global_load_dword v164, v[36:37], off
	s_mov_b64 s[98:99], 0x1000
	v_lshl_add_u64 v[166:167], v[36:37], 0, s[98:99]
	global_load_dword v165, v[166:167], off
	s_mov_b64 s[98:99], 0x2000
	v_lshl_add_u64 v[166:167], v[36:37], 0, s[98:99]
	s_mov_b64 s[98:99], 0x3000
	v_lshl_add_u64 v[168:169], v[36:37], 0, s[98:99]
	global_load_dword v166, v[166:167], off
	global_load_dword v167, v[168:169], off
	s_mov_b64 s[98:99], 0x4000
	v_lshl_add_u64 v[168:169], v[36:37], 0, s[98:99]
	s_mov_b64 s[98:99], 0x5000
	v_lshl_add_u64 v[170:171], v[36:37], 0, s[98:99]
	global_load_dword v168, v[168:169], off
	global_load_dword v169, v[170:171], off
	s_mov_b64 s[98:99], 0x6000
	v_lshl_add_u64 v[170:171], v[36:37], 0, s[98:99]
	v_add_co_u32_e32 v36, vcc, 0x7000, v36
	global_load_dword v170, v[170:171], off
	s_nop 0
	v_addc_co_u32_e32 v37, vcc, 0, v37, vcc
	global_load_dword v171, v[36:37], off
	s_branch .LBB0_1046

.LBB0_1053:
	v_ashrrev_i32_e32 v0, 31, v92
	v_lshrrev_b32_e32 v1, 30, v0
	v_add_u32_e32 v1, v92, v1
	v_ashrrev_i32_e32 v2, 2, v1
	v_lshrrev_b32_e32 v0, 27, v0
	v_and_b32_e32 v36, 7, v2
	v_add_u32_e32 v0, v92, v0
	v_ashrrev_i32_e32 v32, 5, v0
	v_lshlrev_b32_e32 v0, 2, v36
	global_load_dword v0, v0, s[84:85]
	v_and_b32_e32 v1, 0x3fffffc, v1
	v_sub_u32_e32 v1, v92, v1
	v_lshlrev_b32_e32 v34, 6, v1
	s_mov_b32 s52, 0x3fb8aa3b
	v_readlane_b32 s80, v241, 18
	v_readlane_b32 s88, v241, 26
	v_readlane_b32 s89, v241, 27
	v_ashrrev_i32_e32 v35, 31, v34
	s_waitcnt vmcnt(0)
	v_mov_b32_e32 v69, v65
	v_mov_b32_e32 v71, v65
	v_readlane_b32 s81, v241, 19
	v_readlane_b32 s82, v241, 20
	v_readlane_b32 s83, v241, 21
	v_readlane_b32 s84, v241, 22
	v_readlane_b32 s85, v241, 23
	v_readlane_b32 s86, v241, 24
	v_readlane_b32 s87, v241, 25
	v_readlane_b32 s90, v241, 28
	v_readlane_b32 s91, v241, 29
	v_readlane_b32 s92, v241, 30
	v_readlane_b32 s93, v241, 31
	v_readlane_b32 s94, v241, 32
	v_readlane_b32 s95, v241, 33
	s_waitcnt vmcnt(0)
	v_mul_f32_e32 v1, 0x3fb8aa3b, v0
	v_fma_f32 v2, v0, s52, -v1
	v_rndne_f32_e32 v3, v1
	v_fmac_f32_e32 v2, 0x32a5705f, v0
	v_sub_f32_e32 v1, v1, v3
	v_add_f32_e32 v1, v1, v2
	v_exp_f32_e32 v1, v1
	v_cvt_i32_f32_e32 v2, v3
	s_mov_b32 s52, 0xc2ce8ed0
	v_cmp_ngt_f32_e32 vcc, s52, v0
	s_mov_b32 s52, 0x42b17218
	v_ldexp_f32 v1, v1, v2
	v_cndmask_b32_e32 v1, 0, v1, vcc
	v_cmp_nlt_f32_e32 vcc, s52, v0
	s_mov_b32 s52, 0x3f2aaaab
	s_nop 0
	v_cndmask_b32_e32 v2, v124, v1, vcc
	v_sub_f32_e32 v3, 1.0, v2
	v_add_f32_e32 v0, -1.0, v3
	v_sub_f32_e32 v1, v0, v3
	v_add_f32_e32 v1, 1.0, v1
	v_sub_f32_e64 v0, -v2, v0
	v_add_f32_e32 v4, v0, v1
	v_frexp_mant_f32_e32 v0, v3
	v_cmp_gt_f32_e32 vcc, s52, v0
	v_cvt_f64_f32_e32 v[0:1], v3
	v_frexp_exp_i32_f64_e32 v0, v[0:1]
	v_subbrev_co_u32_e32 v0, vcc, 0, v0, vcc
	v_sub_u32_e32 v1, 0, v0
	v_ldexp_f32 v3, v3, v1
	v_ldexp_f32 v1, v4, v1
	v_add_f32_e32 v4, -1.0, v3
	v_add_f32_e32 v5, 1.0, v4
	v_sub_f32_e32 v5, v3, v5
	v_add_f32_e32 v5, v1, v5
	v_add_f32_e32 v6, v4, v5
	v_sub_f32_e32 v4, v6, v4
	v_sub_f32_e32 v4, v5, v4
	v_add_f32_e32 v5, 1.0, v3
	v_add_f32_e32 v7, -1.0, v5
	v_sub_f32_e32 v3, v3, v7
	v_add_f32_e32 v1, v1, v3
	v_add_f32_e32 v3, v5, v1
	v_sub_f32_e32 v5, v3, v5
	v_sub_f32_e32 v1, v1, v5
	v_rcp_f32_e32 v5, v3
	v_cvt_f32_i32_e32 v0, v0
	s_mov_b32 s52, 0x3f317218
	v_cmp_nlt_f32_e32 vcc, 1.0, v2
	v_mul_f32_e32 v7, v6, v5
	v_mul_f32_e32 v8, v3, v7
	v_fma_f32 v9, v7, v3, -v8
	v_fmac_f32_e32 v9, v7, v1
	v_add_f32_e32 v10, v8, v9
	v_sub_f32_e32 v11, v6, v10
	v_sub_f32_e32 v6, v6, v11
	v_sub_f32_e32 v8, v10, v8
	v_sub_f32_e32 v6, v6, v10
	v_add_f32_e32 v4, v4, v6
	v_sub_f32_e32 v6, v8, v9
	v_add_f32_e32 v4, v6, v4
	v_add_f32_e32 v6, v11, v4
	v_mul_f32_e32 v8, v5, v6
	v_mul_f32_e32 v9, v3, v8
	v_fma_f32 v3, v8, v3, -v9
	v_fmac_f32_e32 v3, v8, v1
	v_sub_f32_e32 v1, v11, v6
	v_add_f32_e32 v1, v4, v1
	v_add_f32_e32 v4, v9, v3
	v_sub_f32_e32 v10, v6, v4
	v_sub_f32_e32 v6, v6, v10
	v_sub_f32_e32 v9, v4, v9
	v_sub_f32_e32 v4, v6, v4
	v_add_f32_e32 v1, v1, v4
	v_sub_f32_e32 v3, v9, v3
	v_add_f32_e32 v1, v3, v1
	v_add_f32_e32 v3, v7, v8
	v_add_f32_e32 v1, v10, v1
	v_sub_f32_e32 v4, v3, v7
	v_mul_f32_e32 v1, v5, v1
	v_sub_f32_e32 v4, v8, v4
	v_add_f32_e32 v1, v4, v1
	v_mul_f32_e32 v7, 0x3f317218, v0
	v_add_f32_e32 v4, v3, v1
	v_fma_f32 v8, v0, s52, -v7
	v_mul_f32_e32 v5, v4, v4
	v_fmac_f32_e32 v8, 0xb102e308, v0
	v_sub_f32_e32 v0, v4, v3
	v_fmamk_f32 v6, v5, 0x3e9b6dac, v99
	v_sub_f32_e32 v0, v1, v0
	v_add_f32_e32 v1, v7, v8
	v_fmaak_f32 v6, v5, v6, 0x3f2aaada
	v_sub_f32_e32 v3, v1, v7
	v_ldexp_f32 v7, v4, 1
	v_mul_f32_e32 v4, v4, v5
	v_mul_f32_e32 v4, v4, v6
	v_add_f32_e32 v5, v7, v4
	v_sub_f32_e32 v6, v5, v7
	v_ldexp_f32 v0, v0, 1
	v_sub_f32_e32 v4, v4, v6
	v_add_f32_e32 v0, v0, v4
	v_add_f32_e32 v4, v5, v0
	v_sub_f32_e32 v5, v4, v5
	v_sub_f32_e32 v0, v0, v5
	v_add_f32_e32 v5, v1, v4
	v_sub_f32_e32 v6, v5, v1
	v_sub_f32_e32 v7, v5, v6
	v_sub_f32_e32 v3, v8, v3
	v_sub_f32_e32 v1, v1, v7
	v_sub_f32_e32 v4, v4, v6
	v_add_f32_e32 v1, v4, v1
	v_add_f32_e32 v4, v3, v0
	v_sub_f32_e32 v6, v4, v3
	v_sub_f32_e32 v7, v4, v6
	v_sub_f32_e32 v3, v3, v7
	v_sub_f32_e32 v0, v0, v6
	v_add_f32_e32 v1, v4, v1
	v_add_f32_e32 v0, v0, v3
	v_add_f32_e32 v3, v5, v1
	v_sub_f32_e32 v4, v3, v5
	v_sub_f32_e32 v1, v1, v4
	v_add_f32_e32 v0, v0, v1
	v_add_f32_e32 v0, v3, v0
	v_cndmask_b32_e32 v0, v125, v0, vcc
	v_cmp_neq_f32_e32 vcc, 1.0, v2
	s_mov_b32 s52, 0x33800000
	v_cmp_lt_f32_e64 s[52:53], |v2|, s52
	v_cndmask_b32_e32 v0, v126, v0, vcc
	s_nop 0
	v_cndmask_b32_e64 v0, v0, -v2, s[52:53]
	v_mul_f32_e32 v33, 0x3fb8aa3b, v0
	v_lshl_or_b32 v0, v32, 4, v36
	v_ashrrev_i32_e32 v1, 31, v0
	v_lshlrev_b64 v[0:1], 17, v[0:1]
	v_lshl_add_u64 v[0:1], s[88:89], 0, v[0:1]
	v_lshl_add_u64 v[0:1], v[34:35], 2, v[0:1]
	v_lshl_add_u64 v[0:1], v[0:1], 0, v[64:65]
	v_lshl_add_u64 v[0:1], v[0:1], 0, v[68:69]
	v_lshl_add_u64 v[28:29], v[0:1], 0, v[70:71]
	s_mov_b32 s52, 0x8000
	v_add_co_u32_e32 v8, vcc, s54, v28
	global_load_dword v4, v[28:29], off
	global_load_dword v5, v[28:29], off offset:1024
	global_load_dword v6, v[28:29], off offset:2048
	global_load_dword v7, v[28:29], off offset:3072
	v_addc_co_u32_e32 v9, vcc, 0, v29, vcc
	s_mov_b32 s98, s52
	s_mov_b32 s99, 0
	v_lshl_add_u64 v[12:13], v[28:29], 0, s[98:99]
	s_mov_b32 s52, 0xc000
	s_mov_b32 s98, s52
	s_mov_b32 s99, 0
	v_lshl_add_u64 v[16:17], v[28:29], 0, s[98:99]
	s_mov_b32 s52, 0x10000
	s_mov_b32 s98, s52
	s_mov_b32 s99, 0
	v_lshl_add_u64 v[20:21], v[28:29], 0, s[98:99]
	s_mov_b32 s52, 0x14000
	s_mov_b32 s98, s52
	s_mov_b32 s99, 0
	v_lshl_add_u64 v[24:25], v[28:29], 0, s[98:99]
	global_load_dword v0, v[8:9], off
	global_load_dword v1, v[8:9], off offset:1024
	global_load_dword v2, v[8:9], off offset:2048
	global_load_dword v3, v[8:9], off offset:3072
	s_mov_b64 s[98:99], 0x18000
	v_lshl_add_u64 v[30:31], v[28:29], 0, s[98:99]
	global_load_dword v8, v[12:13], off
	global_load_dword v9, v[12:13], off offset:1024
	global_load_dword v10, v[12:13], off offset:2048
	global_load_dword v11, v[12:13], off offset:3072
	v_add_co_u32_e32 v38, vcc, 0x1c000, v28
	global_load_dword v12, v[16:17], off
	global_load_dword v13, v[16:17], off offset:1024
	global_load_dword v14, v[16:17], off offset:2048
	global_load_dword v15, v[16:17], off offset:3072
	v_addc_co_u32_e32 v39, vcc, 0, v29, vcc
	global_load_dword v16, v[20:21], off
	global_load_dword v17, v[20:21], off offset:1024
	global_load_dword v18, v[20:21], off offset:2048
	global_load_dword v19, v[20:21], off offset:3072
	s_nop 0
	global_load_dword v20, v[24:25], off
	global_load_dword v21, v[24:25], off offset:1024
	global_load_dword v22, v[24:25], off offset:2048
	global_load_dword v23, v[24:25], off offset:3072
	s_nop 0
	global_load_dword v24, v[30:31], off
	global_load_dword v25, v[30:31], off offset:1024
	global_load_dword v26, v[30:31], off offset:2048
	global_load_dword v27, v[30:31], off offset:3072
	global_load_dword v28, v[38:39], off
	global_load_dword v29, v[38:39], off offset:1024
	s_nop 0
	global_load_dword v30, v[38:39], off offset:2048
	global_load_dword v31, v[38:39], off offset:3072
	s_and_saveexec_b64 s[52:53], s[38:39]
	s_cbranch_execz .LBB0_1055
	v_mul_f32_e32 v37, v33, v88
	v_exp_f32_e64 v39, -v37
	v_exp_f32_e32 v38, v37
	ds_write_b64 v100, v[38:39]

.LBB0_1057:
	s_or_b64 exec, exec, s[52:53]
	v_ashrrev_i32_e32 v33, 31, v32
	v_lshlrev_b64 v[38:39], 11, v[32:33]
	s_mov_b64 s[52:53], 0x2000
	v_lshl_add_u64 v[38:39], v[38:39], 0, s[52:53]
	v_lshlrev_b64 v[40:41], 11, v[38:39]
	v_lshl_add_u64 v[42:43], s[68:69], 0, v[40:41]
	v_lshlrev_b32_e32 v44, 8, v36
	v_mov_b32_e32 v45, v65
	v_lshl_add_u64 v[40:41], s[42:43], 0, v[40:41]
	v_lshlrev_b64 v[38:39], 12, v[38:39]
	v_lshl_add_u64 v[42:43], v[42:43], 0, v[44:45]
	v_lshl_add_u64 v[40:41], v[40:41], 0, v[44:45]
	v_lshl_add_u64 v[38:39], s[44:45], 0, v[38:39]
	v_lshlrev_b32_e32 v44, 9, v36
	v_lshl_add_u64 v[38:39], v[38:39], 0, v[44:45]
	v_lshlrev_b64 v[34:35], 1, v[34:35]
	v_lshl_add_u64 v[38:39], v[38:39], 0, v[34:35]
	v_mov_b32_e32 v73, v65
	v_mov_b32_e32 v75, v65
	v_lshl_add_u64 v[42:43], v[42:43], 0, v[72:73]
	v_lshl_add_u64 v[40:41], v[40:41], 0, v[72:73]
	v_lshl_add_u64 v[38:39], v[38:39], 0, v[74:75]
	v_mov_b64_e32 v[44:45], v[40:41]
	v_mov_b64_e32 v[46:47], v[42:43]
	v_mov_b64_e32 v[48:49], v[38:39]
	s_waitcnt lgkmcnt(0)
	s_barrier
	global_load_dword v69, v[46:47], off
	global_load_dword v73, v[46:47], off offset:2048
	global_load_dword v71, v[44:45], off
	global_load_dword v75, v[44:45], off offset:2048
	s_mov_b32 s98, s55
	s_mov_b32 s99, 0
	v_lshl_add_u64 v[50:51], v[46:47], 0, s[98:99]
	v_lshlrev_b64 v[32:33], 23, v[32:33]
	s_mov_b32 s98, s55
	s_mov_b32 s99, 0
	v_lshl_add_u64 v[52:53], v[44:45], 0, s[98:99]
	v_lshl_or_b32 v32, v36, 9, v32
	global_load_dword v127, v[50:51], off
	global_load_dword v129, v[50:51], off offset:2048
	global_load_dword v128, v[52:53], off
	global_load_dword v130, v[52:53], off offset:2048
	s_mov_b32 s98, s56
	s_mov_b32 s99, 0
	v_lshl_add_u64 v[50:51], v[46:47], 0, s[98:99]
	v_lshl_add_u64 v[32:33], v[32:33], 0, v[34:35]
	s_nop 0
	s_mov_b32 s98, s56
	s_mov_b32 s99, 0
	v_lshl_add_u64 v[52:53], v[44:45], 0, s[98:99]
	v_readlane_b32 s80, v241, 37
	s_nop 0
	global_load_dword v131, v[50:51], off
	global_load_dword v133, v[50:51], off offset:2048
	global_load_dword v132, v[52:53], off
	global_load_dword v134, v[52:53], off offset:2048
	s_mov_b32 s98, s57
	s_mov_b32 s99, 0
	v_lshl_add_u64 v[50:51], v[46:47], 0, s[98:99]
	s_mov_b32 s52, 0
	s_mov_b32 s98, s57
	s_mov_b32 s99, 0
	v_lshl_add_u64 v[52:53], v[44:45], 0, s[98:99]
	v_mov_b32_e32 v77, v76
	global_load_dword v135, v[50:51], off
	global_load_dword v137, v[50:51], off offset:2048
	global_load_dword v136, v[52:53], off
	global_load_dword v138, v[52:53], off offset:2048
	s_mov_b32 s98, s54
	s_mov_b32 s99, 0
	v_lshl_add_u64 v[50:51], v[46:47], 0, s[98:99]
	v_lshl_add_u64 v[78:79], v[42:43], 0, s[48:49]
	s_mov_b32 s98, s54
	s_mov_b32 s99, 0
	v_lshl_add_u64 v[52:53], v[44:45], 0, s[98:99]
	v_lshl_add_u64 v[80:81], v[40:41], 0, s[48:49]
	global_load_dword v139, v[50:51], off
	global_load_dword v141, v[50:51], off offset:2048
	global_load_dword v140, v[52:53], off
	global_load_dword v142, v[52:53], off offset:2048
	s_mov_b32 s98, s58
	s_mov_b32 s99, 0
	v_lshl_add_u64 v[50:51], v[46:47], 0, s[98:99]
	v_lshl_add_u64 v[82:83], v[38:39], 0, s[50:51]
	s_mov_b32 s98, s58
	s_mov_b32 s99, 0
	v_lshl_add_u64 v[52:53], v[44:45], 0, s[98:99]
	v_lshl_add_u64 v[84:85], v[66:67], 0, v[32:33]
	global_load_dword v143, v[50:51], off
	global_load_dword v145, v[50:51], off offset:2048
	global_load_dword v144, v[52:53], off
	global_load_dword v146, v[52:53], off offset:2048
	s_mov_b32 s98, s59
	s_mov_b32 s99, 0
	v_lshl_add_u64 v[50:51], v[46:47], 0, s[98:99]
	v_readlane_b32 s84, v241, 41
	s_nop 0
	s_mov_b32 s98, s59
	s_mov_b32 s99, 0
	v_lshl_add_u64 v[52:53], v[44:45], 0, s[98:99]
	v_readlane_b32 s85, v241, 42
	s_nop 0
	s_mov_b32 s98, s60
	s_mov_b32 s99, 0
	v_lshl_add_u64 v[46:47], v[46:47], 0, s[98:99]
	global_load_dword v147, v[50:51], off
	global_load_dword v149, v[50:51], off offset:2048
	global_load_dword v148, v[52:53], off
	global_load_dword v150, v[52:53], off offset:2048
	s_mov_b32 s98, s60
	s_mov_b32 s99, 0
	v_lshl_add_u64 v[44:45], v[44:45], 0, s[98:99]
	v_readlane_b32 s86, v241, 43
	s_nop 0
	global_load_dword v151, v[46:47], off
	global_load_dword v153, v[46:47], off offset:2048
	global_load_dword v152, v[44:45], off
	global_load_dword v154, v[44:45], off offset:2048
	global_load_dword v155, v[48:49], off
	s_mov_b32 s98, s55
	s_mov_b32 s99, 0
	v_lshl_add_u64 v[44:45], v[48:49], 0, s[98:99]
	v_readlane_b32 s87, v241, 44
	s_nop 0
	s_mov_b32 s98, s56
	s_mov_b32 s99, 0
	v_lshl_add_u64 v[46:47], v[48:49], 0, s[98:99]
	v_readlane_b32 s88, v241, 45
	s_nop 0
	s_mov_b32 s98, s57
	s_mov_b32 s99, 0
	v_lshl_add_u64 v[50:51], v[48:49], 0, s[98:99]
	v_readlane_b32 s89, v241, 46
	s_nop 0
	s_mov_b32 s98, s54
	s_mov_b32 s99, 0
	v_lshl_add_u64 v[52:53], v[48:49], 0, s[98:99]
	v_readlane_b32 s92, v241, 49
	s_nop 0
	s_mov_b32 s98, s58
	s_mov_b32 s99, 0
	v_lshl_add_u64 v[54:55], v[48:49], 0, s[98:99]
	v_readlane_b32 s93, v241, 50
	s_nop 0
	s_mov_b32 s98, s59
	s_mov_b32 s99, 0
	v_lshl_add_u64 v[56:57], v[48:49], 0, s[98:99]
	v_readlane_b32 s94, v241, 51
	s_nop 0
	v_add_co_u32_e32 v48, vcc, 0x7000, v48
	v_readlane_b32 s95, v241, 52
	s_nop 0
	v_addc_co_u32_e32 v49, vcc, 0, v49, vcc
	global_load_dword v156, v[44:45], off
	global_load_dword v157, v[46:47], off
	global_load_dword v158, v[50:51], off
	global_load_dword v159, v[52:53], off
	global_load_dword v160, v[54:55], off
	global_load_dword v161, v[56:57], off
	global_load_dword v162, v[48:49], off
	v_readlane_b32 s81, v241, 38
	v_readlane_b32 s82, v241, 39
	v_readlane_b32 s83, v241, 40
	v_readlane_b32 s90, v241, 47
	v_readlane_b32 s91, v241, 48
	s_waitcnt vmcnt(0)
	s_branch .LBB0_1059

.LBB0_1059:
	ds_read_b64 v[32:33], v98
	s_waitcnt vmcnt(4) lgkmcnt(0)
	v_lshlrev_b32_e32 v34, 16, v69
	v_and_b32_e32 v35, 0xffff0000, v69
	v_lshlrev_b32_e32 v36, 16, v71
	v_and_b32_e32 v37, 0xffff0000, v71
	v_pk_mul_f32 v[34:35], v[32:33], v[34:35] op_sel_hi:[0,1]
	v_cvt_pk_bf16_f32 v34, v34, v35
	v_pk_mul_f32 v[32:33], v[32:33], v[36:37] op_sel:[1,0]
	ds_write_b32 v101, v34
	v_cvt_pk_bf16_f32 v34, v32, v33
	ds_write_b32 v101, v34 offset:17408
	ds_read_b64 v[34:35], v102
	v_lshlrev_b32_e32 v36, 16, v73
	v_and_b32_e32 v37, 0xffff0000, v73
	v_lshlrev_b32_e32 v38, 16, v127
	v_and_b32_e32 v39, 0xffff0000, v127
	s_waitcnt lgkmcnt(0)
	v_pk_mul_f32 v[36:37], v[34:35], v[36:37] op_sel_hi:[0,1]
	v_cvt_pk_bf16_f32 v36, v36, v37
	ds_write_b32 v101, v36 offset:272
	v_lshlrev_b32_e32 v36, 16, v75
	v_and_b32_e32 v37, 0xffff0000, v75
	v_pk_mul_f32 v[34:35], v[34:35], v[36:37] op_sel:[1,0]
	v_lshlrev_b32_e32 v40, 16, v129
	v_cvt_pk_bf16_f32 v36, v34, v35
	ds_write_b32 v101, v36 offset:17680
	ds_read_b64 v[36:37], v103
	v_and_b32_e32 v41, 0xffff0000, v129
	v_lshlrev_b32_e32 v42, 16, v131
	v_and_b32_e32 v43, 0xffff0000, v131
	v_lshlrev_b32_e32 v44, 16, v133
	s_waitcnt lgkmcnt(0)
	v_pk_mul_f32 v[38:39], v[36:37], v[38:39] op_sel_hi:[0,1]
	v_cvt_pk_bf16_f32 v38, v38, v39
	ds_write_b32 v101, v38 offset:544
	v_lshlrev_b32_e32 v38, 16, v128
	v_and_b32_e32 v39, 0xffff0000, v128
	v_pk_mul_f32 v[38:39], v[36:37], v[38:39] op_sel:[1,0]
	v_and_b32_e32 v45, 0xffff0000, v133
	v_cvt_pk_bf16_f32 v36, v38, v39
	ds_write_b32 v101, v36 offset:17952
	ds_read_b64 v[36:37], v104
	v_lshlrev_b32_e32 v46, 16, v135
	v_and_b32_e32 v47, 0xffff0000, v135
	v_lshlrev_b32_e32 v48, 16, v137
	v_and_b32_e32 v49, 0xffff0000, v137
	s_waitcnt lgkmcnt(0)
	v_pk_mul_f32 v[40:41], v[36:37], v[40:41] op_sel_hi:[0,1]
	v_cvt_pk_bf16_f32 v40, v40, v41
	ds_write_b32 v101, v40 offset:816
	v_lshlrev_b32_e32 v40, 16, v130
	v_and_b32_e32 v41, 0xffff0000, v130
	v_pk_mul_f32 v[40:41], v[36:37], v[40:41] op_sel:[1,0]
	v_lshlrev_b32_e32 v50, 16, v139
	v_cvt_pk_bf16_f32 v36, v40, v41
	ds_write_b32 v101, v36 offset:18224
	ds_read_b64 v[36:37], v105
	v_and_b32_e32 v51, 0xffff0000, v139
	v_lshlrev_b32_e32 v52, 16, v141
	v_and_b32_e32 v53, 0xffff0000, v141
	v_lshlrev_b32_e32 v54, 16, v143
	s_waitcnt lgkmcnt(0)
	v_pk_mul_f32 v[42:43], v[36:37], v[42:43] op_sel_hi:[0,1]
	v_cvt_pk_bf16_f32 v42, v42, v43
	ds_write_b32 v101, v42 offset:1088
	v_lshlrev_b32_e32 v42, 16, v132
	v_and_b32_e32 v43, 0xffff0000, v132
	v_pk_mul_f32 v[42:43], v[36:37], v[42:43] op_sel:[1,0]
	v_and_b32_e32 v55, 0xffff0000, v143
	v_cvt_pk_bf16_f32 v36, v42, v43
	ds_write_b32 v101, v36 offset:18496
	ds_read_b64 v[36:37], v106
	v_lshlrev_b32_e32 v56, 16, v145
	v_and_b32_e32 v57, 0xffff0000, v145
	v_lshlrev_b32_e32 v58, 16, v147
	v_and_b32_e32 v59, 0xffff0000, v147
	s_waitcnt lgkmcnt(0)
	v_pk_mul_f32 v[44:45], v[36:37], v[44:45] op_sel_hi:[0,1]
	v_cvt_pk_bf16_f32 v44, v44, v45
	ds_write_b32 v101, v44 offset:1360
	v_lshlrev_b32_e32 v44, 16, v134
	v_and_b32_e32 v45, 0xffff0000, v134
	v_pk_mul_f32 v[44:45], v[36:37], v[44:45] op_sel:[1,0]
	v_lshlrev_b32_e32 v60, 16, v149
	v_cvt_pk_bf16_f32 v36, v44, v45
	ds_write_b32 v101, v36 offset:18768
	ds_read_b64 v[36:37], v107
	v_and_b32_e32 v61, 0xffff0000, v149
	v_lshlrev_b32_e32 v62, 16, v151
	v_and_b32_e32 v63, 0xffff0000, v151
	v_lshlrev_b32_e32 v86, 16, v153
	s_waitcnt lgkmcnt(0)
	v_pk_mul_f32 v[46:47], v[36:37], v[46:47] op_sel_hi:[0,1]
	v_cvt_pk_bf16_f32 v46, v46, v47
	ds_write_b32 v101, v46 offset:1632
	v_lshlrev_b32_e32 v46, 16, v136
	v_and_b32_e32 v47, 0xffff0000, v136
	v_pk_mul_f32 v[46:47], v[36:37], v[46:47] op_sel:[1,0]
	v_and_b32_e32 v87, 0xffff0000, v153
	v_cvt_pk_bf16_f32 v36, v46, v47
	ds_write_b32 v101, v36 offset:19040
	ds_read_b64 v[36:37], v108
	v_lshlrev_b32_e32 v163, 16, v162
	v_lshlrev_b32_e32 v166, 16, v160
	v_or_b32_sdwa v167, v161, v163 dst_sel:DWORD dst_unused:UNUSED_PAD src0_sel:WORD_0 src1_sel:DWORD
	v_or_b32_sdwa v166, v159, v166 dst_sel:DWORD dst_unused:UNUSED_PAD src0_sel:WORD_0 src1_sel:DWORD
	s_waitcnt lgkmcnt(0)
	v_pk_mul_f32 v[48:49], v[36:37], v[48:49] op_sel_hi:[0,1]
	v_cvt_pk_bf16_f32 v48, v48, v49
	ds_write_b32 v101, v48 offset:1904
	v_lshlrev_b32_e32 v48, 16, v138
	v_and_b32_e32 v49, 0xffff0000, v138
	v_pk_mul_f32 v[48:49], v[36:37], v[48:49] op_sel:[1,0]
	s_cmp_gt_u32 s52, 30
	v_cvt_pk_bf16_f32 v36, v48, v49
	ds_write_b32 v101, v36 offset:19312
	ds_read_b64 v[36:37], v109
	s_waitcnt lgkmcnt(0)
	v_pk_mul_f32 v[50:51], v[36:37], v[50:51] op_sel_hi:[0,1]
	v_cvt_pk_bf16_f32 v50, v50, v51
	ds_write_b32 v101, v50 offset:2176
	v_lshlrev_b32_e32 v50, 16, v140
	v_and_b32_e32 v51, 0xffff0000, v140
	v_pk_mul_f32 v[50:51], v[36:37], v[50:51] op_sel:[1,0]
	s_nop 0
	v_cvt_pk_bf16_f32 v36, v50, v51
	ds_write_b32 v101, v36 offset:19584
	ds_read_b64 v[36:37], v110
	s_waitcnt lgkmcnt(0)
	v_pk_mul_f32 v[52:53], v[36:37], v[52:53] op_sel_hi:[0,1]
	v_cvt_pk_bf16_f32 v52, v52, v53
	ds_write_b32 v101, v52 offset:2448
	v_lshlrev_b32_e32 v52, 16, v142
	v_and_b32_e32 v53, 0xffff0000, v142
	v_pk_mul_f32 v[52:53], v[36:37], v[52:53] op_sel:[1,0]
	s_nop 0
	v_cvt_pk_bf16_f32 v36, v52, v53
	ds_write_b32 v101, v36 offset:19856
	ds_read_b64 v[36:37], v111
	s_waitcnt lgkmcnt(0)
	v_pk_mul_f32 v[54:55], v[36:37], v[54:55] op_sel_hi:[0,1]
	v_cvt_pk_bf16_f32 v54, v54, v55
	ds_write_b32 v101, v54 offset:2720
	v_lshlrev_b32_e32 v54, 16, v144
	v_and_b32_e32 v55, 0xffff0000, v144
	v_pk_mul_f32 v[54:55], v[36:37], v[54:55] op_sel:[1,0]
	s_nop 0
	v_cvt_pk_bf16_f32 v36, v54, v55
	ds_write_b32 v101, v36 offset:20128
	ds_read_b64 v[36:37], v112
	s_waitcnt lgkmcnt(0)
	v_pk_mul_f32 v[56:57], v[36:37], v[56:57] op_sel_hi:[0,1]
	v_cvt_pk_bf16_f32 v56, v56, v57
	ds_write_b32 v101, v56 offset:2992
	v_lshlrev_b32_e32 v56, 16, v146
	v_and_b32_e32 v57, 0xffff0000, v146
	v_pk_mul_f32 v[56:57], v[36:37], v[56:57] op_sel:[1,0]
	s_nop 0
	v_cvt_pk_bf16_f32 v36, v56, v57
	ds_write_b32 v101, v36 offset:20400
	ds_read_b64 v[36:37], v113
	s_waitcnt lgkmcnt(0)
	v_pk_mul_f32 v[58:59], v[36:37], v[58:59] op_sel_hi:[0,1]
	v_cvt_pk_bf16_f32 v58, v58, v59
	ds_write_b32 v101, v58 offset:3264
	v_lshlrev_b32_e32 v58, 16, v148
	v_and_b32_e32 v59, 0xffff0000, v148
	v_pk_mul_f32 v[58:59], v[36:37], v[58:59] op_sel:[1,0]
	s_nop 0
	v_cvt_pk_bf16_f32 v36, v58, v59
	ds_write_b32 v101, v36 offset:20672
	ds_read_b64 v[36:37], v114
	s_waitcnt lgkmcnt(0)
	v_pk_mul_f32 v[60:61], v[36:37], v[60:61] op_sel_hi:[0,1]
	v_cvt_pk_bf16_f32 v60, v60, v61
	ds_write_b32 v101, v60 offset:3536
	v_lshlrev_b32_e32 v60, 16, v150
	v_and_b32_e32 v61, 0xffff0000, v150
	v_pk_mul_f32 v[60:61], v[36:37], v[60:61] op_sel:[1,0]
	s_nop 0
	v_cvt_pk_bf16_f32 v36, v60, v61
	ds_write_b32 v101, v36 offset:20944
	ds_read_b64 v[36:37], v115
	s_waitcnt lgkmcnt(0)
	v_pk_mul_f32 v[62:63], v[36:37], v[62:63] op_sel_hi:[0,1]
	v_cvt_pk_bf16_f32 v62, v62, v63
	ds_write_b32 v101, v62 offset:3808
	v_lshlrev_b32_e32 v62, 16, v152
	v_and_b32_e32 v63, 0xffff0000, v152
	v_pk_mul_f32 v[62:63], v[36:37], v[62:63] op_sel:[1,0]
	s_nop 0
	v_cvt_pk_bf16_f32 v36, v62, v63
	ds_write_b32 v101, v36 offset:21216
	ds_read_b64 v[36:37], v116
	s_waitcnt lgkmcnt(0)
	v_pk_mul_f32 v[86:87], v[36:37], v[86:87] op_sel_hi:[0,1]
	v_cvt_pk_bf16_f32 v86, v86, v87
	ds_write_b32 v101, v86 offset:4080
	v_lshlrev_b32_e32 v86, 16, v154
	v_and_b32_e32 v87, 0xffff0000, v154
	v_pk_mul_f32 v[86:87], v[36:37], v[86:87] op_sel:[1,0]
	v_lshlrev_b32_e32 v37, 16, v156
	v_cvt_pk_bf16_f32 v36, v86, v87
	ds_write_b32 v101, v36 offset:21488
	v_lshlrev_b32_e32 v36, 16, v158
	v_or_b32_sdwa v165, v157, v36 dst_sel:DWORD dst_unused:UNUSED_PAD src0_sel:WORD_0 src1_sel:DWORD
	v_or_b32_sdwa v164, v155, v37 dst_sel:DWORD dst_unused:UNUSED_PAD src0_sel:WORD_0 src1_sel:DWORD
	v_and_b32_e32 v36, 0xffff0000, v158
	v_and_b32_e32 v37, 0xffff0000, v156
	ds_write_b128 v117, v[164:167] offset:35840
	v_or_b32_sdwa v165, v157, v36 dst_sel:DWORD dst_unused:UNUSED_PAD src0_sel:WORD_1 src1_sel:DWORD
	v_or_b32_sdwa v164, v155, v37 dst_sel:DWORD dst_unused:UNUSED_PAD src0_sel:WORD_1 src1_sel:DWORD
	v_and_b32_e32 v36, 0xffff0000, v162
	v_and_b32_e32 v37, 0xffff0000, v160
	v_or_b32_sdwa v167, v161, v36 dst_sel:DWORD dst_unused:UNUSED_PAD src0_sel:WORD_1 src1_sel:DWORD
	v_or_b32_sdwa v166, v159, v37 dst_sel:DWORD dst_unused:UNUSED_PAD src0_sel:WORD_1 src1_sel:DWORD
	ds_write_b128 v117, v[164:167] offset:35984
	s_cbranch_scc1 .LBB0_1058
	v_mov_b64_e32 v[152:153], v[78:79]
	v_mov_b64_e32 v[36:37], v[82:83]
	v_mov_b64_e32 v[154:155], v[80:81]
	global_load_dword v69, v[152:153], off
	global_load_dword v71, v[154:155], off
	global_load_dword v73, v[152:153], off offset:2048
	global_load_dword v75, v[154:155], off offset:2048
	s_mov_b64 s[98:99], 0x1000
	v_lshl_add_u64 v[130:131], v[152:153], 0, s[98:99]
	s_mov_b64 s[98:99], 0x1000
	v_lshl_add_u64 v[132:133], v[154:155], 0, s[98:99]
	global_load_dword v127, v[130:131], off
	s_mov_b64 s[98:99], 0x2000
	v_lshl_add_u64 v[134:135], v[152:153], 0, s[98:99]
	global_load_dword v128, v[132:133], off
	global_load_dword v129, v[130:131], off offset:2048
	global_load_dword v130, v[132:133], off offset:2048
	s_mov_b64 s[98:99], 0x2000
	v_lshl_add_u64 v[136:137], v[154:155], 0, s[98:99]
	global_load_dword v131, v[134:135], off
	s_mov_b64 s[98:99], 0x3000
	v_lshl_add_u64 v[138:139], v[152:153], 0, s[98:99]
	global_load_dword v132, v[136:137], off
	global_load_dword v133, v[134:135], off offset:2048
	global_load_dword v134, v[136:137], off offset:2048
	s_mov_b64 s[98:99], 0x3000
	v_lshl_add_u64 v[140:141], v[154:155], 0, s[98:99]
	global_load_dword v135, v[138:139], off
	s_mov_b32 s98, s54
	s_mov_b32 s99, 0
	v_lshl_add_u64 v[142:143], v[152:153], 0, s[98:99]
	global_load_dword v136, v[140:141], off
	global_load_dword v137, v[138:139], off offset:2048
	global_load_dword v138, v[140:141], off offset:2048
	s_mov_b32 s98, s54
	s_mov_b32 s99, 0
	v_lshl_add_u64 v[144:145], v[154:155], 0, s[98:99]
	global_load_dword v139, v[142:143], off
	s_mov_b32 s98, s58
	s_mov_b32 s99, 0
	v_lshl_add_u64 v[146:147], v[152:153], 0, s[98:99]
	global_load_dword v140, v[144:145], off
	global_load_dword v141, v[142:143], off offset:2048
	global_load_dword v142, v[144:145], off offset:2048
	s_mov_b32 s98, s58
	s_mov_b32 s99, 0
	v_lshl_add_u64 v[148:149], v[154:155], 0, s[98:99]
	global_load_dword v143, v[146:147], off
	s_mov_b32 s98, s59
	s_mov_b32 s99, 0
	v_lshl_add_u64 v[150:151], v[152:153], 0, s[98:99]
	global_load_dword v144, v[148:149], off
	global_load_dword v145, v[146:147], off offset:2048
	global_load_dword v146, v[148:149], off offset:2048
	s_mov_b32 s98, s59
	s_mov_b32 s99, 0
	v_lshl_add_u64 v[156:157], v[154:155], 0, s[98:99]
	global_load_dword v147, v[150:151], off
	global_load_dword v148, v[156:157], off
	global_load_dword v149, v[150:151], off offset:2048
	s_nop 0
	global_load_dword v150, v[156:157], off offset:2048
	s_mov_b64 s[98:99], 0x7000
	v_lshl_add_u64 v[156:157], v[152:153], 0, s[98:99]
	s_mov_b64 s[98:99], 0x7000
	v_lshl_add_u64 v[154:155], v[154:155], 0, s[98:99]
	global_load_dword v151, v[156:157], off
	global_load_dword v152, v[154:155], off
	global_load_dword v153, v[156:157], off offset:2048
	s_nop 0
	global_load_dword v154, v[154:155], off offset:2048
	s_nop 0
	global_load_dword v155, v[36:37], off
	s_mov_b64 s[98:99], 0x1000
	v_lshl_add_u64 v[156:157], v[36:37], 0, s[98:99]
	s_mov_b64 s[98:99], 0x2000
	v_lshl_add_u64 v[158:159], v[36:37], 0, s[98:99]
	global_load_dword v156, v[156:157], off
	global_load_dword v157, v[158:159], off
	s_mov_b64 s[98:99], 0x3000
	v_lshl_add_u64 v[158:159], v[36:37], 0, s[98:99]
	s_mov_b64 s[98:99], 0x4000
	v_lshl_add_u64 v[160:161], v[36:37], 0, s[98:99]
	global_load_dword v158, v[158:159], off
	global_load_dword v159, v[160:161], off
	s_mov_b64 s[98:99], 0x5000
	v_lshl_add_u64 v[160:161], v[36:37], 0, s[98:99]
	s_mov_b64 s[98:99], 0x6000
	v_lshl_add_u64 v[162:163], v[36:37], 0, s[98:99]
	global_load_dword v160, v[160:161], off
	v_add_co_u32_e32 v36, vcc, 0x7000, v36
	global_load_dword v161, v[162:163], off
	s_nop 0
	v_addc_co_u32_e32 v37, vcc, 0, v37, vcc
	global_load_dword v162, v[36:37], off
	s_branch .LBB0_1058

.LBB0_1077:
	v_add_u32_e32 v0, 0x100, v65
	v_cmp_lt_i32_e64 s[64:65], -1, v65
	v_readlane_b32 s4, v241, 37
	v_readlane_b32 s8, v241, 41
	v_cndmask_b32_e64 v0, v0, v65, s[64:65]
	v_ashrrev_i32_e32 v1, 31, v0
	v_lshrrev_b32_e32 v2, 30, v1
	v_add_u32_e32 v2, v0, v2
	s_waitcnt vmcnt(0)
	v_bfe_u32 v165, v2, 2, 3
	v_lshlrev_b32_e32 v68, 2, v165
	v_readlane_b32 s9, v241, 42
	v_and_b32_e32 v2, 0x3fffffc, v2
	v_lshrrev_b32_e32 v1, 27, v1
	v_sub_u32_e32 v2, v0, v2
	v_add_u32_e32 v0, v0, v1
	v_ashrrev_i32_e32 v94, 5, v0
	global_load_dword v32, v68, s[8:9]
	v_lshlrev_b32_e32 v82, 6, v2
	v_cmp_gt_i32_e64 s[66:67], 0, v65
	v_ashrrev_i32_e32 v83, 31, v82
	v_lshl_or_b32 v98, v94, 4, v165
	v_lshlrev_b32_e32 v84, 2, v66
	v_lshlrev_b32_e32 v80, 2, v64
	v_lshlrev_b32_e32 v78, 2, v70
	v_mov_b32_e32 v12, v69
	v_mov_b32_e32 v13, v69
	v_mov_b32_e32 v14, v69
	v_mov_b32_e32 v15, v69
	v_mov_b32_e32 v0, v69
	v_mov_b32_e32 v1, v69
	v_mov_b32_e32 v2, v69
	v_mov_b32_e32 v3, v69
	v_mov_b32_e32 v8, v69
	v_mov_b32_e32 v9, v69
	v_mov_b32_e32 v10, v69
	v_mov_b32_e32 v11, v69
	v_mov_b32_e32 v4, v69
	v_mov_b32_e32 v5, v69
	v_mov_b32_e32 v6, v69
	v_mov_b32_e32 v7, v69
	v_mov_b32_e32 v20, v69
	v_mov_b32_e32 v21, v69
	v_mov_b32_e32 v22, v69
	v_mov_b32_e32 v23, v69
	v_mov_b32_e32 v16, v69
	v_mov_b32_e32 v17, v69
	v_mov_b32_e32 v18, v69
	v_mov_b32_e32 v19, v69
	v_mov_b32_e32 v24, v69
	v_mov_b32_e32 v25, v69
	v_mov_b32_e32 v26, v69
	v_mov_b32_e32 v27, v69
	v_mov_b32_e32 v28, v69
	v_mov_b32_e32 v29, v69
	v_mov_b32_e32 v30, v69
	v_mov_b32_e32 v31, v69
	v_readlane_b32 s5, v241, 38
	v_readlane_b32 s6, v241, 39
	v_readlane_b32 s7, v241, 40
	v_readlane_b32 s10, v241, 43
	v_readlane_b32 s11, v241, 44
	v_readlane_b32 s12, v241, 45
	v_readlane_b32 s13, v241, 46
	v_readlane_b32 s14, v241, 47
	v_readlane_b32 s15, v241, 48
	v_readlane_b32 s16, v241, 49
	v_readlane_b32 s17, v241, 50
	v_readlane_b32 s18, v241, 51
	v_readlane_b32 s19, v241, 52
	s_and_saveexec_b64 s[82:83], s[66:67]
	s_cbranch_execz .LBB0_1079
	v_ashrrev_i32_e32 v99, 31, v98
	v_readlane_b32 s4, v241, 18
	v_lshlrev_b64 v[0:1], 17, v[98:99]
	v_readlane_b32 s12, v241, 26
	v_readlane_b32 s13, v241, 27
	v_mov_b32_e32 v85, v69
	v_mov_b32_e32 v81, v69
	v_lshl_add_u64 v[0:1], s[12:13], 0, v[0:1]
	v_lshl_add_u64 v[0:1], v[82:83], 2, v[0:1]
	v_lshl_add_u64 v[0:1], v[0:1], 0, v[84:85]
	v_lshl_add_u64 v[0:1], v[0:1], 0, v[80:81]
	v_mov_b32_e32 v79, v69
	v_lshl_add_u64 v[24:25], v[0:1], 0, v[78:79]
	s_mov_b32 s4, 0x8000
	s_mov_b32 s98, s33
	s_mov_b32 s99, 0
	v_lshl_add_u64 v[4:5], v[24:25], 0, s[98:99]
	v_readlane_b32 s5, v241, 19
	s_nop 0
	global_load_dword v12, v[24:25], off
	global_load_dword v13, v[24:25], off offset:1024
	global_load_dword v14, v[24:25], off offset:2048
	global_load_dword v15, v[24:25], off offset:3072
	global_load_dword v0, v[4:5], off
	global_load_dword v1, v[4:5], off offset:1024
	global_load_dword v2, v[4:5], off offset:2048
	global_load_dword v3, v[4:5], off offset:3072
	s_mov_b32 s98, s4
	s_mov_b32 s99, 0
	v_lshl_add_u64 v[4:5], v[24:25], 0, s[98:99]
	s_mov_b32 s4, 0xc000
	s_mov_b32 s98, s4
	s_mov_b32 s99, 0
	v_lshl_add_u64 v[16:17], v[24:25], 0, s[98:99]
	s_mov_b32 s4, 0x10000
	global_load_dword v8, v[4:5], off
	global_load_dword v9, v[4:5], off offset:1024
	global_load_dword v10, v[4:5], off offset:2048
	global_load_dword v11, v[4:5], off offset:3072
	s_nop 0
	global_load_dword v4, v[16:17], off
	global_load_dword v5, v[16:17], off offset:1024
	global_load_dword v6, v[16:17], off offset:2048
	global_load_dword v7, v[16:17], off offset:3072
	s_mov_b32 s98, s4
	s_mov_b32 s99, 0
	v_lshl_add_u64 v[16:17], v[24:25], 0, s[98:99]
	s_mov_b32 s4, 0x14000
	s_nop 0
	s_mov_b32 s98, s4
	s_mov_b32 s99, 0
	v_lshl_add_u64 v[26:27], v[24:25], 0, s[98:99]
	v_readlane_b32 s6, v241, 20
	s_nop 0
	v_add_co_u32_e32 v28, vcc, 0x18000, v24
	global_load_dword v20, v[16:17], off
	global_load_dword v21, v[16:17], off offset:1024
	global_load_dword v22, v[16:17], off offset:2048
	global_load_dword v23, v[16:17], off offset:3072
	s_nop 0
	global_load_dword v16, v[26:27], off
	global_load_dword v17, v[26:27], off offset:1024
	global_load_dword v18, v[26:27], off offset:2048
	global_load_dword v19, v[26:27], off offset:3072
	v_addc_co_u32_e32 v29, vcc, 0, v25, vcc
	v_add_co_u32_e32 v34, vcc, 0x1c000, v24
	v_readlane_b32 s7, v241, 21
	s_nop 0
	v_addc_co_u32_e32 v35, vcc, 0, v25, vcc
	global_load_dword v24, v[28:29], off
	global_load_dword v25, v[28:29], off offset:1024
	global_load_dword v26, v[28:29], off offset:2048
	global_load_dword v27, v[28:29], off offset:3072
	s_nop 0
	global_load_dword v28, v[34:35], off
	global_load_dword v29, v[34:35], off offset:1024
	global_load_dword v30, v[34:35], off offset:2048
	global_load_dword v31, v[34:35], off offset:3072
	v_readlane_b32 s8, v241, 22
	v_readlane_b32 s9, v241, 23
	v_readlane_b32 s10, v241, 24
	v_readlane_b32 s11, v241, 25
	v_readlane_b32 s14, v241, 28
	v_readlane_b32 s15, v241, 29
	v_readlane_b32 s16, v241, 30
	v_readlane_b32 s17, v241, 31
	v_readlane_b32 s18, v241, 32
	v_readlane_b32 s19, v241, 33

.LBB0_1083:
	s_or_b64 exec, exec, s[82:83]
	v_ashrrev_i32_e32 v95, 31, v94
	v_readlane_b32 s4, v241, 37
	v_lshlrev_b64 v[32:33], 11, v[94:95]
	s_mov_b64 s[82:83], 0x2000
	v_readlane_b32 s5, v241, 38
	v_readlane_b32 s6, v241, 39
	v_readlane_b32 s7, v241, 40
	v_lshl_add_u64 v[32:33], v[32:33], 0, s[82:83]
	v_lshlrev_b64 v[34:35], 8, v[94:95]
	v_cndmask_b32_e64 v33, v33, v35, s[64:65]
	v_cndmask_b32_e64 v32, v32, v34, s[64:65]
	v_readlane_b32 s4, v241, 53
	v_lshlrev_b64 v[34:35], 11, v[32:33]
	v_readlane_b32 s5, v241, 54
	v_readlane_b32 s8, v241, 41
	v_readlane_b32 s9, v241, 42
	v_lshl_add_u64 v[36:37], s[4:5], 0, v[34:35]
	v_readlane_b32 s4, v241, 63
	v_readlane_b32 s5, v240, 0
	v_lshlrev_b32_e32 v96, 8, v165
	v_mov_b32_e32 v97, v69
	v_lshl_add_u64 v[34:35], s[4:5], 0, v[34:35]
	v_readlane_b32 s4, v240, 1
	v_lshlrev_b64 v[32:33], 12, v[32:33]
	v_readlane_b32 s5, v240, 2
	v_lshl_add_u64 v[108:109], s[8:9], 0, v[68:69]
	v_lshl_add_u64 v[102:103], v[34:35], 0, v[96:97]
	v_lshl_add_u64 v[34:35], s[4:5], 0, v[32:33]
	v_lshlrev_b32_e32 v68, 9, v165
	v_lshl_add_u64 v[100:101], v[36:37], 0, v[96:97]
	v_lshl_add_u64 v[34:35], v[34:35], 0, v[68:69]
	v_lshlrev_b64 v[36:37], 1, v[82:83]
	v_lshl_add_u64 v[104:105], v[34:35], 0, v[36:37]
	v_lshlrev_b32_e32 v106, 2, v72
	v_mov_b32_e32 v107, v69
	v_mov_b32_e32 v75, v69
	v_lshl_add_u64 v[86:87], v[100:101], 0, v[106:107]
	v_lshl_add_u64 v[88:89], v[102:103], 0, v[106:107]
	v_lshl_add_u64 v[90:91], v[104:105], 0, v[74:75]
	v_mov_b64_e32 v[34:35], v[86:87]
	v_mov_b64_e32 v[38:39], v[90:91]
	v_mov_b64_e32 v[40:41], v[88:89]
	s_movk_i32 s4, 0x1000
	s_waitcnt lgkmcnt(0)
	s_barrier
	s_movk_i32 s5, 0x2000
	v_add_co_u32_e32 v42, vcc, s4, v34
	global_load_dword v75, v[34:35], off
	global_load_dword v81, v[34:35], off offset:2048
	global_load_dword v79, v[40:41], off
	global_load_dword v85, v[40:41], off offset:2048
	v_addc_co_u32_e32 v43, vcc, 0, v35, vcc
	s_mov_b32 s98, s4
	s_mov_b32 s99, 0
	v_lshl_add_u64 v[44:45], v[40:41], 0, s[98:99]
	v_readlane_b32 s6, v241, 55
	s_nop 0
	global_load_dword v95, v[42:43], off
	global_load_dword v99, v[42:43], off offset:2048
	global_load_dword v97, v[44:45], off
	global_load_dword v107, v[44:45], off offset:2048
	s_mov_b32 s98, s5
	s_mov_b32 s99, 0
	v_lshl_add_u64 v[42:43], v[34:35], 0, s[98:99]
	s_movk_i32 s6, 0x7000
	s_mov_b32 s98, s5
	s_mov_b32 s99, 0
	v_lshl_add_u64 v[44:45], v[40:41], 0, s[98:99]
	v_mov_b32_e32 v77, v69
	global_load_dword v166, v[42:43], off
	global_load_dword v168, v[42:43], off offset:2048
	global_load_dword v167, v[44:45], off
	global_load_dword v169, v[44:45], off offset:2048
	s_mov_b32 s98, s76
	s_mov_b32 s99, 0
	v_lshl_add_u64 v[42:43], v[34:35], 0, s[98:99]
	v_cndmask_b32_e64 v161, 32, 4, s[64:65]
	s_mov_b32 s98, s76
	s_mov_b32 s99, 0
	v_lshl_add_u64 v[44:45], v[40:41], 0, s[98:99]
	s_mov_b32 s79, 0
	global_load_dword v170, v[42:43], off
	global_load_dword v172, v[42:43], off offset:2048
	global_load_dword v171, v[44:45], off
	global_load_dword v173, v[44:45], off offset:2048
	s_mov_b32 s98, s33
	s_mov_b32 s99, 0
	v_lshl_add_u64 v[42:43], v[34:35], 0, s[98:99]
	v_mov_b32_e32 v111, v110
	s_mov_b32 s98, s33
	s_mov_b32 s99, 0
	v_lshl_add_u64 v[44:45], v[40:41], 0, s[98:99]
	v_lshl_add_u64 v[112:113], v[90:91], 0, s[74:75]
	global_load_dword v174, v[42:43], off
	global_load_dword v176, v[42:43], off offset:2048
	global_load_dword v175, v[44:45], off
	global_load_dword v177, v[44:45], off offset:2048
	s_mov_b32 s98, s77
	s_mov_b32 s99, 0
	v_lshl_add_u64 v[42:43], v[34:35], 0, s[98:99]
	v_lshl_add_u64 v[114:115], v[88:89], 0, s[80:81]
	s_mov_b32 s98, s77
	s_mov_b32 s99, 0
	v_lshl_add_u64 v[44:45], v[40:41], 0, s[98:99]
	v_lshl_add_u64 v[116:117], v[86:87], 0, s[80:81]
	global_load_dword v187, v[42:43], off
	global_load_dword v189, v[42:43], off offset:2048
	global_load_dword v188, v[44:45], off
	global_load_dword v190, v[44:45], off offset:2048
	s_mov_b32 s98, s78
	s_mov_b32 s99, 0
	v_lshl_add_u64 v[42:43], v[34:35], 0, s[98:99]
	s_mov_b64 s[82:83], 0
	s_nop 0
	s_mov_b32 s98, s78
	s_mov_b32 s99, 0
	v_lshl_add_u64 v[44:45], v[40:41], 0, s[98:99]
	v_readlane_b32 s10, v241, 43
	s_nop 0
	s_mov_b32 s98, s6
	s_mov_b32 s99, 0
	v_lshl_add_u64 v[34:35], v[34:35], 0, s[98:99]
	global_load_dword v191, v[42:43], off
	global_load_dword v193, v[42:43], off offset:2048
	global_load_dword v192, v[44:45], off
	global_load_dword v194, v[44:45], off offset:2048
	s_mov_b32 s98, s6
	s_mov_b32 s99, 0
	v_lshl_add_u64 v[40:41], v[40:41], 0, s[98:99]
	v_readlane_b32 s11, v241, 44
	s_nop 0
	global_load_dword v195, v[34:35], off
	global_load_dword v197, v[34:35], off offset:2048
	global_load_dword v196, v[40:41], off
	global_load_dword v198, v[40:41], off offset:2048
	global_load_dword v199, v[38:39], off
	s_mov_b32 s98, s4
	s_mov_b32 s99, 0
	v_lshl_add_u64 v[34:35], v[38:39], 0, s[98:99]
	v_readlane_b32 s12, v241, 45
	s_nop 0
	s_mov_b32 s98, s5
	s_mov_b32 s99, 0
	v_lshl_add_u64 v[40:41], v[38:39], 0, s[98:99]
	v_readlane_b32 s4, v240, 3
	s_nop 0
	s_mov_b32 s98, s76
	s_mov_b32 s99, 0
	v_lshl_add_u64 v[42:43], v[38:39], 0, s[98:99]
	v_readlane_b32 s5, v240, 4
	s_nop 0
	s_mov_b32 s98, s33
	s_mov_b32 s99, 0
	v_lshl_add_u64 v[44:45], v[38:39], 0, s[98:99]
	v_lshl_add_u64 v[32:33], s[4:5], 0, v[32:33]
	s_nop 0
	s_mov_b32 s98, s77
	s_mov_b32 s99, 0
	v_lshl_add_u64 v[46:47], v[38:39], 0, s[98:99]
	v_lshl_add_u64 v[32:33], v[32:33], 0, v[68:69]
	s_mov_b32 s98, s78
	s_mov_b32 s99, 0
	v_lshl_add_u64 v[48:49], v[38:39], 0, s[98:99]
	v_lshl_add_u64 v[32:33], v[32:33], 0, v[36:37]
	v_add_co_u32_e32 v38, vcc, 0x7000, v38
	v_lshl_add_u64 v[92:93], v[32:33], 0, v[76:77]
	s_nop 0
	v_addc_co_u32_e32 v39, vcc, 0, v39, vcc
	global_load_dword v200, v[34:35], off
	global_load_dword v201, v[40:41], off
	global_load_dword v202, v[42:43], off
	global_load_dword v203, v[44:45], off
	global_load_dword v204, v[46:47], off
	global_load_dword v205, v[48:49], off
	global_load_dword v206, v[38:39], off
	v_mov_b32_e32 v68, v122
	v_readlane_b32 s13, v241, 46
	v_readlane_b32 s14, v241, 47
	v_readlane_b32 s15, v241, 48
	v_readlane_b32 s16, v241, 49
	v_readlane_b32 s17, v241, 50
	v_readlane_b32 s18, v241, 51
	v_readlane_b32 s19, v241, 52
	v_readlane_b32 s7, v241, 56
	s_waitcnt vmcnt(0)
	s_branch .LBB0_1085

.LBB0_1085:
	ds_read_b64 v[32:33], v127
	s_waitcnt vmcnt(4) lgkmcnt(0)
	v_lshlrev_b32_e32 v34, 16, v75
	v_and_b32_e32 v35, 0xffff0000, v75
	v_lshlrev_b32_e32 v36, 16, v79
	v_and_b32_e32 v37, 0xffff0000, v79
	v_pk_mul_f32 v[34:35], v[32:33], v[34:35] op_sel_hi:[0,1]
	v_cvt_pk_bf16_f32 v34, v34, v35
	v_pk_mul_f32 v[32:33], v[32:33], v[36:37] op_sel:[1,0]
	ds_write_b32 v135, v34
	v_cvt_pk_bf16_f32 v34, v32, v33
	ds_write_b32 v135, v34 offset:17408
	ds_read_b64 v[34:35], v136
	v_lshlrev_b32_e32 v36, 16, v81
	v_and_b32_e32 v37, 0xffff0000, v81
	v_lshlrev_b32_e32 v38, 16, v95
	v_and_b32_e32 v39, 0xffff0000, v95
	s_waitcnt lgkmcnt(0)
	v_pk_mul_f32 v[36:37], v[34:35], v[36:37] op_sel_hi:[0,1]
	v_cvt_pk_bf16_f32 v36, v36, v37
	ds_write_b32 v135, v36 offset:272
	v_lshlrev_b32_e32 v36, 16, v85
	v_and_b32_e32 v37, 0xffff0000, v85
	v_pk_mul_f32 v[34:35], v[34:35], v[36:37] op_sel:[1,0]
	v_lshlrev_b32_e32 v40, 16, v99
	v_cvt_pk_bf16_f32 v36, v34, v35
	ds_write_b32 v135, v36 offset:17680
	ds_read_b64 v[36:37], v137
	v_and_b32_e32 v41, 0xffff0000, v99
	v_lshlrev_b32_e32 v42, 16, v166
	v_and_b32_e32 v43, 0xffff0000, v166
	v_lshlrev_b32_e32 v44, 16, v168
	s_waitcnt lgkmcnt(0)
	v_pk_mul_f32 v[38:39], v[36:37], v[38:39] op_sel_hi:[0,1]
	v_cvt_pk_bf16_f32 v38, v38, v39
	ds_write_b32 v135, v38 offset:544
	v_lshlrev_b32_e32 v38, 16, v97
	v_and_b32_e32 v39, 0xffff0000, v97
	v_pk_mul_f32 v[38:39], v[36:37], v[38:39] op_sel:[1,0]
	v_and_b32_e32 v45, 0xffff0000, v168
	v_cvt_pk_bf16_f32 v36, v38, v39
	ds_write_b32 v135, v36 offset:17952
	ds_read_b64 v[36:37], v138
	v_lshlrev_b32_e32 v46, 16, v170
	v_and_b32_e32 v47, 0xffff0000, v170
	v_lshlrev_b32_e32 v48, 16, v172
	v_and_b32_e32 v49, 0xffff0000, v172
	s_waitcnt lgkmcnt(0)
	v_pk_mul_f32 v[40:41], v[36:37], v[40:41] op_sel_hi:[0,1]
	v_cvt_pk_bf16_f32 v40, v40, v41
	ds_write_b32 v135, v40 offset:816
	v_lshlrev_b32_e32 v40, 16, v107
	v_and_b32_e32 v41, 0xffff0000, v107
	v_pk_mul_f32 v[40:41], v[36:37], v[40:41] op_sel:[1,0]
	v_lshlrev_b32_e32 v50, 16, v174
	v_cvt_pk_bf16_f32 v36, v40, v41
	ds_write_b32 v135, v36 offset:18224
	ds_read_b64 v[36:37], v139
	v_and_b32_e32 v51, 0xffff0000, v174
	v_lshlrev_b32_e32 v52, 16, v176
	v_and_b32_e32 v53, 0xffff0000, v176
	v_lshlrev_b32_e32 v54, 16, v187
	s_waitcnt lgkmcnt(0)
	v_pk_mul_f32 v[42:43], v[36:37], v[42:43] op_sel_hi:[0,1]
	v_cvt_pk_bf16_f32 v42, v42, v43
	ds_write_b32 v135, v42 offset:1088
	v_lshlrev_b32_e32 v42, 16, v167
	v_and_b32_e32 v43, 0xffff0000, v167
	v_pk_mul_f32 v[42:43], v[36:37], v[42:43] op_sel:[1,0]
	v_and_b32_e32 v55, 0xffff0000, v187
	v_cvt_pk_bf16_f32 v36, v42, v43
	ds_write_b32 v135, v36 offset:18496
	ds_read_b64 v[36:37], v140
	v_lshlrev_b32_e32 v56, 16, v189
	v_and_b32_e32 v57, 0xffff0000, v189
	v_lshlrev_b32_e32 v58, 16, v191
	v_and_b32_e32 v59, 0xffff0000, v191
	s_waitcnt lgkmcnt(0)
	v_pk_mul_f32 v[44:45], v[36:37], v[44:45] op_sel_hi:[0,1]
	v_cvt_pk_bf16_f32 v44, v44, v45
	ds_write_b32 v135, v44 offset:1360
	v_lshlrev_b32_e32 v44, 16, v169
	v_and_b32_e32 v45, 0xffff0000, v169
	v_pk_mul_f32 v[44:45], v[36:37], v[44:45] op_sel:[1,0]
	v_lshlrev_b32_e32 v60, 16, v193
	v_cvt_pk_bf16_f32 v36, v44, v45
	ds_write_b32 v141, v36 offset:17408
	ds_read_b64 v[36:37], v142
	v_and_b32_e32 v61, 0xffff0000, v193
	v_lshlrev_b32_e32 v62, 16, v195
	v_and_b32_e32 v63, 0xffff0000, v195
	v_lshlrev_b32_e32 v118, 16, v197
	s_waitcnt lgkmcnt(0)
	v_pk_mul_f32 v[46:47], v[36:37], v[46:47] op_sel_hi:[0,1]
	v_cvt_pk_bf16_f32 v46, v46, v47
	ds_write_b32 v141, v46 offset:272
	v_lshlrev_b32_e32 v46, 16, v171
	v_and_b32_e32 v47, 0xffff0000, v171
	v_pk_mul_f32 v[46:47], v[36:37], v[46:47] op_sel:[1,0]
	v_and_b32_e32 v119, 0xffff0000, v197
	v_cvt_pk_bf16_f32 v36, v46, v47
	ds_write_b32 v141, v36 offset:17680
	ds_read_b64 v[36:37], v143
	v_lshlrev_b32_e32 v162, 16, v204
	v_or_b32_sdwa v210, v203, v162 dst_sel:DWORD dst_unused:UNUSED_PAD src0_sel:WORD_0 src1_sel:DWORD
	s_add_i32 s79, s79, 1
	v_cmp_lt_u32_e32 vcc, s79, v161
	s_waitcnt lgkmcnt(0)
	v_pk_mul_f32 v[48:49], v[36:37], v[48:49] op_sel_hi:[0,1]
	v_cvt_pk_bf16_f32 v48, v48, v49
	ds_write_b32 v141, v48 offset:544
	v_lshlrev_b32_e32 v48, 16, v173
	v_and_b32_e32 v49, 0xffff0000, v173
	v_pk_mul_f32 v[48:49], v[36:37], v[48:49] op_sel:[1,0]
	s_nop 0
	v_cvt_pk_bf16_f32 v36, v48, v49
	ds_write_b32 v141, v36 offset:17952
	ds_read_b64 v[36:37], v144
	s_waitcnt lgkmcnt(0)
	v_pk_mul_f32 v[50:51], v[36:37], v[50:51] op_sel_hi:[0,1]
	v_cvt_pk_bf16_f32 v50, v50, v51
	ds_write_b32 v141, v50 offset:816
	v_lshlrev_b32_e32 v50, 16, v175
	v_and_b32_e32 v51, 0xffff0000, v175
	v_pk_mul_f32 v[50:51], v[36:37], v[50:51] op_sel:[1,0]
	s_nop 0
	v_cvt_pk_bf16_f32 v36, v50, v51
	ds_write_b32 v141, v36 offset:18224
	ds_read_b64 v[36:37], v145
	s_waitcnt lgkmcnt(0)
	v_pk_mul_f32 v[52:53], v[36:37], v[52:53] op_sel_hi:[0,1]
	v_cvt_pk_bf16_f32 v52, v52, v53
	ds_write_b32 v141, v52 offset:1088
	v_lshlrev_b32_e32 v52, 16, v177
	v_and_b32_e32 v53, 0xffff0000, v177
	v_pk_mul_f32 v[52:53], v[36:37], v[52:53] op_sel:[1,0]
	s_nop 0
	v_cvt_pk_bf16_f32 v36, v52, v53
	ds_write_b32 v141, v36 offset:18496
	ds_read_b64 v[36:37], v146
	s_waitcnt lgkmcnt(0)
	v_pk_mul_f32 v[54:55], v[36:37], v[54:55] op_sel_hi:[0,1]
	v_cvt_pk_bf16_f32 v54, v54, v55
	ds_write_b32 v141, v54 offset:1360
	v_lshlrev_b32_e32 v54, 16, v188
	v_and_b32_e32 v55, 0xffff0000, v188
	v_pk_mul_f32 v[54:55], v[36:37], v[54:55] op_sel:[1,0]
	s_nop 0
	v_cvt_pk_bf16_f32 v36, v54, v55
	ds_write_b32 v141, v36 offset:18768
	ds_read_b64 v[36:37], v147
	s_waitcnt lgkmcnt(0)
	v_pk_mul_f32 v[56:57], v[36:37], v[56:57] op_sel_hi:[0,1]
	v_cvt_pk_bf16_f32 v56, v56, v57
	ds_write_b32 v141, v56 offset:1632
	v_lshlrev_b32_e32 v56, 16, v190
	v_and_b32_e32 v57, 0xffff0000, v190
	v_pk_mul_f32 v[56:57], v[36:37], v[56:57] op_sel:[1,0]
	s_nop 0
	v_cvt_pk_bf16_f32 v36, v56, v57
	ds_write_b32 v141, v36 offset:19040
	ds_read_b64 v[36:37], v148
	s_waitcnt lgkmcnt(0)
	v_pk_mul_f32 v[58:59], v[36:37], v[58:59] op_sel_hi:[0,1]
	v_cvt_pk_bf16_f32 v58, v58, v59
	ds_write_b32 v141, v58 offset:1904
	v_lshlrev_b32_e32 v58, 16, v192
	v_and_b32_e32 v59, 0xffff0000, v192
	v_pk_mul_f32 v[58:59], v[36:37], v[58:59] op_sel:[1,0]
	s_nop 0
	v_cvt_pk_bf16_f32 v36, v58, v59
	ds_write_b32 v141, v36 offset:19312
	ds_read_b64 v[36:37], v149
	s_waitcnt lgkmcnt(0)
	v_pk_mul_f32 v[60:61], v[36:37], v[60:61] op_sel_hi:[0,1]
	v_cvt_pk_bf16_f32 v60, v60, v61
	ds_write_b32 v141, v60 offset:2176
	v_lshlrev_b32_e32 v60, 16, v194
	v_and_b32_e32 v61, 0xffff0000, v194
	v_pk_mul_f32 v[60:61], v[36:37], v[60:61] op_sel:[1,0]
	s_nop 0
	v_cvt_pk_bf16_f32 v36, v60, v61
	ds_write_b32 v141, v36 offset:19584
	ds_read_b64 v[36:37], v150
	s_waitcnt lgkmcnt(0)
	v_pk_mul_f32 v[62:63], v[36:37], v[62:63] op_sel_hi:[0,1]
	v_cvt_pk_bf16_f32 v62, v62, v63
	ds_write_b32 v141, v62 offset:2448
	v_lshlrev_b32_e32 v62, 16, v196
	v_and_b32_e32 v63, 0xffff0000, v196
	v_pk_mul_f32 v[62:63], v[36:37], v[62:63] op_sel:[1,0]
	s_nop 0
	v_cvt_pk_bf16_f32 v36, v62, v63
	ds_write_b32 v141, v36 offset:19856
	ds_read_b64 v[36:37], v151
	s_waitcnt lgkmcnt(0)
	v_pk_mul_f32 v[118:119], v[36:37], v[118:119] op_sel_hi:[0,1]
	v_cvt_pk_bf16_f32 v77, v118, v119
	v_lshlrev_b32_e32 v118, 16, v198
	v_and_b32_e32 v119, 0xffff0000, v198
	v_pk_mul_f32 v[118:119], v[36:37], v[118:119] op_sel:[1,0]
	ds_write_b32 v141, v77 offset:2720
	v_cvt_pk_bf16_f32 v36, v118, v119
	ds_write_b32 v141, v36 offset:20128
	v_lshlrev_b32_e32 v36, 16, v202
	v_lshlrev_b32_e32 v37, 16, v200
	v_lshlrev_b32_e32 v77, 16, v206
	v_or_b32_sdwa v209, v201, v36 dst_sel:DWORD dst_unused:UNUSED_PAD src0_sel:WORD_0 src1_sel:DWORD
	v_or_b32_sdwa v208, v199, v37 dst_sel:DWORD dst_unused:UNUSED_PAD src0_sel:WORD_0 src1_sel:DWORD
	v_or_b32_sdwa v211, v205, v77 dst_sel:DWORD dst_unused:UNUSED_PAD src0_sel:WORD_0 src1_sel:DWORD
	v_and_b32_e32 v36, 0xffff0000, v202
	v_and_b32_e32 v37, 0xffff0000, v200
	ds_write_b128 v152, v[208:211] offset:35840
	v_or_b32_sdwa v209, v201, v36 dst_sel:DWORD dst_unused:UNUSED_PAD src0_sel:WORD_1 src1_sel:DWORD
	v_or_b32_sdwa v208, v199, v37 dst_sel:DWORD dst_unused:UNUSED_PAD src0_sel:WORD_1 src1_sel:DWORD
	v_and_b32_e32 v36, 0xffff0000, v206
	v_and_b32_e32 v37, 0xffff0000, v204
	v_or_b32_sdwa v211, v205, v36 dst_sel:DWORD dst_unused:UNUSED_PAD src0_sel:WORD_1 src1_sel:DWORD
	v_or_b32_sdwa v210, v203, v37 dst_sel:DWORD dst_unused:UNUSED_PAD src0_sel:WORD_1 src1_sel:DWORD
	ds_write_b128 v152, v[208:211] offset:35984
	s_and_saveexec_b64 s[90:91], vcc
	s_cbranch_execz .LBB0_1084
	v_mov_b64_e32 v[162:163], v[114:115]
	v_mov_b64_e32 v[196:197], v[116:117]
	v_mov_b64_e32 v[36:37], v[112:113]
	global_load_dword v75, v[196:197], off
	global_load_dword v79, v[162:163], off
	global_load_dword v81, v[196:197], off offset:2048
	global_load_dword v85, v[162:163], off offset:2048
	s_mov_b64 s[98:99], 0x1000
	v_lshl_add_u64 v[166:167], v[196:197], 0, s[98:99]
	s_mov_b64 s[98:99], 0x1000
	v_lshl_add_u64 v[168:169], v[162:163], 0, s[98:99]
	global_load_dword v95, v[166:167], off
	global_load_dword v97, v[168:169], off
	global_load_dword v99, v[166:167], off offset:2048
	global_load_dword v107, v[168:169], off offset:2048
	s_mov_b64 s[98:99], 0x2000
	v_lshl_add_u64 v[168:169], v[196:197], 0, s[98:99]
	s_mov_b64 s[98:99], 0x2000
	v_lshl_add_u64 v[170:171], v[162:163], 0, s[98:99]
	global_load_dword v166, v[168:169], off
	s_mov_b64 s[98:99], 0x3000
	v_lshl_add_u64 v[172:173], v[196:197], 0, s[98:99]
	global_load_dword v167, v[170:171], off
	global_load_dword v168, v[168:169], off offset:2048
	global_load_dword v169, v[170:171], off offset:2048
	s_mov_b64 s[98:99], 0x3000
	v_lshl_add_u64 v[174:175], v[162:163], 0, s[98:99]
	global_load_dword v170, v[172:173], off
	s_mov_b32 s98, s33
	s_mov_b32 s99, 0
	v_lshl_add_u64 v[176:177], v[196:197], 0, s[98:99]
	global_load_dword v171, v[174:175], off
	global_load_dword v172, v[172:173], off offset:2048
	global_load_dword v173, v[174:175], off offset:2048
	s_mov_b32 s98, s33
	s_mov_b32 s99, 0
	v_lshl_add_u64 v[188:189], v[162:163], 0, s[98:99]
	global_load_dword v174, v[176:177], off
	s_mov_b32 s98, s77
	s_mov_b32 s99, 0
	v_lshl_add_u64 v[190:191], v[196:197], 0, s[98:99]
	global_load_dword v175, v[188:189], off
	global_load_dword v176, v[176:177], off offset:2048
	global_load_dword v177, v[188:189], off offset:2048
	s_mov_b32 s98, s77
	s_mov_b32 s99, 0
	v_lshl_add_u64 v[192:193], v[162:163], 0, s[98:99]
	global_load_dword v187, v[190:191], off
	s_mov_b32 s98, s78
	s_mov_b32 s99, 0
	v_lshl_add_u64 v[194:195], v[196:197], 0, s[98:99]
	global_load_dword v188, v[192:193], off
	global_load_dword v189, v[190:191], off offset:2048
	global_load_dword v190, v[192:193], off offset:2048
	s_mov_b32 s98, s78
	s_mov_b32 s99, 0
	v_lshl_add_u64 v[198:199], v[162:163], 0, s[98:99]
	global_load_dword v191, v[194:195], off
	global_load_dword v192, v[198:199], off
	global_load_dword v193, v[194:195], off offset:2048
	s_nop 0
	global_load_dword v194, v[198:199], off offset:2048
	s_mov_b64 s[98:99], 0x7000
	v_lshl_add_u64 v[198:199], v[196:197], 0, s[98:99]
	s_mov_b64 s[98:99], 0x7000
	v_lshl_add_u64 v[162:163], v[162:163], 0, s[98:99]
	global_load_dword v195, v[198:199], off
	global_load_dword v196, v[162:163], off
	global_load_dword v197, v[198:199], off offset:2048
	s_nop 0
	global_load_dword v198, v[162:163], off offset:2048
	global_load_dword v199, v[36:37], off
	s_mov_b64 s[98:99], 0x1000
	v_lshl_add_u64 v[162:163], v[36:37], 0, s[98:99]
	global_load_dword v200, v[162:163], off
	s_mov_b64 s[98:99], 0x2000
	v_lshl_add_u64 v[162:163], v[36:37], 0, s[98:99]
	global_load_dword v201, v[162:163], off
	s_mov_b64 s[98:99], 0x3000
	v_lshl_add_u64 v[162:163], v[36:37], 0, s[98:99]
	global_load_dword v202, v[162:163], off
	s_mov_b64 s[98:99], 0x4000
	v_lshl_add_u64 v[162:163], v[36:37], 0, s[98:99]
	global_load_dword v203, v[162:163], off
	s_mov_b64 s[98:99], 0x5000
	v_lshl_add_u64 v[162:163], v[36:37], 0, s[98:99]
	global_load_dword v204, v[162:163], off
	s_mov_b64 s[98:99], 0x6000
	v_lshl_add_u64 v[162:163], v[36:37], 0, s[98:99]
	v_add_co_u32_e32 v36, vcc, 0x7000, v36
	global_load_dword v205, v[162:163], off
	s_nop 0
	v_addc_co_u32_e32 v37, vcc, 0, v37, vcc
	global_load_dword v206, v[36:37], off
	s_branch .LBB0_1084
.LBB0_1087:
	s_or_b64 exec, exec, s[82:83]
	s_and_saveexec_b64 s[82:83], s[64:65]
	s_cbranch_execz .LBB0_1089
	s_waitcnt vmcnt(0)
	v_mov_b32_e32 v99, v69
	v_readlane_b32 s4, v240, 5
	v_lshlrev_b64 v[32:33], 17, v[98:99]
	v_readlane_b32 s5, v240, 6
	v_mov_b32_e32 v85, v69
	v_mov_b32_e32 v81, v69
	v_lshl_add_u64 v[32:33], s[4:5], 0, v[32:33]
	v_lshl_add_u64 v[32:33], v[82:83], 2, v[32:33]
	v_lshl_add_u64 v[32:33], v[32:33], 0, v[84:85]
	v_lshl_add_u64 v[32:33], v[32:33], 0, v[80:81]
	v_mov_b32_e32 v79, v69
	v_lshl_add_u64 v[32:33], v[32:33], 0, v[78:79]
	global_store_dword v[32:33], v12, off
	global_store_dword v[32:33], v13, off offset:1024
	global_store_dword v[32:33], v14, off offset:2048
	global_store_dword v[32:33], v15, off offset:3072
	s_mov_b32 s98, s33
	s_mov_b32 s99, 0
	v_lshl_add_u64 v[12:13], v[32:33], 0, s[98:99]
	s_mov_b32 s4, 0x8000
	global_store_dword v[12:13], v0, off
	global_store_dword v[12:13], v1, off offset:1024
	global_store_dword v[12:13], v2, off offset:2048
	global_store_dword v[12:13], v3, off offset:3072
	s_mov_b32 s98, s4
	s_mov_b32 s99, 0
	v_lshl_add_u64 v[0:1], v[32:33], 0, s[98:99]
	s_mov_b32 s4, 0xc000
	global_store_dword v[0:1], v8, off
	global_store_dword v[0:1], v9, off offset:1024
	global_store_dword v[0:1], v10, off offset:2048
	global_store_dword v[0:1], v11, off offset:3072
	s_mov_b32 s98, s4
	s_mov_b32 s99, 0
	v_lshl_add_u64 v[0:1], v[32:33], 0, s[98:99]
	s_mov_b32 s4, 0x10000
	global_store_dword v[0:1], v4, off
	global_store_dword v[0:1], v5, off offset:1024
	global_store_dword v[0:1], v6, off offset:2048
	global_store_dword v[0:1], v7, off offset:3072
	s_mov_b32 s98, s4
	s_mov_b32 s99, 0
	v_lshl_add_u64 v[0:1], v[32:33], 0, s[98:99]
	s_mov_b32 s4, 0x14000
	global_store_dword v[0:1], v20, off
	global_store_dword v[0:1], v21, off offset:1024
	global_store_dword v[0:1], v22, off offset:2048
	global_store_dword v[0:1], v23, off offset:3072
	s_mov_b32 s98, s4
	s_mov_b32 s99, 0
	v_lshl_add_u64 v[0:1], v[32:33], 0, s[98:99]
	global_store_dword v[0:1], v16, off
	global_store_dword v[0:1], v17, off offset:1024
	global_store_dword v[0:1], v18, off offset:2048
	global_store_dword v[0:1], v19, off offset:3072
	s_mov_b64 s[98:99], 0x18000
	v_lshl_add_u64 v[0:1], v[32:33], 0, s[98:99]
	global_store_dword v[0:1], v24, off
	global_store_dword v[0:1], v25, off offset:1024
	global_store_dword v[0:1], v26, off offset:2048
	global_store_dword v[0:1], v27, off offset:3072
	v_add_co_u32_e32 v0, vcc, 0x1c000, v32
	s_nop 1
	v_addc_co_u32_e32 v1, vcc, 0, v33, vcc
	global_store_dword v[0:1], v28, off
	global_store_dword v[0:1], v29, off offset:1024
	global_store_dword v[0:1], v30, off offset:2048
	global_store_dword v[0:1], v31, off offset:3072
.LBB0_1089:
	s_or_b64 exec, exec, s[82:83]
	global_load_dword v32, v[108:109], off offset:32
	v_mov_b32_e32 v8, 0
	v_lshlrev_b32_e32 v0, 4, v94
	v_or3_b32 v98, v0, v165, 8
	v_mov_b32_e32 v9, v8
	v_mov_b32_e32 v10, v8
	v_mov_b32_e32 v11, v8
	v_mov_b32_e32 v0, v8
	v_mov_b32_e32 v1, v8
	v_mov_b32_e32 v2, v8
	v_mov_b32_e32 v3, v8
	v_mov_b32_e32 v12, v8
	v_mov_b32_e32 v13, v8
	v_mov_b32_e32 v14, v8
	v_mov_b32_e32 v15, v8
	v_mov_b32_e32 v4, v8
	v_mov_b32_e32 v5, v8
	v_mov_b32_e32 v6, v8
	v_mov_b32_e32 v7, v8
	v_mov_b32_e32 v20, v8
	v_mov_b32_e32 v21, v8
	v_mov_b32_e32 v22, v8
	v_mov_b32_e32 v23, v8
	v_mov_b32_e32 v16, v8
	v_mov_b32_e32 v17, v8
	v_mov_b32_e32 v18, v8
	v_mov_b32_e32 v19, v8
	v_mov_b32_e32 v28, v8
	v_mov_b32_e32 v29, v8
	v_mov_b32_e32 v30, v8
	v_mov_b32_e32 v31, v8
	v_mov_b32_e32 v24, v8
	v_mov_b32_e32 v25, v8
	v_mov_b32_e32 v26, v8
	v_mov_b32_e32 v27, v8
	s_and_saveexec_b64 s[82:83], s[66:67]
	s_cbranch_execz .LBB0_1091
	s_waitcnt vmcnt(0)
	v_ashrrev_i32_e32 v99, 31, v98
	v_readlane_b32 s4, v241, 18
	v_lshlrev_b64 v[0:1], 17, v[98:99]
	v_readlane_b32 s12, v241, 26
	v_readlane_b32 s13, v241, 27
	v_mov_b32_e32 v85, v69
	v_mov_b32_e32 v81, v69
	v_lshl_add_u64 v[0:1], s[12:13], 0, v[0:1]
	v_lshl_add_u64 v[0:1], v[82:83], 2, v[0:1]
	v_lshl_add_u64 v[0:1], v[0:1], 0, v[84:85]
	v_lshl_add_u64 v[0:1], v[0:1], 0, v[80:81]
	v_mov_b32_e32 v79, v69
	v_lshl_add_u64 v[24:25], v[0:1], 0, v[78:79]
	s_mov_b32 s4, 0x8000
	s_mov_b32 s98, s33
	s_mov_b32 s99, 0
	v_lshl_add_u64 v[4:5], v[24:25], 0, s[98:99]
	v_readlane_b32 s5, v241, 19
	s_nop 0
	global_load_dword v8, v[24:25], off
	global_load_dword v9, v[24:25], off offset:1024
	global_load_dword v10, v[24:25], off offset:2048
	global_load_dword v11, v[24:25], off offset:3072
	global_load_dword v0, v[4:5], off
	global_load_dword v1, v[4:5], off offset:1024
	global_load_dword v2, v[4:5], off offset:2048
	global_load_dword v3, v[4:5], off offset:3072
	s_mov_b32 s98, s4
	s_mov_b32 s99, 0
	v_lshl_add_u64 v[4:5], v[24:25], 0, s[98:99]
	s_mov_b32 s4, 0xc000
	s_mov_b32 s98, s4
	s_mov_b32 s99, 0
	v_lshl_add_u64 v[16:17], v[24:25], 0, s[98:99]
	s_mov_b32 s4, 0x10000
	global_load_dword v12, v[4:5], off
	global_load_dword v13, v[4:5], off offset:1024
	global_load_dword v14, v[4:5], off offset:2048
	global_load_dword v15, v[4:5], off offset:3072
	s_nop 0
	global_load_dword v4, v[16:17], off
	global_load_dword v5, v[16:17], off offset:1024
	global_load_dword v6, v[16:17], off offset:2048
	global_load_dword v7, v[16:17], off offset:3072
	s_mov_b32 s98, s4
	s_mov_b32 s99, 0
	v_lshl_add_u64 v[16:17], v[24:25], 0, s[98:99]
	s_mov_b32 s4, 0x14000
	s_nop 0
	s_mov_b32 s98, s4
	s_mov_b32 s99, 0
	v_lshl_add_u64 v[26:27], v[24:25], 0, s[98:99]
	v_readlane_b32 s6, v241, 20
	s_nop 0
	global_load_dword v20, v[16:17], off
	global_load_dword v21, v[16:17], off offset:1024
	global_load_dword v22, v[16:17], off offset:2048
	global_load_dword v23, v[16:17], off offset:3072
	s_nop 0
	global_load_dword v16, v[26:27], off
	global_load_dword v17, v[26:27], off offset:1024
	global_load_dword v18, v[26:27], off offset:2048
	global_load_dword v19, v[26:27], off offset:3072
	s_mov_b64 s[98:99], 0x18000
	v_lshl_add_u64 v[26:27], v[24:25], 0, s[98:99]
	v_readlane_b32 s7, v241, 21
	s_nop 0
	v_add_co_u32_e32 v34, vcc, 0x1c000, v24
	v_readlane_b32 s8, v241, 22
	s_nop 0
	v_addc_co_u32_e32 v35, vcc, 0, v25, vcc
	global_load_dword v28, v[26:27], off
	global_load_dword v29, v[26:27], off offset:1024
	global_load_dword v30, v[26:27], off offset:2048
	global_load_dword v31, v[26:27], off offset:3072
	global_load_dword v24, v[34:35], off
	global_load_dword v25, v[34:35], off offset:1024
	s_nop 0
	global_load_dword v26, v[34:35], off offset:2048
	global_load_dword v27, v[34:35], off offset:3072
	v_readlane_b32 s9, v241, 23
	v_readlane_b32 s10, v241, 24
	v_readlane_b32 s11, v241, 25
	v_readlane_b32 s14, v241, 28
	v_readlane_b32 s15, v241, 29
	v_readlane_b32 s16, v241, 30
	v_readlane_b32 s17, v241, 31
	v_readlane_b32 s18, v241, 32
	v_readlane_b32 s19, v241, 33

.LBB0_1095:
	s_or_b64 exec, exec, s[82:83]
	v_add_u32_e32 v68, -1, v161
	v_lshlrev_b64 v[32:33], 17, v[68:69]
	v_lshl_add_u64 v[34:35], v[100:101], 0, v[32:33]
	v_mov_b32_e32 v107, v69
	v_lshl_add_u64 v[32:33], v[102:103], 0, v[32:33]
	v_lshl_add_u64 v[36:37], v[32:33], 0, v[106:107]
	v_lshlrev_b64 v[32:33], 18, v[68:69]
	v_lshl_add_u64 v[32:33], v[104:105], 0, v[32:33]
	v_mov_b32_e32 v75, v69
	v_lshl_add_u64 v[34:35], v[34:35], 0, v[106:107]
	v_lshl_add_u64 v[32:33], v[32:33], 0, v[74:75]
	s_movk_i32 s4, 0x1000
	s_waitcnt lgkmcnt(0)
	s_barrier
	s_movk_i32 s5, 0x2000
	v_add_co_u32_e32 v38, vcc, s4, v34
	global_load_dword v75, v[34:35], off
	global_load_dword v79, v[36:37], off
	global_load_dword v81, v[34:35], off offset:2048
	global_load_dword v85, v[36:37], off offset:2048
	v_addc_co_u32_e32 v39, vcc, 0, v35, vcc
	s_mov_b32 s98, s4
	s_mov_b32 s99, 0
	v_lshl_add_u64 v[40:41], v[36:37], 0, s[98:99]
	global_load_dword v95, v[38:39], off
	global_load_dword v99, v[40:41], off
	global_load_dword v104, v[38:39], off offset:2048
	global_load_dword v105, v[40:41], off offset:2048
	s_mov_b32 s98, s5
	s_mov_b32 s99, 0
	v_lshl_add_u64 v[38:39], v[34:35], 0, s[98:99]
	s_movk_i32 s6, 0x7000
	s_mov_b32 s98, s5
	s_mov_b32 s99, 0
	v_lshl_add_u64 v[40:41], v[36:37], 0, s[98:99]
	global_load_dword v106, v[38:39], off
	global_load_dword v107, v[40:41], off
	global_load_dword v110, v[38:39], off offset:2048
	global_load_dword v111, v[40:41], off offset:2048
	s_mov_b32 s98, s76
	s_mov_b32 s99, 0
	v_lshl_add_u64 v[38:39], v[34:35], 0, s[98:99]
	s_movk_i32 s79, 0xffc0
	s_mov_b32 s98, s76
	s_mov_b32 s99, 0
	v_lshl_add_u64 v[40:41], v[36:37], 0, s[98:99]
	global_load_dword v112, v[38:39], off
	global_load_dword v113, v[40:41], off
	global_load_dword v114, v[38:39], off offset:2048
	global_load_dword v115, v[40:41], off offset:2048
	s_mov_b32 s98, s33
	s_mov_b32 s99, 0
	v_lshl_add_u64 v[38:39], v[34:35], 0, s[98:99]
	v_mov_b32_e32 v109, v108
	s_mov_b32 s98, s33
	s_mov_b32 s99, 0
	v_lshl_add_u64 v[40:41], v[36:37], 0, s[98:99]
	global_load_dword v116, v[38:39], off
	global_load_dword v117, v[40:41], off
	global_load_dword v119, v[38:39], off offset:2048
	global_load_dword v165, v[40:41], off offset:2048
	s_mov_b32 s98, s77
	s_mov_b32 s99, 0
	v_lshl_add_u64 v[38:39], v[34:35], 0, s[98:99]
	s_mov_b64 s[82:83], 0
	s_mov_b32 s98, s77
	s_mov_b32 s99, 0
	v_lshl_add_u64 v[40:41], v[36:37], 0, s[98:99]
	global_load_dword v166, v[38:39], off
	global_load_dword v167, v[40:41], off
	global_load_dword v170, v[38:39], off offset:2048
	global_load_dword v171, v[40:41], off offset:2048
	s_mov_b32 s98, s78
	s_mov_b32 s99, 0
	v_lshl_add_u64 v[38:39], v[34:35], 0, s[98:99]
	v_lshlrev_b32_e32 v96, 1, v96
	s_mov_b32 s98, s78
	s_mov_b32 s99, 0
	v_lshl_add_u64 v[40:41], v[36:37], 0, s[98:99]
	global_load_dword v172, v[38:39], off
	s_mov_b32 s98, s6
	s_mov_b32 s99, 0
	v_lshl_add_u64 v[34:35], v[34:35], 0, s[98:99]
	global_load_dword v173, v[40:41], off
	global_load_dword v174, v[38:39], off offset:2048
	global_load_dword v175, v[40:41], off offset:2048
	s_mov_b32 s98, s6
	s_mov_b32 s99, 0
	v_lshl_add_u64 v[36:37], v[36:37], 0, s[98:99]
	global_load_dword v176, v[34:35], off
	global_load_dword v177, v[36:37], off
	global_load_dword v187, v[34:35], off offset:2048
	global_load_dword v188, v[36:37], off offset:2048
	global_load_dword v189, v[32:33], off
	s_mov_b32 s98, s4
	s_mov_b32 s99, 0
	v_lshl_add_u64 v[34:35], v[32:33], 0, s[98:99]
	global_load_dword v190, v[34:35], off
	s_mov_b32 s98, s5
	s_mov_b32 s99, 0
	v_lshl_add_u64 v[34:35], v[32:33], 0, s[98:99]
	global_load_dword v191, v[34:35], off
	s_mov_b32 s98, s76
	s_mov_b32 s99, 0
	v_lshl_add_u64 v[34:35], v[32:33], 0, s[98:99]
	global_load_dword v192, v[34:35], off
	s_mov_b32 s98, s33
	s_mov_b32 s99, 0
	v_lshl_add_u64 v[34:35], v[32:33], 0, s[98:99]
	global_load_dword v193, v[34:35], off
	s_mov_b32 s98, s77
	s_mov_b32 s99, 0
	v_lshl_add_u64 v[34:35], v[32:33], 0, s[98:99]
	global_load_dword v194, v[34:35], off
	s_mov_b32 s98, s78
	s_mov_b32 s99, 0
	v_lshl_add_u64 v[34:35], v[32:33], 0, s[98:99]
	v_add_co_u32_e32 v32, vcc, 0x7000, v32
	global_load_dword v195, v[34:35], off
	s_nop 0
	v_addc_co_u32_e32 v33, vcc, 0, v33, vcc
	global_load_dword v196, v[32:33], off
	v_lshlrev_b32_e32 v33, 6, v161
	v_lshlrev_b32_e32 v32, 11, v94
	v_add_u32_e32 v100, v129, v33
	v_add_u32_e32 v94, -2, v161
	v_lshlrev_b32_e32 v168, 11, v100
	v_add3_u32 v169, v32, v33, s79
	s_mov_b32 s79, 1
	s_waitcnt vmcnt(0)
	s_branch .LBB0_1097

.LBB0_1097:
	ds_read_b64 v[32:33], v127
	s_waitcnt vmcnt(1) lgkmcnt(0)
	v_lshlrev_b32_e32 v34, 16, v75
	v_and_b32_e32 v35, 0xffff0000, v75
	v_lshlrev_b32_e32 v36, 16, v79
	v_and_b32_e32 v37, 0xffff0000, v79
	v_pk_mul_f32 v[34:35], v[32:33], v[34:35] op_sel_hi:[0,1]
	v_cvt_pk_bf16_f32 v34, v34, v35
	v_pk_mul_f32 v[32:33], v[32:33], v[36:37] op_sel:[1,0]
	ds_write_b32 v135, v34
	v_cvt_pk_bf16_f32 v34, v32, v33
	ds_write_b32 v135, v34 offset:17408
	ds_read_b64 v[34:35], v136
	v_lshlrev_b32_e32 v36, 16, v81
	v_and_b32_e32 v37, 0xffff0000, v81
	v_lshlrev_b32_e32 v38, 16, v95
	v_and_b32_e32 v39, 0xffff0000, v95
	s_waitcnt lgkmcnt(0)
	v_pk_mul_f32 v[36:37], v[34:35], v[36:37] op_sel_hi:[0,1]
	v_cvt_pk_bf16_f32 v36, v36, v37
	ds_write_b32 v135, v36 offset:272
	v_lshlrev_b32_e32 v36, 16, v85
	v_and_b32_e32 v37, 0xffff0000, v85
	v_pk_mul_f32 v[34:35], v[34:35], v[36:37] op_sel:[1,0]
	v_lshlrev_b32_e32 v40, 16, v104
	v_cvt_pk_bf16_f32 v36, v34, v35
	ds_write_b32 v135, v36 offset:17680
	ds_read_b64 v[36:37], v137
	v_and_b32_e32 v41, 0xffff0000, v104
	v_lshlrev_b32_e32 v42, 16, v106
	v_and_b32_e32 v43, 0xffff0000, v106
	v_lshlrev_b32_e32 v44, 16, v110
	s_waitcnt lgkmcnt(0)
	v_pk_mul_f32 v[38:39], v[36:37], v[38:39] op_sel_hi:[0,1]
	v_cvt_pk_bf16_f32 v38, v38, v39
	ds_write_b32 v135, v38 offset:544
	v_lshlrev_b32_e32 v38, 16, v99
	v_and_b32_e32 v39, 0xffff0000, v99
	v_pk_mul_f32 v[38:39], v[36:37], v[38:39] op_sel:[1,0]
	v_and_b32_e32 v45, 0xffff0000, v110
	v_cvt_pk_bf16_f32 v36, v38, v39
	ds_write_b32 v135, v36 offset:17952
	ds_read_b64 v[36:37], v138
	v_lshlrev_b32_e32 v46, 16, v112
	v_and_b32_e32 v47, 0xffff0000, v112
	v_lshlrev_b32_e32 v48, 16, v114
	v_and_b32_e32 v49, 0xffff0000, v114
	s_waitcnt lgkmcnt(0)
	v_pk_mul_f32 v[40:41], v[36:37], v[40:41] op_sel_hi:[0,1]
	v_cvt_pk_bf16_f32 v40, v40, v41
	ds_write_b32 v135, v40 offset:816
	v_lshlrev_b32_e32 v40, 16, v105
	v_and_b32_e32 v41, 0xffff0000, v105
	v_pk_mul_f32 v[40:41], v[36:37], v[40:41] op_sel:[1,0]
	v_lshlrev_b32_e32 v50, 16, v116
	v_cvt_pk_bf16_f32 v36, v40, v41
	ds_write_b32 v135, v36 offset:18224
	ds_read_b64 v[36:37], v139
	v_and_b32_e32 v51, 0xffff0000, v116
	v_lshlrev_b32_e32 v52, 16, v119
	v_and_b32_e32 v53, 0xffff0000, v119
	v_lshlrev_b32_e32 v54, 16, v166
	s_waitcnt lgkmcnt(0)
	v_pk_mul_f32 v[42:43], v[36:37], v[42:43] op_sel_hi:[0,1]
	v_cvt_pk_bf16_f32 v42, v42, v43
	ds_write_b32 v135, v42 offset:1088
	v_lshlrev_b32_e32 v42, 16, v107
	v_and_b32_e32 v43, 0xffff0000, v107
	v_pk_mul_f32 v[42:43], v[36:37], v[42:43] op_sel:[1,0]
	v_and_b32_e32 v55, 0xffff0000, v166
	v_cvt_pk_bf16_f32 v36, v42, v43
	ds_write_b32 v135, v36 offset:18496
	ds_read_b64 v[36:37], v140
	v_lshlrev_b32_e32 v56, 16, v170
	v_and_b32_e32 v57, 0xffff0000, v170
	v_lshlrev_b32_e32 v58, 16, v172
	v_and_b32_e32 v59, 0xffff0000, v172
	s_waitcnt lgkmcnt(0)
	v_pk_mul_f32 v[44:45], v[36:37], v[44:45] op_sel_hi:[0,1]
	v_cvt_pk_bf16_f32 v44, v44, v45
	ds_write_b32 v135, v44 offset:1360
	v_lshlrev_b32_e32 v44, 16, v111
	v_and_b32_e32 v45, 0xffff0000, v111
	v_pk_mul_f32 v[44:45], v[36:37], v[44:45] op_sel:[1,0]
	v_lshlrev_b32_e32 v60, 16, v174
	v_cvt_pk_bf16_f32 v36, v44, v45
	ds_write_b32 v141, v36 offset:17408
	ds_read_b64 v[36:37], v142
	v_and_b32_e32 v61, 0xffff0000, v174
	v_lshlrev_b32_e32 v62, 16, v176
	v_and_b32_e32 v63, 0xffff0000, v176
	v_lshlrev_b32_e32 v102, 16, v187
	s_waitcnt lgkmcnt(0)
	v_pk_mul_f32 v[46:47], v[36:37], v[46:47] op_sel_hi:[0,1]
	v_cvt_pk_bf16_f32 v46, v46, v47
	ds_write_b32 v141, v46 offset:272
	v_lshlrev_b32_e32 v46, 16, v113
	v_and_b32_e32 v47, 0xffff0000, v113
	v_pk_mul_f32 v[46:47], v[36:37], v[46:47] op_sel:[1,0]
	v_and_b32_e32 v103, 0xffff0000, v187
	v_cvt_pk_bf16_f32 v36, v46, v47
	ds_write_b32 v141, v36 offset:17680
	ds_read_b64 v[36:37], v143
	v_lshlrev_b32_e32 v77, 16, v194
	v_or_b32_sdwa v200, v193, v77 dst_sel:DWORD dst_unused:UNUSED_PAD src0_sel:WORD_0 src1_sel:DWORD
	v_cmp_lt_u32_e32 vcc, s79, v161
	s_waitcnt lgkmcnt(0)
	v_pk_mul_f32 v[48:49], v[36:37], v[48:49] op_sel_hi:[0,1]
	v_cvt_pk_bf16_f32 v48, v48, v49
	ds_write_b32 v141, v48 offset:544
	v_lshlrev_b32_e32 v48, 16, v115
	v_and_b32_e32 v49, 0xffff0000, v115
	v_pk_mul_f32 v[48:49], v[36:37], v[48:49] op_sel:[1,0]
	s_nop 0
	v_cvt_pk_bf16_f32 v36, v48, v49
	ds_write_b32 v141, v36 offset:17952
	ds_read_b64 v[36:37], v144
	s_waitcnt lgkmcnt(0)
	v_pk_mul_f32 v[50:51], v[36:37], v[50:51] op_sel_hi:[0,1]
	v_cvt_pk_bf16_f32 v50, v50, v51
	ds_write_b32 v141, v50 offset:816
	v_lshlrev_b32_e32 v50, 16, v117
	v_and_b32_e32 v51, 0xffff0000, v117
	v_pk_mul_f32 v[50:51], v[36:37], v[50:51] op_sel:[1,0]
	s_nop 0
	v_cvt_pk_bf16_f32 v36, v50, v51
	ds_write_b32 v141, v36 offset:18224
	ds_read_b64 v[36:37], v145
	s_waitcnt lgkmcnt(0)
	v_pk_mul_f32 v[52:53], v[36:37], v[52:53] op_sel_hi:[0,1]
	v_cvt_pk_bf16_f32 v52, v52, v53
	ds_write_b32 v141, v52 offset:1088
	v_lshlrev_b32_e32 v52, 16, v165
	v_and_b32_e32 v53, 0xffff0000, v165
	v_pk_mul_f32 v[52:53], v[36:37], v[52:53] op_sel:[1,0]
	s_nop 0
	v_cvt_pk_bf16_f32 v36, v52, v53
	ds_write_b32 v141, v36 offset:18496
	ds_read_b64 v[36:37], v146
	s_waitcnt lgkmcnt(0)
	v_pk_mul_f32 v[54:55], v[36:37], v[54:55] op_sel_hi:[0,1]
	v_cvt_pk_bf16_f32 v54, v54, v55
	ds_write_b32 v141, v54 offset:1360
	v_lshlrev_b32_e32 v54, 16, v167
	v_and_b32_e32 v55, 0xffff0000, v167
	v_pk_mul_f32 v[54:55], v[36:37], v[54:55] op_sel:[1,0]
	s_nop 0
	v_cvt_pk_bf16_f32 v36, v54, v55
	ds_write_b32 v141, v36 offset:18768
	ds_read_b64 v[36:37], v147
	s_waitcnt lgkmcnt(0)
	v_pk_mul_f32 v[56:57], v[36:37], v[56:57] op_sel_hi:[0,1]
	v_cvt_pk_bf16_f32 v56, v56, v57
	ds_write_b32 v141, v56 offset:1632
	v_lshlrev_b32_e32 v56, 16, v171
	v_and_b32_e32 v57, 0xffff0000, v171
	v_pk_mul_f32 v[56:57], v[36:37], v[56:57] op_sel:[1,0]
	s_nop 0
	v_cvt_pk_bf16_f32 v36, v56, v57
	ds_write_b32 v141, v36 offset:19040
	ds_read_b64 v[36:37], v148
	s_waitcnt lgkmcnt(0)
	v_pk_mul_f32 v[58:59], v[36:37], v[58:59] op_sel_hi:[0,1]
	v_cvt_pk_bf16_f32 v58, v58, v59
	ds_write_b32 v141, v58 offset:1904
	v_lshlrev_b32_e32 v58, 16, v173
	v_and_b32_e32 v59, 0xffff0000, v173
	v_pk_mul_f32 v[58:59], v[36:37], v[58:59] op_sel:[1,0]
	s_nop 0
	v_cvt_pk_bf16_f32 v36, v58, v59
	ds_write_b32 v141, v36 offset:19312
	ds_read_b64 v[36:37], v149
	s_waitcnt lgkmcnt(0)
	v_pk_mul_f32 v[60:61], v[36:37], v[60:61] op_sel_hi:[0,1]
	v_cvt_pk_bf16_f32 v60, v60, v61
	ds_write_b32 v141, v60 offset:2176
	v_lshlrev_b32_e32 v60, 16, v175
	v_and_b32_e32 v61, 0xffff0000, v175
	v_pk_mul_f32 v[60:61], v[36:37], v[60:61] op_sel:[1,0]
	s_nop 0
	v_cvt_pk_bf16_f32 v36, v60, v61
	ds_write_b32 v141, v36 offset:19584
	ds_read_b64 v[36:37], v150
	s_waitcnt lgkmcnt(0)
	v_pk_mul_f32 v[62:63], v[36:37], v[62:63] op_sel_hi:[0,1]
	v_cvt_pk_bf16_f32 v62, v62, v63
	ds_write_b32 v141, v62 offset:2448
	v_lshlrev_b32_e32 v62, 16, v177
	v_and_b32_e32 v63, 0xffff0000, v177
	v_pk_mul_f32 v[62:63], v[36:37], v[62:63] op_sel:[1,0]
	s_nop 0
	v_cvt_pk_bf16_f32 v36, v62, v63
	ds_write_b32 v141, v36 offset:19856
	ds_read_b64 v[36:37], v151
	s_waitcnt lgkmcnt(0)
	v_pk_mul_f32 v[102:103], v[36:37], v[102:103] op_sel_hi:[0,1]
	v_cvt_pk_bf16_f32 v68, v102, v103
	v_lshlrev_b32_e32 v102, 16, v188
	v_and_b32_e32 v103, 0xffff0000, v188
	v_pk_mul_f32 v[102:103], v[36:37], v[102:103] op_sel:[1,0]
	ds_write_b32 v141, v68 offset:2720
	v_cvt_pk_bf16_f32 v36, v102, v103
	ds_write_b32 v141, v36 offset:20128
	v_lshlrev_b32_e32 v36, 16, v192
	v_lshlrev_b32_e32 v37, 16, v190
	v_lshlrev_b32_e32 v68, 16, v196
	v_or_b32_sdwa v199, v191, v36 dst_sel:DWORD dst_unused:UNUSED_PAD src0_sel:WORD_0 src1_sel:DWORD
	v_or_b32_sdwa v198, v189, v37 dst_sel:DWORD dst_unused:UNUSED_PAD src0_sel:WORD_0 src1_sel:DWORD
	v_or_b32_sdwa v201, v195, v68 dst_sel:DWORD dst_unused:UNUSED_PAD src0_sel:WORD_0 src1_sel:DWORD
	v_and_b32_e32 v36, 0xffff0000, v192
	v_and_b32_e32 v37, 0xffff0000, v190
	ds_write_b128 v152, v[198:201] offset:35840
	v_or_b32_sdwa v199, v191, v36 dst_sel:DWORD dst_unused:UNUSED_PAD src0_sel:WORD_1 src1_sel:DWORD
	v_or_b32_sdwa v198, v189, v37 dst_sel:DWORD dst_unused:UNUSED_PAD src0_sel:WORD_1 src1_sel:DWORD
	v_and_b32_e32 v36, 0xffff0000, v196
	v_and_b32_e32 v37, 0xffff0000, v194
	v_or_b32_sdwa v201, v195, v36 dst_sel:DWORD dst_unused:UNUSED_PAD src0_sel:WORD_1 src1_sel:DWORD
	v_or_b32_sdwa v200, v193, v37 dst_sel:DWORD dst_unused:UNUSED_PAD src0_sel:WORD_1 src1_sel:DWORD
	ds_write_b128 v152, v[198:201] offset:35984
	s_and_saveexec_b64 s[90:91], vcc
	s_cbranch_execz .LBB0_1099
	v_ashrrev_i32_e32 v95, 31, v94
	v_lshlrev_b64 v[36:37], 17, v[94:95]
	v_lshl_add_u64 v[176:177], v[86:87], 0, v[36:37]
	v_lshl_add_u64 v[188:189], v[88:89], 0, v[36:37]
	v_lshlrev_b64 v[36:37], 18, v[94:95]
	v_lshl_add_u64 v[36:37], v[90:91], 0, v[36:37]
	global_load_dword v75, v[176:177], off
	global_load_dword v79, v[188:189], off
	global_load_dword v81, v[176:177], off offset:2048
	global_load_dword v85, v[188:189], off offset:2048
	s_mov_b64 s[98:99], 0x1000
	v_lshl_add_u64 v[104:105], v[176:177], 0, s[98:99]
	s_mov_b64 s[98:99], 0x1000
	v_lshl_add_u64 v[106:107], v[188:189], 0, s[98:99]
	global_load_dword v95, v[104:105], off
	s_mov_b64 s[98:99], 0x2000
	v_lshl_add_u64 v[110:111], v[176:177], 0, s[98:99]
	global_load_dword v99, v[106:107], off
	global_load_dword v104, v[104:105], off offset:2048
	global_load_dword v105, v[106:107], off offset:2048
	s_mov_b64 s[98:99], 0x2000
	v_lshl_add_u64 v[112:113], v[188:189], 0, s[98:99]
	global_load_dword v106, v[110:111], off
	s_mov_b64 s[98:99], 0x3000
	v_lshl_add_u64 v[114:115], v[176:177], 0, s[98:99]
	global_load_dword v107, v[112:113], off
	global_load_dword v110, v[110:111], off offset:2048
	global_load_dword v111, v[112:113], off offset:2048
	s_mov_b64 s[98:99], 0x3000
	v_lshl_add_u64 v[116:117], v[188:189], 0, s[98:99]
	global_load_dword v112, v[114:115], off
	s_mov_b32 s98, s33
	s_mov_b32 s99, 0
	v_lshl_add_u64 v[166:167], v[176:177], 0, s[98:99]
	global_load_dword v113, v[116:117], off
	global_load_dword v114, v[114:115], off offset:2048
	global_load_dword v115, v[116:117], off offset:2048
	s_mov_b32 s98, s33
	s_mov_b32 s99, 0
	v_lshl_add_u64 v[170:171], v[188:189], 0, s[98:99]
	global_load_dword v116, v[166:167], off
	global_load_dword v117, v[170:171], off
	global_load_dword v119, v[166:167], off offset:2048
	global_load_dword v165, v[170:171], off offset:2048
	s_mov_b32 s98, s77
	s_mov_b32 s99, 0
	v_lshl_add_u64 v[170:171], v[176:177], 0, s[98:99]
	s_mov_b32 s98, s77
	s_mov_b32 s99, 0
	v_lshl_add_u64 v[172:173], v[188:189], 0, s[98:99]
	global_load_dword v166, v[170:171], off
	s_mov_b32 s98, s78
	s_mov_b32 s99, 0
	v_lshl_add_u64 v[174:175], v[176:177], 0, s[98:99]
	global_load_dword v167, v[172:173], off
	global_load_dword v170, v[170:171], off offset:2048
	global_load_dword v171, v[172:173], off offset:2048
	s_mov_b32 s98, s78
	s_mov_b32 s99, 0
	v_lshl_add_u64 v[190:191], v[188:189], 0, s[98:99]
	global_load_dword v172, v[174:175], off
	global_load_dword v173, v[190:191], off
	s_nop 0
	global_load_dword v174, v[174:175], off offset:2048
	s_nop 0
	global_load_dword v175, v[190:191], off offset:2048
	s_mov_b64 s[98:99], 0x7000
	v_lshl_add_u64 v[190:191], v[176:177], 0, s[98:99]
	s_mov_b64 s[98:99], 0x7000
	v_lshl_add_u64 v[188:189], v[188:189], 0, s[98:99]
	global_load_dword v176, v[190:191], off
	global_load_dword v177, v[188:189], off
	global_load_dword v187, v[190:191], off offset:2048
	s_nop 0
	global_load_dword v188, v[188:189], off offset:2048
	s_nop 0
	global_load_dword v189, v[36:37], off
	s_mov_b64 s[98:99], 0x1000
	v_lshl_add_u64 v[190:191], v[36:37], 0, s[98:99]
	s_mov_b64 s[98:99], 0x2000
	v_lshl_add_u64 v[192:193], v[36:37], 0, s[98:99]
	global_load_dword v190, v[190:191], off
	global_load_dword v191, v[192:193], off
	s_mov_b64 s[98:99], 0x3000
	v_lshl_add_u64 v[192:193], v[36:37], 0, s[98:99]
	s_mov_b64 s[98:99], 0x4000
	v_lshl_add_u64 v[194:195], v[36:37], 0, s[98:99]
	global_load_dword v192, v[192:193], off
	global_load_dword v193, v[194:195], off
	s_mov_b64 s[98:99], 0x5000
	v_lshl_add_u64 v[194:195], v[36:37], 0, s[98:99]
	s_mov_b64 s[98:99], 0x6000
	v_lshl_add_u64 v[196:197], v[36:37], 0, s[98:99]
	global_load_dword v194, v[194:195], off
	v_add_co_u32_e32 v36, vcc, 0x7000, v36
	global_load_dword v195, v[196:197], off
	s_nop 0
	v_addc_co_u32_e32 v37, vcc, 0, v37, vcc
	global_load_dword v196, v[36:37], off

.LBB0_1111:
	s_or_b64 exec, exec, s[82:83]
	s_and_saveexec_b64 s[66:67], s[64:65]
	s_cbranch_execz .LBB0_1076
	s_waitcnt vmcnt(0)
	v_mov_b32_e32 v99, v69
	v_readlane_b32 s4, v240, 5
	v_lshlrev_b64 v[32:33], 17, v[98:99]
	v_readlane_b32 s5, v240, 6
	v_mov_b32_e32 v85, v69
	v_mov_b32_e32 v81, v69
	v_lshl_add_u64 v[32:33], s[4:5], 0, v[32:33]
	v_lshl_add_u64 v[32:33], v[82:83], 2, v[32:33]
	v_lshl_add_u64 v[32:33], v[32:33], 0, v[84:85]
	v_lshl_add_u64 v[32:33], v[32:33], 0, v[80:81]
	v_mov_b32_e32 v79, v69
	v_lshl_add_u64 v[32:33], v[32:33], 0, v[78:79]
	global_store_dword v[32:33], v8, off
	global_store_dword v[32:33], v9, off offset:1024
	global_store_dword v[32:33], v10, off offset:2048
	global_store_dword v[32:33], v11, off offset:3072
	s_mov_b32 s98, s33
	s_mov_b32 s99, 0
	v_lshl_add_u64 v[8:9], v[32:33], 0, s[98:99]
	s_mov_b32 s4, 0x8000
	global_store_dword v[8:9], v0, off
	global_store_dword v[8:9], v1, off offset:1024
	global_store_dword v[8:9], v2, off offset:2048
	global_store_dword v[8:9], v3, off offset:3072
	s_mov_b32 s98, s4
	s_mov_b32 s99, 0
	v_lshl_add_u64 v[0:1], v[32:33], 0, s[98:99]
	s_mov_b32 s4, 0xc000
	global_store_dword v[0:1], v12, off
	global_store_dword v[0:1], v13, off offset:1024
	global_store_dword v[0:1], v14, off offset:2048
	global_store_dword v[0:1], v15, off offset:3072
	s_mov_b32 s98, s4
	s_mov_b32 s99, 0
	v_lshl_add_u64 v[0:1], v[32:33], 0, s[98:99]
	s_mov_b32 s4, 0x10000
	global_store_dword v[0:1], v4, off
	global_store_dword v[0:1], v5, off offset:1024
	global_store_dword v[0:1], v6, off offset:2048
	global_store_dword v[0:1], v7, off offset:3072
	s_mov_b32 s98, s4
	s_mov_b32 s99, 0
	v_lshl_add_u64 v[0:1], v[32:33], 0, s[98:99]
	s_mov_b32 s4, 0x14000
	global_store_dword v[0:1], v20, off
	global_store_dword v[0:1], v21, off offset:1024
	global_store_dword v[0:1], v22, off offset:2048
	global_store_dword v[0:1], v23, off offset:3072
	s_mov_b32 s98, s4
	s_mov_b32 s99, 0
	v_lshl_add_u64 v[0:1], v[32:33], 0, s[98:99]
	global_store_dword v[0:1], v16, off
	global_store_dword v[0:1], v17, off offset:1024
	global_store_dword v[0:1], v18, off offset:2048
	global_store_dword v[0:1], v19, off offset:3072
	s_mov_b64 s[98:99], 0x18000
	v_lshl_add_u64 v[0:1], v[32:33], 0, s[98:99]
	global_store_dword v[0:1], v28, off
	global_store_dword v[0:1], v29, off offset:1024
	global_store_dword v[0:1], v30, off offset:2048
	global_store_dword v[0:1], v31, off offset:3072
	v_add_co_u32_e32 v0, vcc, 0x1c000, v32
	s_nop 1
	v_addc_co_u32_e32 v1, vcc, 0, v33, vcc
	global_store_dword v[0:1], v24, off
	global_store_dword v[0:1], v25, off offset:1024
	global_store_dword v[0:1], v26, off offset:2048
	global_store_dword v[0:1], v27, off offset:3072
	s_branch .LBB0_1076

.LBB0_1458:
	s_movk_i32 s42, 0x7f
	v_add_u32_e32 v0, 0xffffff80, v100
	v_cmp_lt_i32_e64 s[42:43], s42, v100
	v_cmp_gt_i32_e32 vcc, s33, v100
	v_lshlrev_b32_e32 v82, 2, v64
	v_cndmask_b32_e64 v0, v100, v0, s[42:43]
	v_lshrrev_b32_e32 v1, 31, v0
	v_add_u32_e32 v1, v0, v1
	v_and_b32_e32 v2, 0x3fffffe, v1
	v_bfe_u32 v34, v1, 1, 3
	v_ashrrev_i32_e32 v1, 31, v0
	v_lshrrev_b32_e32 v1, 28, v1
	v_sub_u32_e32 v2, v0, v2
	v_add_u32_e32 v0, v0, v1
	v_ashrrev_i32_e32 v32, 4, v0
	v_lshlrev_b32_e32 v80, 6, v2
	v_lshlrev_b32_e32 v0, 4, v32
	v_ashrrev_i32_e32 v81, 31, v80
	v_or3_b32 v84, v0, v34, 8
	v_lshlrev_b32_e32 v78, 2, v68
	v_mov_b32_e32 v16, v67
	v_mov_b32_e32 v17, v67
	v_mov_b32_e32 v18, v67
	v_mov_b32_e32 v19, v67
	v_mov_b32_e32 v0, v67
	v_mov_b32_e32 v1, v67
	v_mov_b32_e32 v2, v67
	v_mov_b32_e32 v3, v67
	v_mov_b32_e32 v8, v67
	v_mov_b32_e32 v9, v67
	v_mov_b32_e32 v10, v67
	v_mov_b32_e32 v11, v67
	v_mov_b32_e32 v4, v67
	v_mov_b32_e32 v5, v67
	v_mov_b32_e32 v6, v67
	v_mov_b32_e32 v7, v67
	v_mov_b32_e32 v20, v67
	v_mov_b32_e32 v21, v67
	v_mov_b32_e32 v22, v67
	v_mov_b32_e32 v23, v67
	v_mov_b32_e32 v12, v67
	v_mov_b32_e32 v13, v67
	v_mov_b32_e32 v14, v67
	v_mov_b32_e32 v15, v67
	v_mov_b32_e32 v24, v67
	v_mov_b32_e32 v25, v67
	v_mov_b32_e32 v26, v67
	v_mov_b32_e32 v27, v67
	v_mov_b32_e32 v28, v67
	v_mov_b32_e32 v29, v67
	v_mov_b32_e32 v30, v67
	v_mov_b32_e32 v31, v67
	s_and_saveexec_b64 s[56:57], vcc
	s_cbranch_execz .LBB0_1460
	s_waitcnt vmcnt(0)
	v_ashrrev_i32_e32 v85, 31, v84
	v_readlane_b32 s80, v241, 18
	v_lshlrev_b64 v[0:1], 16, v[84:85]
	v_readlane_b32 s90, v241, 28
	v_readlane_b32 s91, v241, 29
	v_mov_b32_e32 v77, v67
	v_mov_b32_e32 v83, v67
	v_lshl_add_u64 v[0:1], s[90:91], 0, v[0:1]
	v_lshl_add_u64 v[0:1], v[80:81], 2, v[0:1]
	v_lshl_add_u64 v[0:1], v[0:1], 0, v[76:77]
	v_lshl_add_u64 v[0:1], v[0:1], 0, v[82:83]
	v_mov_b32_e32 v79, v67
	v_lshl_add_u64 v[24:25], v[0:1], 0, v[78:79]
	v_readlane_b32 s81, v241, 19
	s_mov_b32 s98, s60
	s_mov_b32 s99, 0
	v_lshl_add_u64 v[4:5], v[24:25], 0, s[98:99]
	v_readlane_b32 s82, v241, 20
	s_nop 0
	global_load_dword v16, v[24:25], off
	global_load_dword v17, v[24:25], off offset:512
	global_load_dword v18, v[24:25], off offset:1024
	global_load_dword v19, v[24:25], off offset:1536
	global_load_dword v0, v[4:5], off
	global_load_dword v1, v[4:5], off offset:512
	global_load_dword v2, v[4:5], off offset:1024
	global_load_dword v3, v[4:5], off offset:1536
	s_mov_b32 s98, s61
	s_mov_b32 s99, 0
	v_lshl_add_u64 v[4:5], v[24:25], 0, s[98:99]
	v_readlane_b32 s83, v241, 21
	s_nop 0
	s_mov_b32 s98, s62
	s_mov_b32 s99, 0
	v_lshl_add_u64 v[12:13], v[24:25], 0, s[98:99]
	v_readlane_b32 s84, v241, 22
	s_nop 0
	global_load_dword v8, v[4:5], off
	global_load_dword v9, v[4:5], off offset:512
	global_load_dword v10, v[4:5], off offset:1024
	global_load_dword v11, v[4:5], off offset:1536
	s_nop 0
	global_load_dword v4, v[12:13], off
	global_load_dword v5, v[12:13], off offset:512
	global_load_dword v6, v[12:13], off offset:1024
	global_load_dword v7, v[12:13], off offset:1536
	s_mov_b32 s98, s63
	s_mov_b32 s99, 0
	v_lshl_add_u64 v[12:13], v[24:25], 0, s[98:99]
	v_readlane_b32 s85, v241, 23
	s_nop 0
	s_mov_b32 s98, s64
	s_mov_b32 s99, 0
	v_lshl_add_u64 v[26:27], v[24:25], 0, s[98:99]
	v_readlane_b32 s86, v241, 24
	s_nop 0
	v_add_co_u32_e32 v28, vcc, 0xc000, v24
	global_load_dword v20, v[12:13], off
	global_load_dword v21, v[12:13], off offset:512
	global_load_dword v22, v[12:13], off offset:1024
	global_load_dword v23, v[12:13], off offset:1536
	s_nop 0
	global_load_dword v12, v[26:27], off
	global_load_dword v13, v[26:27], off offset:512
	global_load_dword v14, v[26:27], off offset:1024
	global_load_dword v15, v[26:27], off offset:1536
	v_addc_co_u32_e32 v29, vcc, 0, v25, vcc
	v_add_co_u32_e32 v36, vcc, 0xe000, v24
	v_readlane_b32 s87, v241, 25
	s_nop 0
	v_addc_co_u32_e32 v37, vcc, 0, v25, vcc
	global_load_dword v24, v[28:29], off
	global_load_dword v25, v[28:29], off offset:512
	global_load_dword v26, v[28:29], off offset:1024
	global_load_dword v27, v[28:29], off offset:1536
	s_nop 0
	global_load_dword v28, v[36:37], off
	global_load_dword v29, v[36:37], off offset:512
	global_load_dword v30, v[36:37], off offset:1024
	global_load_dword v31, v[36:37], off offset:1536
	v_readlane_b32 s88, v241, 26
	v_readlane_b32 s89, v241, 27
	v_readlane_b32 s92, v241, 30
	v_readlane_b32 s93, v241, 31
	v_readlane_b32 s94, v241, 32
	v_readlane_b32 s95, v241, 33
	v_readlane_b32 s80, v241, 37
	v_readlane_b32 s92, v241, 49
	v_readlane_b32 s93, v241, 50
	v_readlane_b32 s94, v241, 51
	v_readlane_b32 s95, v241, 52
	v_readlane_b32 s81, v241, 38
	v_readlane_b32 s82, v241, 39
	v_readlane_b32 s83, v241, 40
	v_readlane_b32 s84, v241, 41
	v_readlane_b32 s85, v241, 42
	v_readlane_b32 s86, v241, 43
	v_readlane_b32 s87, v241, 44
	v_readlane_b32 s88, v241, 45
	v_readlane_b32 s89, v241, 46
	v_readlane_b32 s90, v241, 47
	v_readlane_b32 s91, v241, 48
.LBB0_1460:
	s_or_b64 exec, exec, s[56:57]
	v_ashrrev_i32_e32 v33, 31, v32
	v_lshlrev_b64 v[36:37], 11, v[32:33]
	s_mov_b64 s[56:57], 0x2000
	v_lshl_add_u64 v[36:37], v[36:37], 0, s[56:57]
	v_lshlrev_b64 v[32:33], 8, v[32:33]
	v_cndmask_b32_e64 v33, v37, v33, s[42:43]
	v_cndmask_b32_e64 v32, v36, v32, s[42:43]
	v_lshlrev_b64 v[36:37], 11, v[32:33]
	v_cndmask_b32_e64 v77, 32, 4, s[42:43]
	v_lshl_add_u64 v[38:39], s[68:69], 0, v[36:37]
	v_lshlrev_b32_e32 v66, 8, v34
	v_lshl_add_u64 v[40:41], s[48:49], 0, v[36:37]
	v_lshl_add_u64 v[36:37], s[50:51], 0, v[36:37]
	v_lshl_add_u64 v[38:39], v[38:39], 0, v[66:67]
	v_lshl_add_u64 v[40:41], v[40:41], 0, v[66:67]
	v_lshl_add_u64 v[36:37], v[36:37], 0, v[66:67]
	v_add_u32_e32 v66, -1, v77
	v_lshl_add_u64 v[36:37], v[80:81], 1, v[36:37]
	v_lshlrev_b64 v[42:43], 17, v[66:67]
	v_lshl_add_u64 v[44:45], v[38:39], 0, v[42:43]
	v_mov_b32_e32 v71, v67
	v_lshl_add_u64 v[46:47], v[40:41], 0, v[42:43]
	v_lshl_add_u64 v[42:43], v[36:37], 0, v[42:43]
	v_mov_b32_e32 v73, v67
	v_lshl_add_u64 v[44:45], v[44:45], 0, v[70:71]
	v_lshl_add_u64 v[46:47], v[46:47], 0, v[70:71]
	v_lshl_add_u64 v[42:43], v[42:43], 0, v[72:73]
	s_waitcnt vmcnt(0)
	global_load_dword v79, v[44:45], off
	global_load_dword v83, v[44:45], off offset:2048
	global_load_dword v85, v[46:47], off
	global_load_dword v93, v[46:47], off offset:2048
	s_mov_b32 s98, s65
	s_mov_b32 s99, 0
	v_lshl_add_u64 v[48:49], v[44:45], 0, s[98:99]
	v_lshlrev_b32_e32 v33, 6, v77
	s_mov_b32 s98, s65
	s_mov_b32 s99, 0
	v_lshl_add_u64 v[50:51], v[46:47], 0, s[98:99]
	v_lshlrev_b32_e32 v34, 7, v34
	global_load_dword v124, v[48:49], off
	global_load_dword v125, v[48:49], off offset:2048
	global_load_dword v126, v[50:51], off
	global_load_dword v127, v[50:51], off offset:2048
	s_mov_b32 s98, s60
	s_mov_b32 s99, 0
	v_lshl_add_u64 v[48:49], v[44:45], 0, s[98:99]
	v_lshl_add_u64 v[86:87], v[38:39], 0, v[70:71]
	s_mov_b32 s98, s60
	s_mov_b32 s99, 0
	v_lshl_add_u64 v[50:51], v[46:47], 0, s[98:99]
	v_lshl_add_u64 v[88:89], v[40:41], 0, v[70:71]
	global_load_dword v128, v[48:49], off
	global_load_dword v129, v[48:49], off offset:2048
	global_load_dword v130, v[50:51], off
	global_load_dword v131, v[50:51], off offset:2048
	s_mov_b32 s98, s66
	s_mov_b32 s99, 0
	v_lshl_add_u64 v[48:49], v[44:45], 0, s[98:99]
	v_add3_u32 v71, v113, v33, v32
	s_mov_b32 s98, s66
	s_mov_b32 s99, 0
	v_lshl_add_u64 v[50:51], v[46:47], 0, s[98:99]
	s_mov_b32 s73, 1
	global_load_dword v132, v[48:49], off
	global_load_dword v133, v[48:49], off offset:2048
	global_load_dword v134, v[50:51], off
	global_load_dword v135, v[50:51], off offset:2048
	s_mov_b32 s98, s61
	s_mov_b32 s99, 0
	v_lshl_add_u64 v[48:49], v[44:45], 0, s[98:99]
	v_lshl_add_u64 v[90:91], v[36:37], 0, v[72:73]
	s_mov_b32 s98, s61
	s_mov_b32 s99, 0
	v_lshl_add_u64 v[50:51], v[46:47], 0, s[98:99]
	v_add_u32_e32 v92, -2, v77
	global_load_dword v136, v[48:49], off
	global_load_dword v137, v[48:49], off offset:2048
	global_load_dword v138, v[50:51], off
	global_load_dword v139, v[50:51], off offset:2048
	s_mov_b32 s98, s67
	s_mov_b32 s99, 0
	v_lshl_add_u64 v[48:49], v[44:45], 0, s[98:99]
	v_lshlrev_b32_e32 v73, 10, v71
	s_mov_b32 s98, s67
	s_mov_b32 s99, 0
	v_lshl_add_u64 v[50:51], v[46:47], 0, s[98:99]
	s_mov_b64 s[56:57], 0
	global_load_dword v140, v[48:49], off
	global_load_dword v141, v[48:49], off offset:2048
	global_load_dword v142, v[50:51], off
	global_load_dword v143, v[50:51], off offset:2048
	s_mov_b32 s98, s62
	s_mov_b32 s99, 0
	v_lshl_add_u64 v[48:49], v[44:45], 0, s[98:99]
	v_lshlrev_b32_e32 v94, 1, v34
	s_mov_b32 s98, s62
	s_mov_b32 s99, 0
	v_lshl_add_u64 v[50:51], v[46:47], 0, s[98:99]
	s_mov_b32 s98, s72
	s_mov_b32 s99, 0
	v_lshl_add_u64 v[44:45], v[44:45], 0, s[98:99]
	global_load_dword v144, v[48:49], off
	global_load_dword v145, v[48:49], off offset:2048
	global_load_dword v146, v[50:51], off
	global_load_dword v147, v[50:51], off offset:2048
	s_mov_b32 s98, s72
	s_mov_b32 s99, 0
	v_lshl_add_u64 v[46:47], v[46:47], 0, s[98:99]
	global_load_dword v148, v[44:45], off
	global_load_dword v149, v[44:45], off offset:2048
	global_load_dword v150, v[46:47], off
	global_load_dword v151, v[46:47], off offset:2048
	global_load_dword v152, v[42:43], off
	global_load_dword v153, v[42:43], off offset:2048
	s_mov_b32 s98, s65
	s_mov_b32 s99, 0
	v_lshl_add_u64 v[44:45], v[42:43], 0, s[98:99]
	s_mov_b32 s98, s60
	s_mov_b32 s99, 0
	v_lshl_add_u64 v[46:47], v[42:43], 0, s[98:99]
	v_add_co_u32_e32 v42, vcc, 0x3000, v42
	s_nop 1
	v_addc_co_u32_e32 v43, vcc, 0, v43, vcc
	global_load_dword v154, v[44:45], off
	global_load_dword v155, v[44:45], off offset:2048
	global_load_dword v156, v[46:47], off
	global_load_dword v157, v[46:47], off offset:2048
	global_load_dword v158, v[42:43], off
	global_load_dword v159, v[42:43], off offset:2048
	s_waitcnt vmcnt(0)
	s_branch .LBB0_1462

.LBB0_1464:
	s_or_b64 exec, exec, s[58:59]
	v_lshlrev_b32_e32 v32, 16, v155
	v_lshlrev_b32_e32 v34, 16, v153
	v_lshlrev_b32_e32 v95, 16, v159
	v_lshlrev_b32_e32 v162, 16, v157
	v_or_b32_sdwa v161, v154, v32 dst_sel:DWORD dst_unused:UNUSED_PAD src0_sel:WORD_0 src1_sel:DWORD
	v_or_b32_sdwa v160, v152, v34 dst_sel:DWORD dst_unused:UNUSED_PAD src0_sel:WORD_0 src1_sel:DWORD
	v_or_b32_sdwa v163, v158, v95 dst_sel:DWORD dst_unused:UNUSED_PAD src0_sel:WORD_0 src1_sel:DWORD
	v_or_b32_sdwa v162, v156, v162 dst_sel:DWORD dst_unused:UNUSED_PAD src0_sel:WORD_0 src1_sel:DWORD
	v_and_b32_e32 v32, 0xffff0000, v155
	v_and_b32_e32 v34, 0xffff0000, v153
	ds_write_b128 v115, v[160:163] offset:35840
	v_or_b32_sdwa v161, v154, v32 dst_sel:DWORD dst_unused:UNUSED_PAD src0_sel:WORD_1 src1_sel:DWORD
	v_or_b32_sdwa v160, v152, v34 dst_sel:DWORD dst_unused:UNUSED_PAD src0_sel:WORD_1 src1_sel:DWORD
	v_and_b32_e32 v32, 0xffff0000, v159
	v_and_b32_e32 v34, 0xffff0000, v157
	v_or_b32_sdwa v163, v158, v32 dst_sel:DWORD dst_unused:UNUSED_PAD src0_sel:WORD_1 src1_sel:DWORD
	v_or_b32_sdwa v162, v156, v34 dst_sel:DWORD dst_unused:UNUSED_PAD src0_sel:WORD_1 src1_sel:DWORD
	v_cmp_lt_u32_e32 vcc, s73, v77
	ds_write_b128 v115, v[160:163] offset:35984
	s_and_saveexec_b64 s[58:59], vcc
	s_cbranch_execz .LBB0_1461
	v_ashrrev_i32_e32 v93, 31, v92
	v_lshlrev_b64 v[124:125], 17, v[92:93]
	v_lshl_add_u64 v[148:149], v[86:87], 0, v[124:125]
	v_lshl_add_u64 v[150:151], v[88:89], 0, v[124:125]
	v_lshl_add_u64 v[154:155], v[90:91], 0, v[124:125]
	global_load_dword v79, v[148:149], off
	global_load_dword v83, v[148:149], off offset:2048
	global_load_dword v85, v[150:151], off
	global_load_dword v93, v[150:151], off offset:2048
	s_mov_b64 s[98:99], 0x1000
	v_lshl_add_u64 v[126:127], v[148:149], 0, s[98:99]
	s_mov_b64 s[98:99], 0x1000
	v_lshl_add_u64 v[128:129], v[150:151], 0, s[98:99]
	s_mov_b32 s98, s60
	s_mov_b32 s99, 0
	v_lshl_add_u64 v[130:131], v[148:149], 0, s[98:99]
	global_load_dword v124, v[126:127], off
	global_load_dword v125, v[126:127], off offset:2048
	global_load_dword v126, v[128:129], off
	global_load_dword v127, v[128:129], off offset:2048
	s_mov_b32 s98, s60
	s_mov_b32 s99, 0
	v_lshl_add_u64 v[132:133], v[150:151], 0, s[98:99]
	s_mov_b32 s98, s66
	s_mov_b32 s99, 0
	v_lshl_add_u64 v[134:135], v[148:149], 0, s[98:99]
	global_load_dword v128, v[130:131], off
	global_load_dword v129, v[130:131], off offset:2048
	global_load_dword v130, v[132:133], off
	global_load_dword v131, v[132:133], off offset:2048
	s_mov_b32 s98, s66
	s_mov_b32 s99, 0
	v_lshl_add_u64 v[136:137], v[150:151], 0, s[98:99]
	s_mov_b32 s98, s61
	s_mov_b32 s99, 0
	v_lshl_add_u64 v[138:139], v[148:149], 0, s[98:99]
	global_load_dword v132, v[134:135], off
	global_load_dword v133, v[134:135], off offset:2048
	global_load_dword v134, v[136:137], off
	global_load_dword v135, v[136:137], off offset:2048
	s_mov_b32 s98, s61
	s_mov_b32 s99, 0
	v_lshl_add_u64 v[140:141], v[150:151], 0, s[98:99]
	s_mov_b32 s98, s67
	s_mov_b32 s99, 0
	v_lshl_add_u64 v[142:143], v[148:149], 0, s[98:99]
	global_load_dword v136, v[138:139], off
	global_load_dword v137, v[138:139], off offset:2048
	global_load_dword v138, v[140:141], off
	global_load_dword v139, v[140:141], off offset:2048
	s_mov_b32 s98, s67
	s_mov_b32 s99, 0
	v_lshl_add_u64 v[144:145], v[150:151], 0, s[98:99]
	s_mov_b32 s98, s62
	s_mov_b32 s99, 0
	v_lshl_add_u64 v[146:147], v[148:149], 0, s[98:99]
	global_load_dword v140, v[142:143], off
	global_load_dword v141, v[142:143], off offset:2048
	global_load_dword v142, v[144:145], off
	global_load_dword v143, v[144:145], off offset:2048
	s_mov_b32 s98, s62
	s_mov_b32 s99, 0
	v_lshl_add_u64 v[152:153], v[150:151], 0, s[98:99]
	global_load_dword v144, v[146:147], off
	global_load_dword v145, v[146:147], off offset:2048
	s_nop 0
	global_load_dword v146, v[152:153], off
	global_load_dword v147, v[152:153], off offset:2048
	s_mov_b64 s[98:99], 0x7000
	v_lshl_add_u64 v[152:153], v[148:149], 0, s[98:99]
	s_mov_b64 s[98:99], 0x7000
	v_lshl_add_u64 v[156:157], v[150:151], 0, s[98:99]
	global_load_dword v148, v[152:153], off
	global_load_dword v149, v[152:153], off offset:2048
	global_load_dword v150, v[156:157], off
	global_load_dword v151, v[156:157], off offset:2048
	s_nop 0
	global_load_dword v152, v[154:155], off
	global_load_dword v153, v[154:155], off offset:2048
	s_mov_b64 s[98:99], 0x1000
	v_lshl_add_u64 v[156:157], v[154:155], 0, s[98:99]
	s_mov_b64 s[98:99], 0x2000
	v_lshl_add_u64 v[158:159], v[154:155], 0, s[98:99]
	v_add_co_u32_e32 v160, vcc, 0x3000, v154
	s_nop 1
	v_addc_co_u32_e32 v161, vcc, 0, v155, vcc
	global_load_dword v154, v[156:157], off
	global_load_dword v155, v[156:157], off offset:2048
	s_nop 0
	global_load_dword v156, v[158:159], off
	global_load_dword v157, v[158:159], off offset:2048
	s_nop 0
	global_load_dword v158, v[160:161], off
	global_load_dword v159, v[160:161], off offset:2048
	s_branch .LBB0_1461
.LBB0_1466:
	s_or_b64 exec, exec, s[56:57]
	s_and_saveexec_b64 s[56:57], s[42:43]
	s_cbranch_execz .LBB0_1457
	s_waitcnt vmcnt(0)
	v_ashrrev_i32_e32 v85, 31, v84
	v_lshlrev_b64 v[32:33], 16, v[84:85]
	v_lshl_add_u64 v[32:33], s[52:53], 0, v[32:33]
	v_lshl_add_u64 v[32:33], v[80:81], 2, v[32:33]
	v_mov_b32_e32 v77, v67
	v_lshl_add_u64 v[32:33], v[32:33], 0, v[76:77]
	v_mov_b32_e32 v83, v67
	v_lshl_add_u64 v[32:33], v[32:33], 0, v[82:83]
	v_mov_b32_e32 v79, v67
	v_lshl_add_u64 v[32:33], v[32:33], 0, v[78:79]
	global_store_dword v[32:33], v16, off
	global_store_dword v[32:33], v17, off offset:512
	global_store_dword v[32:33], v18, off offset:1024
	global_store_dword v[32:33], v19, off offset:1536
	s_mov_b32 s98, s60
	s_mov_b32 s99, 0
	v_lshl_add_u64 v[16:17], v[32:33], 0, s[98:99]
	global_store_dword v[16:17], v0, off
	global_store_dword v[16:17], v1, off offset:512
	global_store_dword v[16:17], v2, off offset:1024
	global_store_dword v[16:17], v3, off offset:1536
	s_mov_b32 s98, s61
	s_mov_b32 s99, 0
	v_lshl_add_u64 v[0:1], v[32:33], 0, s[98:99]
	global_store_dword v[0:1], v8, off
	global_store_dword v[0:1], v9, off offset:512
	global_store_dword v[0:1], v10, off offset:1024
	global_store_dword v[0:1], v11, off offset:1536
	s_mov_b32 s98, s62
	s_mov_b32 s99, 0
	v_lshl_add_u64 v[0:1], v[32:33], 0, s[98:99]
	global_store_dword v[0:1], v4, off
	global_store_dword v[0:1], v5, off offset:512
	global_store_dword v[0:1], v6, off offset:1024
	global_store_dword v[0:1], v7, off offset:1536
	s_mov_b32 s98, s63
	s_mov_b32 s99, 0
	v_lshl_add_u64 v[0:1], v[32:33], 0, s[98:99]
	global_store_dword v[0:1], v20, off
	global_store_dword v[0:1], v21, off offset:512
	global_store_dword v[0:1], v22, off offset:1024
	global_store_dword v[0:1], v23, off offset:1536
	s_mov_b32 s98, s64
	s_mov_b32 s99, 0
	v_lshl_add_u64 v[0:1], v[32:33], 0, s[98:99]
	global_store_dword v[0:1], v12, off
	global_store_dword v[0:1], v13, off offset:512
	global_store_dword v[0:1], v14, off offset:1024
	global_store_dword v[0:1], v15, off offset:1536
	s_mov_b64 s[98:99], 0xc000
	v_lshl_add_u64 v[0:1], v[32:33], 0, s[98:99]
	global_store_dword v[0:1], v24, off
	global_store_dword v[0:1], v25, off offset:512
	global_store_dword v[0:1], v26, off offset:1024
	global_store_dword v[0:1], v27, off offset:1536
	v_add_co_u32_e32 v0, vcc, 0xe000, v32
	s_nop 1
	v_addc_co_u32_e32 v1, vcc, 0, v33, vcc
	global_store_dword v[0:1], v28, off
	global_store_dword v[0:1], v29, off offset:512
	global_store_dword v[0:1], v30, off offset:1024
	global_store_dword v[0:1], v31, off offset:1536
	s_branch .LBB0_1457

.LBB0_1473:
	s_movk_i32 s38, 0x80
	v_cmp_gt_i32_e32 vcc, s38, v100
	v_add_u32_e32 v0, 0xffffff80, v100
	v_cmp_lt_i32_e64 s[38:39], s33, v100
	v_lshlrev_b32_e32 v78, 2, v66
	v_mov_b32_e32 v12, v65
	v_cndmask_b32_e64 v0, v100, v0, s[38:39]
	v_lshrrev_b32_e32 v1, 31, v0
	v_add_u32_e32 v1, v0, v1
	v_and_b32_e32 v2, 0x3fffffe, v1
	v_bfe_u32 v34, v1, 1, 3
	v_ashrrev_i32_e32 v1, 31, v0
	v_lshrrev_b32_e32 v1, 28, v1
	v_sub_u32_e32 v2, v0, v2
	v_add_u32_e32 v0, v0, v1
	v_ashrrev_i32_e32 v32, 4, v0
	v_lshlrev_b32_e32 v80, 6, v2
	v_lshl_or_b32 v82, v32, 4, v34
	v_ashrrev_i32_e32 v81, 31, v80
	v_ashrrev_i32_e32 v83, 31, v82
	v_mov_b32_e32 v13, v65
	v_mov_b32_e32 v14, v65
	v_mov_b32_e32 v15, v65
	v_mov_b32_e32 v0, v65
	v_mov_b32_e32 v1, v65
	v_mov_b32_e32 v2, v65
	v_mov_b32_e32 v3, v65
	v_mov_b32_e32 v8, v65
	v_mov_b32_e32 v9, v65
	v_mov_b32_e32 v10, v65
	v_mov_b32_e32 v11, v65
	v_mov_b32_e32 v4, v65
	v_mov_b32_e32 v5, v65
	v_mov_b32_e32 v6, v65
	v_mov_b32_e32 v7, v65
	v_mov_b32_e32 v20, v65
	v_mov_b32_e32 v21, v65
	v_mov_b32_e32 v22, v65
	v_mov_b32_e32 v23, v65
	v_mov_b32_e32 v16, v65
	v_mov_b32_e32 v17, v65
	v_mov_b32_e32 v18, v65
	v_mov_b32_e32 v19, v65
	v_mov_b32_e32 v24, v65
	v_mov_b32_e32 v25, v65
	v_mov_b32_e32 v26, v65
	v_mov_b32_e32 v27, v65
	v_mov_b32_e32 v28, v65
	v_mov_b32_e32 v29, v65
	v_mov_b32_e32 v30, v65
	v_mov_b32_e32 v31, v65
	s_and_saveexec_b64 s[58:59], vcc
	s_cbranch_execz .LBB0_1475
	v_readlane_b32 s80, v241, 18
	v_lshlrev_b64 v[0:1], 16, v[82:83]
	v_readlane_b32 s90, v241, 28
	v_readlane_b32 s91, v241, 29
	s_waitcnt vmcnt(0)
	v_mov_b32_e32 v75, v65
	v_mov_b32_e32 v77, v65
	v_lshl_add_u64 v[0:1], s[90:91], 0, v[0:1]
	v_lshl_add_u64 v[0:1], v[80:81], 2, v[0:1]
	v_lshl_add_u64 v[0:1], v[0:1], 0, v[74:75]
	v_lshl_add_u64 v[0:1], v[0:1], 0, v[76:77]
	v_mov_b32_e32 v79, v65
	v_lshl_add_u64 v[24:25], v[0:1], 0, v[78:79]
	v_readlane_b32 s81, v241, 19
	s_mov_b32 s98, s62
	s_mov_b32 s99, 0
	v_lshl_add_u64 v[4:5], v[24:25], 0, s[98:99]
	v_readlane_b32 s82, v241, 20
	s_nop 0
	global_load_dword v12, v[24:25], off
	global_load_dword v13, v[24:25], off offset:512
	global_load_dword v14, v[24:25], off offset:1024
	global_load_dword v15, v[24:25], off offset:1536
	global_load_dword v0, v[4:5], off
	global_load_dword v1, v[4:5], off offset:512
	global_load_dword v2, v[4:5], off offset:1024
	global_load_dword v3, v[4:5], off offset:1536
	s_mov_b32 s98, s63
	s_mov_b32 s99, 0
	v_lshl_add_u64 v[4:5], v[24:25], 0, s[98:99]
	v_readlane_b32 s83, v241, 21
	s_nop 0
	s_mov_b32 s98, s64
	s_mov_b32 s99, 0
	v_lshl_add_u64 v[16:17], v[24:25], 0, s[98:99]
	v_readlane_b32 s84, v241, 22
	s_nop 0
	global_load_dword v8, v[4:5], off
	global_load_dword v9, v[4:5], off offset:512
	global_load_dword v10, v[4:5], off offset:1024
	global_load_dword v11, v[4:5], off offset:1536
	s_nop 0
	global_load_dword v4, v[16:17], off
	global_load_dword v5, v[16:17], off offset:512
	global_load_dword v6, v[16:17], off offset:1024
	global_load_dword v7, v[16:17], off offset:1536
	s_mov_b32 s98, s65
	s_mov_b32 s99, 0
	v_lshl_add_u64 v[16:17], v[24:25], 0, s[98:99]
	v_readlane_b32 s85, v241, 23
	s_nop 0
	s_mov_b32 s98, s66
	s_mov_b32 s99, 0
	v_lshl_add_u64 v[26:27], v[24:25], 0, s[98:99]
	v_readlane_b32 s86, v241, 24
	s_nop 0
	v_add_co_u32_e32 v28, vcc, 0xc000, v24
	global_load_dword v20, v[16:17], off
	global_load_dword v21, v[16:17], off offset:512
	global_load_dword v22, v[16:17], off offset:1024
	global_load_dword v23, v[16:17], off offset:1536
	s_nop 0
	global_load_dword v16, v[26:27], off
	global_load_dword v17, v[26:27], off offset:512
	global_load_dword v18, v[26:27], off offset:1024
	global_load_dword v19, v[26:27], off offset:1536
	v_addc_co_u32_e32 v29, vcc, 0, v25, vcc
	v_add_co_u32_e32 v36, vcc, 0xe000, v24
	v_readlane_b32 s87, v241, 25
	s_nop 0
	v_addc_co_u32_e32 v37, vcc, 0, v25, vcc
	global_load_dword v24, v[28:29], off
	global_load_dword v25, v[28:29], off offset:512
	global_load_dword v26, v[28:29], off offset:1024
	global_load_dword v27, v[28:29], off offset:1536
	s_nop 0
	global_load_dword v28, v[36:37], off
	global_load_dword v29, v[36:37], off offset:512
	global_load_dword v30, v[36:37], off offset:1024
	global_load_dword v31, v[36:37], off offset:1536
	v_readlane_b32 s88, v241, 26
	v_readlane_b32 s89, v241, 27
	v_readlane_b32 s92, v241, 30
	v_readlane_b32 s93, v241, 31
	v_readlane_b32 s94, v241, 32
	v_readlane_b32 s95, v241, 33
	v_readlane_b32 s80, v241, 37
	v_readlane_b32 s92, v241, 49
	v_readlane_b32 s93, v241, 50
	v_readlane_b32 s94, v241, 51
	v_readlane_b32 s95, v241, 52
	v_readlane_b32 s81, v241, 38
	v_readlane_b32 s82, v241, 39
	v_readlane_b32 s83, v241, 40
	v_readlane_b32 s84, v241, 41
	v_readlane_b32 s85, v241, 42
	v_readlane_b32 s86, v241, 43
	v_readlane_b32 s87, v241, 44
	v_readlane_b32 s88, v241, 45
	v_readlane_b32 s89, v241, 46
	v_readlane_b32 s90, v241, 47
	v_readlane_b32 s91, v241, 48
.LBB0_1475:
	s_or_b64 exec, exec, s[58:59]
	v_ashrrev_i32_e32 v33, 31, v32
	v_lshlrev_b64 v[36:37], 11, v[32:33]
	s_mov_b64 s[58:59], 0x2000
	v_lshl_add_u64 v[36:37], v[36:37], 0, s[58:59]
	v_lshlrev_b64 v[32:33], 8, v[32:33]
	v_cndmask_b32_e64 v33, v37, v33, s[38:39]
	v_cndmask_b32_e64 v32, v36, v32, s[38:39]
	v_lshlrev_b64 v[32:33], 11, v[32:33]
	v_lshl_add_u64 v[36:37], s[68:69], 0, v[32:33]
	v_lshlrev_b32_e32 v64, 8, v34
	v_lshl_add_u64 v[38:39], s[48:49], 0, v[32:33]
	v_lshl_add_u64 v[34:35], v[36:37], 0, v[64:65]
	v_lshl_add_u64 v[36:37], s[46:47], 0, v[32:33]
	v_lshl_add_u64 v[38:39], v[38:39], 0, v[64:65]
	v_lshlrev_b64 v[40:41], 1, v[80:81]
	v_lshl_add_u64 v[36:37], v[36:37], 0, v[64:65]
	v_lshl_add_u64 v[38:39], v[38:39], 0, v[40:41]
	s_waitcnt vmcnt(0)
	v_mov_b32_e32 v69, v65
	v_mov_b32_e32 v71, v65
	v_lshl_add_u64 v[34:35], v[34:35], 0, v[68:69]
	v_lshl_add_u64 v[36:37], v[36:37], 0, v[68:69]
	v_lshl_add_u64 v[38:39], v[38:39], 0, v[70:71]
	v_mov_b64_e32 v[42:43], v[34:35]
	v_mov_b64_e32 v[44:45], v[38:39]
	v_mov_b64_e32 v[46:47], v[36:37]
	global_load_dword v69, v[42:43], off
	global_load_dword v71, v[42:43], off offset:2048
	global_load_dword v75, v[46:47], off
	global_load_dword v77, v[46:47], off offset:2048
	s_mov_b32 s98, s67
	s_mov_b32 s99, 0
	v_lshl_add_u64 v[48:49], v[42:43], 0, s[98:99]
	v_lshl_add_u64 v[32:33], s[50:51], 0, v[32:33]
	s_mov_b32 s98, s67
	s_mov_b32 s99, 0
	v_lshl_add_u64 v[50:51], v[46:47], 0, s[98:99]
	v_lshl_add_u64 v[32:33], v[32:33], 0, v[64:65]
	global_load_dword v79, v[48:49], off
	global_load_dword v119, v[48:49], off offset:2048
	global_load_dword v120, v[50:51], off
	global_load_dword v121, v[50:51], off offset:2048
	s_mov_b32 s98, s62
	s_mov_b32 s99, 0
	v_lshl_add_u64 v[48:49], v[42:43], 0, s[98:99]
	v_lshl_add_u64 v[32:33], v[32:33], 0, v[40:41]
	s_mov_b32 s98, s62
	s_mov_b32 s99, 0
	v_lshl_add_u64 v[50:51], v[46:47], 0, s[98:99]
	v_mov_b32_e32 v73, v65
	global_load_dword v122, v[48:49], off
	global_load_dword v123, v[48:49], off offset:2048
	global_load_dword v124, v[50:51], off
	global_load_dword v125, v[50:51], off offset:2048
	s_mov_b32 s98, s72
	s_mov_b32 s99, 0
	v_lshl_add_u64 v[48:49], v[42:43], 0, s[98:99]
	v_cndmask_b32_e64 v132, 32, 4, s[38:39]
	s_mov_b32 s98, s72
	s_mov_b32 s99, 0
	v_lshl_add_u64 v[50:51], v[46:47], 0, s[98:99]
	s_mov_b32 s75, 0
	global_load_dword v126, v[48:49], off
	global_load_dword v127, v[48:49], off offset:2048
	global_load_dword v128, v[50:51], off
	global_load_dword v129, v[50:51], off offset:2048
	s_mov_b32 s98, s63
	s_mov_b32 s99, 0
	v_lshl_add_u64 v[48:49], v[42:43], 0, s[98:99]
	v_lshl_add_u64 v[84:85], v[32:33], 0, v[72:73]
	s_mov_b32 s98, s63
	s_mov_b32 s99, 0
	v_lshl_add_u64 v[50:51], v[46:47], 0, s[98:99]
	v_lshl_add_u64 v[86:87], v[38:39], 0, s[56:57]
	global_load_dword v130, v[48:49], off
	global_load_dword v131, v[48:49], off offset:2048
	global_load_dword v133, v[50:51], off
	global_load_dword v134, v[50:51], off offset:2048
	s_mov_b32 s98, s73
	s_mov_b32 s99, 0
	v_lshl_add_u64 v[48:49], v[42:43], 0, s[98:99]
	v_lshl_add_u64 v[88:89], v[36:37], 0, s[56:57]
	s_mov_b32 s98, s73
	s_mov_b32 s99, 0
	v_lshl_add_u64 v[50:51], v[46:47], 0, s[98:99]
	v_lshl_add_u64 v[90:91], v[34:35], 0, s[56:57]
	global_load_dword v135, v[48:49], off
	global_load_dword v136, v[48:49], off offset:2048
	global_load_dword v137, v[50:51], off
	global_load_dword v138, v[50:51], off offset:2048
	s_mov_b32 s98, s64
	s_mov_b32 s99, 0
	v_lshl_add_u64 v[48:49], v[42:43], 0, s[98:99]
	s_mov_b64 s[58:59], 0
	s_mov_b32 s98, s64
	s_mov_b32 s99, 0
	v_lshl_add_u64 v[50:51], v[46:47], 0, s[98:99]
	v_mov_b32_e32 v64, v106
	s_mov_b32 s98, s74
	s_mov_b32 s99, 0
	v_lshl_add_u64 v[42:43], v[42:43], 0, s[98:99]
	global_load_dword v139, v[48:49], off
	global_load_dword v140, v[48:49], off offset:2048
	global_load_dword v141, v[50:51], off
	global_load_dword v142, v[50:51], off offset:2048
	s_mov_b32 s98, s74
	s_mov_b32 s99, 0
	v_lshl_add_u64 v[46:47], v[46:47], 0, s[98:99]
	global_load_dword v143, v[42:43], off
	global_load_dword v144, v[42:43], off offset:2048
	global_load_dword v145, v[46:47], off
	global_load_dword v146, v[46:47], off offset:2048
	global_load_dword v147, v[44:45], off
	global_load_dword v148, v[44:45], off offset:2048
	s_mov_b32 s98, s67
	s_mov_b32 s99, 0
	v_lshl_add_u64 v[42:43], v[44:45], 0, s[98:99]
	s_mov_b32 s98, s62
	s_mov_b32 s99, 0
	v_lshl_add_u64 v[46:47], v[44:45], 0, s[98:99]
	v_add_co_u32_e32 v44, vcc, 0x3000, v44
	s_nop 1
	v_addc_co_u32_e32 v45, vcc, 0, v45, vcc
	global_load_dword v149, v[42:43], off
	global_load_dword v150, v[42:43], off offset:2048
	global_load_dword v151, v[46:47], off
	global_load_dword v152, v[46:47], off offset:2048
	global_load_dword v153, v[44:45], off
	global_load_dword v154, v[44:45], off offset:2048
	s_waitcnt vmcnt(0)
	s_branch .LBB0_1477

.LBB0_1479:
	s_or_b64 exec, exec, s[60:61]
	v_lshlrev_b32_e32 v32, 16, v150
	v_lshlrev_b32_e32 v34, 16, v148
	v_lshlrev_b32_e32 v158, 16, v154
	v_lshlrev_b32_e32 v160, 16, v152
	v_or_b32_sdwa v157, v149, v32 dst_sel:DWORD dst_unused:UNUSED_PAD src0_sel:WORD_0 src1_sel:DWORD
	v_or_b32_sdwa v156, v147, v34 dst_sel:DWORD dst_unused:UNUSED_PAD src0_sel:WORD_0 src1_sel:DWORD
	v_or_b32_sdwa v159, v153, v158 dst_sel:DWORD dst_unused:UNUSED_PAD src0_sel:WORD_0 src1_sel:DWORD
	v_or_b32_sdwa v158, v151, v160 dst_sel:DWORD dst_unused:UNUSED_PAD src0_sel:WORD_0 src1_sel:DWORD
	v_and_b32_e32 v32, 0xffff0000, v150
	v_and_b32_e32 v34, 0xffff0000, v148
	ds_write_b128 v112, v[156:159] offset:35840
	v_or_b32_sdwa v157, v149, v32 dst_sel:DWORD dst_unused:UNUSED_PAD src0_sel:WORD_1 src1_sel:DWORD
	v_or_b32_sdwa v156, v147, v34 dst_sel:DWORD dst_unused:UNUSED_PAD src0_sel:WORD_1 src1_sel:DWORD
	v_and_b32_e32 v32, 0xffff0000, v154
	v_and_b32_e32 v34, 0xffff0000, v152
	s_add_i32 s75, s75, 1
	v_or_b32_sdwa v159, v153, v32 dst_sel:DWORD dst_unused:UNUSED_PAD src0_sel:WORD_1 src1_sel:DWORD
	v_or_b32_sdwa v158, v151, v34 dst_sel:DWORD dst_unused:UNUSED_PAD src0_sel:WORD_1 src1_sel:DWORD
	v_cmp_lt_u32_e32 vcc, s75, v132
	ds_write_b128 v112, v[156:159] offset:35984
	s_and_saveexec_b64 s[60:61], vcc
	s_cbranch_execz .LBB0_1476
	v_mov_b64_e32 v[144:145], v[90:91]
	v_mov_b64_e32 v[150:151], v[86:87]
	v_mov_b64_e32 v[146:147], v[88:89]
	global_load_dword v69, v[144:145], off
	global_load_dword v71, v[144:145], off offset:2048
	global_load_dword v75, v[146:147], off
	global_load_dword v77, v[146:147], off offset:2048
	s_mov_b64 s[98:99], 0x1000
	v_lshl_add_u64 v[120:121], v[144:145], 0, s[98:99]
	s_mov_b64 s[98:99], 0x1000
	v_lshl_add_u64 v[122:123], v[146:147], 0, s[98:99]
	s_mov_b32 s98, s62
	s_mov_b32 s99, 0
	v_lshl_add_u64 v[124:125], v[144:145], 0, s[98:99]
	global_load_dword v79, v[120:121], off
	global_load_dword v119, v[120:121], off offset:2048
	global_load_dword v120, v[122:123], off
	global_load_dword v121, v[122:123], off offset:2048
	s_mov_b32 s98, s62
	s_mov_b32 s99, 0
	v_lshl_add_u64 v[126:127], v[146:147], 0, s[98:99]
	s_mov_b32 s98, s72
	s_mov_b32 s99, 0
	v_lshl_add_u64 v[128:129], v[144:145], 0, s[98:99]
	global_load_dword v122, v[124:125], off
	global_load_dword v123, v[124:125], off offset:2048
	global_load_dword v124, v[126:127], off
	global_load_dword v125, v[126:127], off offset:2048
	s_mov_b32 s98, s72
	s_mov_b32 s99, 0
	v_lshl_add_u64 v[130:131], v[146:147], 0, s[98:99]
	s_mov_b32 s98, s63
	s_mov_b32 s99, 0
	v_lshl_add_u64 v[134:135], v[144:145], 0, s[98:99]
	global_load_dword v126, v[128:129], off
	global_load_dword v127, v[128:129], off offset:2048
	global_load_dword v128, v[130:131], off
	global_load_dword v129, v[130:131], off offset:2048
	s_mov_b32 s98, s63
	s_mov_b32 s99, 0
	v_lshl_add_u64 v[136:137], v[146:147], 0, s[98:99]
	global_load_dword v130, v[134:135], off
	global_load_dword v131, v[134:135], off offset:2048
	global_load_dword v133, v[136:137], off
	s_nop 0
	global_load_dword v134, v[136:137], off offset:2048
	s_mov_b32 s98, s73
	s_mov_b32 s99, 0
	v_lshl_add_u64 v[136:137], v[144:145], 0, s[98:99]
	s_mov_b32 s98, s73
	s_mov_b32 s99, 0
	v_lshl_add_u64 v[138:139], v[146:147], 0, s[98:99]
	s_mov_b32 s98, s64
	s_mov_b32 s99, 0
	v_lshl_add_u64 v[140:141], v[144:145], 0, s[98:99]
	global_load_dword v135, v[136:137], off
	global_load_dword v136, v[136:137], off offset:2048
	global_load_dword v137, v[138:139], off
	global_load_dword v138, v[138:139], off offset:2048
	s_mov_b32 s98, s64
	s_mov_b32 s99, 0
	v_lshl_add_u64 v[142:143], v[146:147], 0, s[98:99]
	s_mov_b64 s[98:99], 0x7000
	v_lshl_add_u64 v[144:145], v[144:145], 0, s[98:99]
	global_load_dword v139, v[140:141], off
	global_load_dword v140, v[140:141], off offset:2048
	global_load_dword v141, v[142:143], off
	global_load_dword v142, v[142:143], off offset:2048
	s_mov_b64 s[98:99], 0x7000
	v_lshl_add_u64 v[146:147], v[146:147], 0, s[98:99]
	v_add_co_u32_e32 v152, vcc, 0x1000, v150
	global_load_dword v143, v[144:145], off
	s_nop 0
	global_load_dword v144, v[144:145], off offset:2048
	s_nop 0
	global_load_dword v145, v[146:147], off
	s_nop 0
	global_load_dword v146, v[146:147], off offset:2048
	s_nop 0
	global_load_dword v147, v[150:151], off
	global_load_dword v148, v[150:151], off offset:2048
	v_addc_co_u32_e32 v153, vcc, 0, v151, vcc
	s_mov_b64 s[98:99], 0x2000
	v_lshl_add_u64 v[156:157], v[150:151], 0, s[98:99]
	v_add_co_u32_e32 v158, vcc, 0x3000, v150
	s_nop 1
	v_addc_co_u32_e32 v159, vcc, 0, v151, vcc
	global_load_dword v149, v[152:153], off
	global_load_dword v150, v[152:153], off offset:2048
	global_load_dword v151, v[156:157], off
	s_nop 0
	global_load_dword v152, v[156:157], off offset:2048
	global_load_dword v153, v[158:159], off
	global_load_dword v154, v[158:159], off offset:2048
	s_branch .LBB0_1476
.LBB0_1481:
	s_or_b64 exec, exec, s[58:59]
	s_and_saveexec_b64 s[58:59], s[38:39]
	s_cbranch_execz .LBB0_1472
	v_lshlrev_b64 v[32:33], 16, v[82:83]
	v_lshl_add_u64 v[32:33], s[52:53], 0, v[32:33]
	v_lshl_add_u64 v[32:33], v[80:81], 2, v[32:33]
	s_waitcnt vmcnt(0)
	v_mov_b32_e32 v75, v65
	v_lshl_add_u64 v[32:33], v[32:33], 0, v[74:75]
	v_mov_b32_e32 v77, v65
	v_lshl_add_u64 v[32:33], v[32:33], 0, v[76:77]
	v_mov_b32_e32 v79, v65
	v_lshl_add_u64 v[32:33], v[32:33], 0, v[78:79]
	global_store_dword v[32:33], v12, off
	global_store_dword v[32:33], v13, off offset:512
	global_store_dword v[32:33], v14, off offset:1024
	global_store_dword v[32:33], v15, off offset:1536
	s_mov_b32 s98, s62
	s_mov_b32 s99, 0
	v_lshl_add_u64 v[12:13], v[32:33], 0, s[98:99]
	global_store_dword v[12:13], v0, off
	global_store_dword v[12:13], v1, off offset:512
	global_store_dword v[12:13], v2, off offset:1024
	global_store_dword v[12:13], v3, off offset:1536
	s_mov_b32 s98, s63
	s_mov_b32 s99, 0
	v_lshl_add_u64 v[0:1], v[32:33], 0, s[98:99]
	global_store_dword v[0:1], v8, off
	global_store_dword v[0:1], v9, off offset:512
	global_store_dword v[0:1], v10, off offset:1024
	global_store_dword v[0:1], v11, off offset:1536
	s_mov_b32 s98, s64
	s_mov_b32 s99, 0
	v_lshl_add_u64 v[0:1], v[32:33], 0, s[98:99]
	global_store_dword v[0:1], v4, off
	global_store_dword v[0:1], v5, off offset:512
	global_store_dword v[0:1], v6, off offset:1024
	global_store_dword v[0:1], v7, off offset:1536
	s_mov_b32 s98, s65
	s_mov_b32 s99, 0
	v_lshl_add_u64 v[0:1], v[32:33], 0, s[98:99]
	global_store_dword v[0:1], v20, off
	global_store_dword v[0:1], v21, off offset:512
	global_store_dword v[0:1], v22, off offset:1024
	global_store_dword v[0:1], v23, off offset:1536
	s_mov_b32 s98, s66
	s_mov_b32 s99, 0
	v_lshl_add_u64 v[0:1], v[32:33], 0, s[98:99]
	global_store_dword v[0:1], v16, off
	global_store_dword v[0:1], v17, off offset:512
	global_store_dword v[0:1], v18, off offset:1024
	global_store_dword v[0:1], v19, off offset:1536
	s_mov_b64 s[98:99], 0xc000
	v_lshl_add_u64 v[0:1], v[32:33], 0, s[98:99]
	global_store_dword v[0:1], v24, off
	global_store_dword v[0:1], v25, off offset:512
	global_store_dword v[0:1], v26, off offset:1024
	global_store_dword v[0:1], v27, off offset:1536
	v_add_co_u32_e32 v0, vcc, 0xe000, v32
	s_nop 1
	v_addc_co_u32_e32 v1, vcc, 0, v33, vcc
	global_store_dword v[0:1], v28, off
	global_store_dword v[0:1], v29, off offset:512
	global_store_dword v[0:1], v30, off offset:1024
	global_store_dword v[0:1], v31, off offset:1536
	s_branch .LBB0_1472

.LBB0_1490:
	v_add_u32_e32 v0, s56, v100
	s_movk_i32 s42, 0x7f
	v_add_u32_e32 v1, 0xffffff80, v0
	v_cmp_lt_i32_e64 s[42:43], s42, v0
	v_cmp_gt_i32_e32 vcc, s33, v0
	v_mov_b32_e32 v3, 0
	v_cndmask_b32_e64 v0, v0, v1, s[42:43]
	v_lshrrev_b32_e32 v1, 31, v0
	v_add_u32_e32 v1, v0, v1
	v_and_b32_e32 v2, 0x3fffffe, v1
	v_bfe_u32 v34, v1, 1, 3
	v_ashrrev_i32_e32 v1, 31, v0
	v_lshrrev_b32_e32 v1, 28, v1
	v_sub_u32_e32 v2, v0, v2
	v_add_u32_e32 v0, v0, v1
	v_ashrrev_i32_e32 v32, 4, v0
	v_lshlrev_b32_e32 v58, 6, v2
	v_lshlrev_b32_e32 v1, 4, v32
	v_ashrrev_i32_e32 v59, 31, v58
	v_mov_b32_e32 v0, 0
	v_or3_b32 v60, v1, v34, 8
	v_mov_b32_e32 v1, 0
	v_mov_b32_e32 v2, 0
	v_mov_b32_e32 v4, 0
	v_mov_b32_e32 v5, 0
	v_mov_b32_e32 v6, 0
	v_mov_b32_e32 v7, 0
	v_mov_b32_e32 v12, 0
	v_mov_b32_e32 v13, 0
	v_mov_b32_e32 v14, 0
	v_mov_b32_e32 v15, 0
	v_mov_b32_e32 v8, 0
	v_mov_b32_e32 v9, 0
	v_mov_b32_e32 v10, 0
	v_mov_b32_e32 v11, 0
	v_mov_b32_e32 v20, 0
	v_mov_b32_e32 v21, 0
	v_mov_b32_e32 v22, 0
	v_mov_b32_e32 v23, 0
	v_mov_b32_e32 v16, 0
	v_mov_b32_e32 v17, 0
	v_mov_b32_e32 v18, 0
	v_mov_b32_e32 v19, 0
	v_mov_b32_e32 v28, 0
	v_mov_b32_e32 v29, 0
	v_mov_b32_e32 v30, 0
	v_mov_b32_e32 v31, 0
	v_mov_b32_e32 v24, 0
	v_mov_b32_e32 v25, 0
	v_mov_b32_e32 v26, 0
	v_mov_b32_e32 v27, 0
	s_and_saveexec_b64 s[52:53], vcc
	s_cbranch_execz .LBB0_1492
	v_ashrrev_i32_e32 v61, 31, v60
	v_readlane_b32 s80, v241, 18
	v_lshlrev_b64 v[0:1], 16, v[60:61]
	v_readlane_b32 s90, v241, 28
	v_readlane_b32 s91, v241, 29
	s_waitcnt vmcnt(0)
	v_mov_b32_e32 v67, v57
	v_mov_b32_e32 v69, v57
	v_lshl_add_u64 v[0:1], s[90:91], 0, v[0:1]
	v_lshl_add_u64 v[0:1], v[58:59], 2, v[0:1]
	v_lshl_add_u64 v[0:1], v[0:1], 0, v[66:67]
	v_lshl_add_u64 v[0:1], v[0:1], 0, v[68:69]
	v_lshlrev_b32_e32 v56, 2, v122
	v_lshl_add_u64 v[24:25], v[0:1], 0, v[56:57]
	v_readlane_b32 s81, v241, 19
	s_mov_b32 s98, s57
	s_mov_b32 s99, 0
	v_lshl_add_u64 v[8:9], v[24:25], 0, s[98:99]
	v_readlane_b32 s82, v241, 20
	s_nop 0
	global_load_dword v0, v[24:25], off
	global_load_dword v1, v[24:25], off offset:512
	global_load_dword v2, v[24:25], off offset:1024
	global_load_dword v3, v[24:25], off offset:1536
	global_load_dword v4, v[8:9], off
	global_load_dword v5, v[8:9], off offset:512
	global_load_dword v6, v[8:9], off offset:1024
	global_load_dword v7, v[8:9], off offset:1536
	s_mov_b32 s98, s58
	s_mov_b32 s99, 0
	v_lshl_add_u64 v[8:9], v[24:25], 0, s[98:99]
	v_readlane_b32 s83, v241, 21
	s_nop 0
	s_mov_b32 s98, s59
	s_mov_b32 s99, 0
	v_lshl_add_u64 v[16:17], v[24:25], 0, s[98:99]
	v_readlane_b32 s84, v241, 22
	s_nop 0
	global_load_dword v12, v[8:9], off
	global_load_dword v13, v[8:9], off offset:512
	global_load_dword v14, v[8:9], off offset:1024
	global_load_dword v15, v[8:9], off offset:1536
	s_nop 0
	global_load_dword v8, v[16:17], off
	global_load_dword v9, v[16:17], off offset:512
	global_load_dword v10, v[16:17], off offset:1024
	global_load_dword v11, v[16:17], off offset:1536
	s_mov_b32 s98, s60
	s_mov_b32 s99, 0
	v_lshl_add_u64 v[16:17], v[24:25], 0, s[98:99]
	v_readlane_b32 s85, v241, 23
	s_nop 0
	s_mov_b32 s98, s61
	s_mov_b32 s99, 0
	v_lshl_add_u64 v[26:27], v[24:25], 0, s[98:99]
	v_readlane_b32 s86, v241, 24
	s_nop 0
	global_load_dword v20, v[16:17], off
	global_load_dword v21, v[16:17], off offset:512
	global_load_dword v22, v[16:17], off offset:1024
	global_load_dword v23, v[16:17], off offset:1536
	s_nop 0
	global_load_dword v16, v[26:27], off
	global_load_dword v17, v[26:27], off offset:512
	global_load_dword v18, v[26:27], off offset:1024
	global_load_dword v19, v[26:27], off offset:1536
	s_mov_b64 s[98:99], 0xc000
	v_lshl_add_u64 v[26:27], v[24:25], 0, s[98:99]
	v_readlane_b32 s87, v241, 25
	s_nop 0
	v_add_co_u32_e32 v36, vcc, 0xe000, v24
	v_readlane_b32 s88, v241, 26
	s_nop 0
	v_addc_co_u32_e32 v37, vcc, 0, v25, vcc
	global_load_dword v28, v[26:27], off
	global_load_dword v29, v[26:27], off offset:512
	global_load_dword v30, v[26:27], off offset:1024
	global_load_dword v31, v[26:27], off offset:1536
	global_load_dword v24, v[36:37], off
	global_load_dword v25, v[36:37], off offset:512
	s_nop 0
	global_load_dword v26, v[36:37], off offset:1024
	global_load_dword v27, v[36:37], off offset:1536
	v_readlane_b32 s89, v241, 27
	v_readlane_b32 s92, v241, 30
	v_readlane_b32 s93, v241, 31
	v_readlane_b32 s94, v241, 32
	v_readlane_b32 s95, v241, 33
	v_readlane_b32 s80, v241, 37
	v_readlane_b32 s92, v241, 49
	v_readlane_b32 s93, v241, 50
	v_readlane_b32 s94, v241, 51
	v_readlane_b32 s95, v241, 52
	v_readlane_b32 s81, v241, 38
	v_readlane_b32 s82, v241, 39
	v_readlane_b32 s83, v241, 40
	v_readlane_b32 s84, v241, 41
	v_readlane_b32 s85, v241, 42
	v_readlane_b32 s86, v241, 43
	v_readlane_b32 s87, v241, 44
	v_readlane_b32 s88, v241, 45
	v_readlane_b32 s89, v241, 46
	v_readlane_b32 s90, v241, 47
	v_readlane_b32 s91, v241, 48
.LBB0_1492:
	s_or_b64 exec, exec, s[52:53]
	v_ashrrev_i32_e32 v33, 31, v32
	v_lshlrev_b64 v[36:37], 11, v[32:33]
	s_mov_b64 s[52:53], 0x2000
	v_lshl_add_u64 v[36:37], v[36:37], 0, s[52:53]
	v_lshlrev_b64 v[32:33], 8, v[32:33]
	v_cndmask_b32_e64 v33, v37, v33, s[42:43]
	v_cndmask_b32_e64 v32, v36, v32, s[42:43]
	v_lshlrev_b64 v[36:37], 11, v[32:33]
	v_cndmask_b32_e64 v61, 32, 4, s[42:43]
	v_lshl_add_u64 v[38:39], s[68:69], 0, v[36:37]
	v_lshlrev_b32_e32 v56, 8, v34
	v_lshl_add_u64 v[40:41], s[44:45], 0, v[36:37]
	v_lshl_add_u64 v[36:37], s[46:47], 0, v[36:37]
	v_lshl_add_u64 v[38:39], v[38:39], 0, v[56:57]
	v_lshl_add_u64 v[40:41], v[40:41], 0, v[56:57]
	v_lshl_add_u64 v[36:37], v[36:37], 0, v[56:57]
	v_add_u32_e32 v56, -1, v61
	v_lshl_add_u64 v[36:37], v[58:59], 1, v[36:37]
	v_lshlrev_b64 v[42:43], 17, v[56:57]
	v_lshl_add_u64 v[44:45], v[38:39], 0, v[42:43]
	v_lshlrev_b32_e32 v56, 2, v102
	v_lshl_add_u64 v[46:47], v[40:41], 0, v[42:43]
	v_lshl_add_u64 v[42:43], v[36:37], 0, v[42:43]
	v_mov_b32_e32 v65, v57
	v_lshl_add_u64 v[44:45], v[44:45], 0, v[56:57]
	v_lshl_add_u64 v[46:47], v[46:47], 0, v[56:57]
	v_lshl_add_u64 v[42:43], v[42:43], 0, v[64:65]
	s_waitcnt vmcnt(0)
	global_load_dword v67, v[44:45], off
	global_load_dword v69, v[44:45], off offset:2048
	global_load_dword v75, v[46:47], off
	global_load_dword v150, v[46:47], off offset:2048
	s_mov_b32 s98, s62
	s_mov_b32 s99, 0
	v_lshl_add_u64 v[48:49], v[44:45], 0, s[98:99]
	v_lshlrev_b32_e32 v33, 6, v61
	s_mov_b32 s98, s62
	s_mov_b32 s99, 0
	v_lshl_add_u64 v[50:51], v[46:47], 0, s[98:99]
	v_lshlrev_b32_e32 v34, 7, v34
	global_load_dword v151, v[48:49], off
	global_load_dword v152, v[48:49], off offset:2048
	global_load_dword v153, v[50:51], off
	global_load_dword v154, v[50:51], off offset:2048
	s_mov_b32 s98, s57
	s_mov_b32 s99, 0
	v_lshl_add_u64 v[48:49], v[44:45], 0, s[98:99]
	v_lshl_add_u64 v[72:73], v[36:37], 0, v[64:65]
	s_mov_b32 s98, s57
	s_mov_b32 s99, 0
	v_lshl_add_u64 v[50:51], v[46:47], 0, s[98:99]
	v_add3_u32 v65, v142, v33, v32
	global_load_dword v155, v[48:49], off
	global_load_dword v156, v[48:49], off offset:2048
	global_load_dword v157, v[50:51], off
	global_load_dword v158, v[50:51], off offset:2048
	s_mov_b32 s98, s63
	s_mov_b32 s99, 0
	v_lshl_add_u64 v[48:49], v[44:45], 0, s[98:99]
	s_mov_b32 s66, 1
	s_mov_b32 s98, s63
	s_mov_b32 s99, 0
	v_lshl_add_u64 v[50:51], v[46:47], 0, s[98:99]
	v_lshl_add_u64 v[62:63], v[38:39], 0, v[56:57]
	global_load_dword v159, v[48:49], off
	global_load_dword v160, v[48:49], off offset:2048
	global_load_dword v161, v[50:51], off
	global_load_dword v162, v[50:51], off offset:2048
	s_mov_b32 s98, s58
	s_mov_b32 s99, 0
	v_lshl_add_u64 v[48:49], v[44:45], 0, s[98:99]
	v_lshl_add_u64 v[70:71], v[40:41], 0, v[56:57]
	s_mov_b32 s98, s58
	s_mov_b32 s99, 0
	v_lshl_add_u64 v[50:51], v[46:47], 0, s[98:99]
	v_add_u32_e32 v74, -2, v61
	global_load_dword v163, v[48:49], off
	global_load_dword v165, v[48:49], off offset:2048
	global_load_dword v166, v[50:51], off
	global_load_dword v167, v[50:51], off offset:2048
	s_mov_b32 s98, s64
	s_mov_b32 s99, 0
	v_lshl_add_u64 v[48:49], v[44:45], 0, s[98:99]
	v_lshlrev_b32_e32 v164, 10, v65
	s_mov_b32 s98, s64
	s_mov_b32 s99, 0
	v_lshl_add_u64 v[50:51], v[46:47], 0, s[98:99]
	s_mov_b64 s[52:53], 0
	global_load_dword v168, v[48:49], off
	global_load_dword v169, v[48:49], off offset:2048
	global_load_dword v170, v[50:51], off
	global_load_dword v171, v[50:51], off offset:2048
	s_mov_b32 s98, s59
	s_mov_b32 s99, 0
	v_lshl_add_u64 v[48:49], v[44:45], 0, s[98:99]
	v_lshlrev_b32_e32 v76, 1, v34
	s_mov_b32 s98, s59
	s_mov_b32 s99, 0
	v_lshl_add_u64 v[50:51], v[46:47], 0, s[98:99]
	s_mov_b32 s98, s65
	s_mov_b32 s99, 0
	v_lshl_add_u64 v[44:45], v[44:45], 0, s[98:99]
	global_load_dword v172, v[48:49], off
	global_load_dword v173, v[48:49], off offset:2048
	global_load_dword v174, v[50:51], off
	global_load_dword v175, v[50:51], off offset:2048
	s_mov_b32 s98, s65
	s_mov_b32 s99, 0
	v_lshl_add_u64 v[46:47], v[46:47], 0, s[98:99]
	global_load_dword v176, v[44:45], off
	global_load_dword v177, v[44:45], off offset:2048
	global_load_dword v187, v[46:47], off
	global_load_dword v188, v[46:47], off offset:2048
	global_load_dword v189, v[42:43], off
	global_load_dword v190, v[42:43], off offset:2048
	s_mov_b32 s98, s62
	s_mov_b32 s99, 0
	v_lshl_add_u64 v[44:45], v[42:43], 0, s[98:99]
	s_mov_b32 s98, s57
	s_mov_b32 s99, 0
	v_lshl_add_u64 v[46:47], v[42:43], 0, s[98:99]
	v_add_co_u32_e32 v42, vcc, 0x3000, v42
	s_nop 1
	v_addc_co_u32_e32 v43, vcc, 0, v43, vcc
	global_load_dword v191, v[44:45], off
	global_load_dword v192, v[44:45], off offset:2048
	global_load_dword v193, v[46:47], off
	global_load_dword v194, v[46:47], off offset:2048
	global_load_dword v195, v[42:43], off
	global_load_dword v196, v[42:43], off offset:2048
	s_waitcnt vmcnt(0)
	s_branch .LBB0_1494

.LBB0_1496:
	s_or_b64 exec, exec, s[54:55]
	v_lshlrev_b32_e32 v34, 16, v192
	v_lshlrev_b32_e32 v38, 16, v190
	v_lshlrev_b32_e32 v48, 16, v196
	v_lshlrev_b32_e32 v50, 16, v194
	v_or_b32_sdwa v47, v191, v34 dst_sel:DWORD dst_unused:UNUSED_PAD src0_sel:WORD_0 src1_sel:DWORD
	v_or_b32_sdwa v46, v189, v38 dst_sel:DWORD dst_unused:UNUSED_PAD src0_sel:WORD_0 src1_sel:DWORD
	v_add_u32_e32 v34, v108, v109
	v_or_b32_sdwa v49, v195, v48 dst_sel:DWORD dst_unused:UNUSED_PAD src0_sel:WORD_0 src1_sel:DWORD
	v_or_b32_sdwa v48, v193, v50 dst_sel:DWORD dst_unused:UNUSED_PAD src0_sel:WORD_0 src1_sel:DWORD
	v_and_b32_e32 v38, 0xffff0000, v192
	ds_write_b128 v34, v[46:49] offset:35840
	v_and_b32_e32 v46, 0xffff0000, v190
	v_or_b32_sdwa v47, v191, v38 dst_sel:DWORD dst_unused:UNUSED_PAD src0_sel:WORD_1 src1_sel:DWORD
	v_and_b32_e32 v38, 0xffff0000, v196
	v_and_b32_e32 v48, 0xffff0000, v194
	v_or_b32_sdwa v46, v189, v46 dst_sel:DWORD dst_unused:UNUSED_PAD src0_sel:WORD_1 src1_sel:DWORD
	v_or_b32_sdwa v49, v195, v38 dst_sel:DWORD dst_unused:UNUSED_PAD src0_sel:WORD_1 src1_sel:DWORD
	v_or_b32_sdwa v48, v193, v48 dst_sel:DWORD dst_unused:UNUSED_PAD src0_sel:WORD_1 src1_sel:DWORD
	v_cmp_lt_u32_e32 vcc, s66, v61
	ds_write_b128 v34, v[46:49] offset:35984
	s_and_saveexec_b64 s[54:55], vcc
	s_cbranch_execz .LBB0_1493
	v_ashrrev_i32_e32 v75, 31, v74
	v_lshlrev_b64 v[46:47], 17, v[74:75]
	v_lshl_add_u64 v[48:49], v[62:63], 0, v[46:47]
	v_lshl_add_u64 v[50:51], v[70:71], 0, v[46:47]
	v_lshl_add_u64 v[46:47], v[72:73], 0, v[46:47]
	global_load_dword v67, v[48:49], off
	global_load_dword v69, v[48:49], off offset:2048
	global_load_dword v75, v[50:51], off
	global_load_dword v150, v[50:51], off offset:2048
	s_mov_b64 s[98:99], 0x1000
	v_lshl_add_u64 v[54:55], v[48:49], 0, s[98:99]
	s_mov_b64 s[98:99], 0x1000
	v_lshl_add_u64 v[154:155], v[50:51], 0, s[98:99]
	global_load_dword v151, v[54:55], off
	global_load_dword v152, v[54:55], off offset:2048
	global_load_dword v153, v[154:155], off
	s_nop 0
	global_load_dword v154, v[154:155], off offset:2048
	s_mov_b32 s98, s57
	s_mov_b32 s99, 0
	v_lshl_add_u64 v[54:55], v[48:49], 0, s[98:99]
	s_mov_b32 s98, s57
	s_mov_b32 s99, 0
	v_lshl_add_u64 v[158:159], v[50:51], 0, s[98:99]
	global_load_dword v155, v[54:55], off
	global_load_dword v156, v[54:55], off offset:2048
	global_load_dword v157, v[158:159], off
	s_nop 0
	global_load_dword v158, v[158:159], off offset:2048
	s_mov_b32 s98, s63
	s_mov_b32 s99, 0
	v_lshl_add_u64 v[54:55], v[48:49], 0, s[98:99]
	s_mov_b32 s98, s63
	s_mov_b32 s99, 0
	v_lshl_add_u64 v[162:163], v[50:51], 0, s[98:99]
	global_load_dword v159, v[54:55], off
	global_load_dword v160, v[54:55], off offset:2048
	global_load_dword v161, v[162:163], off
	s_nop 0
	global_load_dword v162, v[162:163], off offset:2048
	s_mov_b32 s98, s58
	s_mov_b32 s99, 0
	v_lshl_add_u64 v[54:55], v[48:49], 0, s[98:99]
	s_mov_b32 s98, s58
	s_mov_b32 s99, 0
	v_lshl_add_u64 v[168:169], v[50:51], 0, s[98:99]
	global_load_dword v163, v[54:55], off
	global_load_dword v165, v[54:55], off offset:2048
	global_load_dword v166, v[168:169], off
	global_load_dword v167, v[168:169], off offset:2048
	s_mov_b32 s98, s64
	s_mov_b32 s99, 0
	v_lshl_add_u64 v[54:55], v[48:49], 0, s[98:99]
	s_mov_b32 s98, s64
	s_mov_b32 s99, 0
	v_lshl_add_u64 v[172:173], v[50:51], 0, s[98:99]
	global_load_dword v168, v[54:55], off
	global_load_dword v169, v[54:55], off offset:2048
	global_load_dword v170, v[172:173], off
	global_load_dword v171, v[172:173], off offset:2048
	s_mov_b32 s98, s59
	s_mov_b32 s99, 0
	v_lshl_add_u64 v[54:55], v[48:49], 0, s[98:99]
	s_mov_b32 s98, s59
	s_mov_b32 s99, 0
	v_lshl_add_u64 v[176:177], v[50:51], 0, s[98:99]
	s_mov_b64 s[98:99], 0x7000
	v_lshl_add_u64 v[48:49], v[48:49], 0, s[98:99]
	global_load_dword v172, v[54:55], off
	global_load_dword v173, v[54:55], off offset:2048
	global_load_dword v174, v[176:177], off
	global_load_dword v175, v[176:177], off offset:2048
	s_mov_b64 s[98:99], 0x7000
	v_lshl_add_u64 v[50:51], v[50:51], 0, s[98:99]
	global_load_dword v176, v[48:49], off
	global_load_dword v177, v[48:49], off offset:2048
	global_load_dword v187, v[50:51], off
	global_load_dword v188, v[50:51], off offset:2048
	global_load_dword v189, v[46:47], off
	global_load_dword v190, v[46:47], off offset:2048
	s_mov_b64 s[98:99], 0x1000
	v_lshl_add_u64 v[48:49], v[46:47], 0, s[98:99]
	s_mov_b64 s[98:99], 0x2000
	v_lshl_add_u64 v[50:51], v[46:47], 0, s[98:99]
	v_add_co_u32_e32 v46, vcc, 0x3000, v46
	s_nop 1
	v_addc_co_u32_e32 v47, vcc, 0, v47, vcc
	global_load_dword v191, v[48:49], off
	global_load_dword v192, v[48:49], off offset:2048
	global_load_dword v193, v[50:51], off
	global_load_dword v194, v[50:51], off offset:2048
	global_load_dword v195, v[46:47], off
	global_load_dword v196, v[46:47], off offset:2048
	s_branch .LBB0_1493
.LBB0_1498:
	s_or_b64 exec, exec, s[52:53]
	s_and_saveexec_b64 s[52:53], s[42:43]
	s_cbranch_execz .LBB0_1489
	v_ashrrev_i32_e32 v61, 31, v60
	v_lshlrev_b64 v[32:33], 16, v[60:61]
	v_lshl_add_u64 v[32:33], s[48:49], 0, v[32:33]
	v_lshl_add_u64 v[32:33], v[58:59], 2, v[32:33]
	s_waitcnt vmcnt(0)
	v_mov_b32_e32 v67, v57
	v_lshl_add_u64 v[32:33], v[32:33], 0, v[66:67]
	v_mov_b32_e32 v69, v57
	v_lshl_add_u64 v[32:33], v[32:33], 0, v[68:69]
	v_lshlrev_b32_e32 v56, 2, v122
	v_lshl_add_u64 v[32:33], v[32:33], 0, v[56:57]
	global_store_dword v[32:33], v0, off
	global_store_dword v[32:33], v1, off offset:512
	global_store_dword v[32:33], v2, off offset:1024
	global_store_dword v[32:33], v3, off offset:1536
	s_mov_b32 s98, s57
	s_mov_b32 s99, 0
	v_lshl_add_u64 v[0:1], v[32:33], 0, s[98:99]
	global_store_dword v[0:1], v4, off
	global_store_dword v[0:1], v5, off offset:512
	global_store_dword v[0:1], v6, off offset:1024
	global_store_dword v[0:1], v7, off offset:1536
	s_mov_b32 s98, s58
	s_mov_b32 s99, 0
	v_lshl_add_u64 v[0:1], v[32:33], 0, s[98:99]
	global_store_dword v[0:1], v12, off
	global_store_dword v[0:1], v13, off offset:512
	global_store_dword v[0:1], v14, off offset:1024
	global_store_dword v[0:1], v15, off offset:1536
	s_mov_b32 s98, s59
	s_mov_b32 s99, 0
	v_lshl_add_u64 v[0:1], v[32:33], 0, s[98:99]
	global_store_dword v[0:1], v8, off
	global_store_dword v[0:1], v9, off offset:512
	global_store_dword v[0:1], v10, off offset:1024
	global_store_dword v[0:1], v11, off offset:1536
	s_mov_b32 s98, s60
	s_mov_b32 s99, 0
	v_lshl_add_u64 v[0:1], v[32:33], 0, s[98:99]
	global_store_dword v[0:1], v20, off
	global_store_dword v[0:1], v21, off offset:512
	global_store_dword v[0:1], v22, off offset:1024
	global_store_dword v[0:1], v23, off offset:1536
	s_mov_b32 s98, s61
	s_mov_b32 s99, 0
	v_lshl_add_u64 v[0:1], v[32:33], 0, s[98:99]
	global_store_dword v[0:1], v16, off
	global_store_dword v[0:1], v17, off offset:512
	global_store_dword v[0:1], v18, off offset:1024
	global_store_dword v[0:1], v19, off offset:1536
	s_mov_b64 s[98:99], 0xc000
	v_lshl_add_u64 v[0:1], v[32:33], 0, s[98:99]
	global_store_dword v[0:1], v28, off
	global_store_dword v[0:1], v29, off offset:512
	global_store_dword v[0:1], v30, off offset:1024
	global_store_dword v[0:1], v31, off offset:1536
	v_add_co_u32_e32 v0, vcc, 0xe000, v32
	s_nop 1
	v_addc_co_u32_e32 v1, vcc, 0, v33, vcc
	global_store_dword v[0:1], v24, off
	global_store_dword v[0:1], v25, off offset:512
	global_store_dword v[0:1], v26, off offset:1024
	global_store_dword v[0:1], v27, off offset:1536
	s_branch .LBB0_1489

.LBB0_1503:
	v_add_u32_e32 v0, s60, v100
	s_movk_i32 s40, 0x80
	v_cmp_gt_i32_e32 vcc, s40, v0
	v_add_u32_e32 v1, 0xffffff80, v0
	v_cmp_lt_i32_e64 s[40:41], s33, v0
	v_mov_b32_e32 v12, v71
	v_mov_b32_e32 v13, v71
	v_cndmask_b32_e64 v0, v0, v1, s[40:41]
	v_lshrrev_b32_e32 v1, 31, v0
	v_add_u32_e32 v1, v0, v1
	v_and_b32_e32 v2, 0x3fffffe, v1
	v_bfe_u32 v34, v1, 1, 3
	v_ashrrev_i32_e32 v1, 31, v0
	v_lshrrev_b32_e32 v1, 28, v1
	v_sub_u32_e32 v2, v0, v2
	v_add_u32_e32 v0, v0, v1
	v_ashrrev_i32_e32 v32, 4, v0
	v_lshlrev_b32_e32 v74, 6, v2
	v_lshl_or_b32 v76, v32, 4, v34
	s_waitcnt vmcnt(0)
	v_ashrrev_i32_e32 v75, 31, v74
	v_ashrrev_i32_e32 v77, 31, v76
	v_mov_b32_e32 v14, v71
	v_mov_b32_e32 v15, v71
	v_mov_b32_e32 v0, v71
	v_mov_b32_e32 v1, v71
	v_mov_b32_e32 v2, v71
	v_mov_b32_e32 v3, v71
	v_mov_b32_e32 v8, v71
	v_mov_b32_e32 v9, v71
	v_mov_b32_e32 v10, v71
	v_mov_b32_e32 v11, v71
	v_mov_b32_e32 v4, v71
	v_mov_b32_e32 v5, v71
	v_mov_b32_e32 v6, v71
	v_mov_b32_e32 v7, v71
	v_mov_b32_e32 v20, v71
	v_mov_b32_e32 v21, v71
	v_mov_b32_e32 v22, v71
	v_mov_b32_e32 v23, v71
	v_mov_b32_e32 v16, v71
	v_mov_b32_e32 v17, v71
	v_mov_b32_e32 v18, v71
	v_mov_b32_e32 v19, v71
	v_mov_b32_e32 v24, v71
	v_mov_b32_e32 v25, v71
	v_mov_b32_e32 v26, v71
	v_mov_b32_e32 v27, v71
	v_mov_b32_e32 v28, v71
	v_mov_b32_e32 v29, v71
	v_mov_b32_e32 v30, v71
	v_mov_b32_e32 v31, v71
	s_and_saveexec_b64 s[56:57], vcc
	s_cbranch_execz .LBB0_1505
	v_readlane_b32 s80, v241, 18
	v_lshlrev_b64 v[0:1], 16, v[76:77]
	v_readlane_b32 s90, v241, 28
	v_readlane_b32 s91, v241, 29
	v_mov_b32_e32 v67, v71
	v_mov_b32_e32 v69, v71
	v_lshl_add_u64 v[0:1], s[90:91], 0, v[0:1]
	v_lshl_add_u64 v[0:1], v[74:75], 2, v[0:1]
	v_lshl_add_u64 v[0:1], v[0:1], 0, v[66:67]
	v_lshl_add_u64 v[0:1], v[0:1], 0, v[68:69]
	v_mov_b32_e32 v73, v71
	v_lshl_add_u64 v[24:25], v[0:1], 0, v[72:73]
	v_readlane_b32 s81, v241, 19
	s_mov_b32 s98, s61
	s_mov_b32 s99, 0
	v_lshl_add_u64 v[4:5], v[24:25], 0, s[98:99]
	v_readlane_b32 s82, v241, 20
	s_nop 0
	global_load_dword v12, v[24:25], off
	global_load_dword v13, v[24:25], off offset:512
	global_load_dword v14, v[24:25], off offset:1024
	global_load_dword v15, v[24:25], off offset:1536
	global_load_dword v0, v[4:5], off
	global_load_dword v1, v[4:5], off offset:512
	global_load_dword v2, v[4:5], off offset:1024
	global_load_dword v3, v[4:5], off offset:1536
	s_mov_b32 s98, s62
	s_mov_b32 s99, 0
	v_lshl_add_u64 v[4:5], v[24:25], 0, s[98:99]
	v_readlane_b32 s83, v241, 21
	s_nop 0
	s_mov_b32 s98, s63
	s_mov_b32 s99, 0
	v_lshl_add_u64 v[16:17], v[24:25], 0, s[98:99]
	v_readlane_b32 s84, v241, 22
	s_nop 0
	global_load_dword v8, v[4:5], off
	global_load_dword v9, v[4:5], off offset:512
	global_load_dword v10, v[4:5], off offset:1024
	global_load_dword v11, v[4:5], off offset:1536
	s_nop 0
	global_load_dword v4, v[16:17], off
	global_load_dword v5, v[16:17], off offset:512
	global_load_dword v6, v[16:17], off offset:1024
	global_load_dword v7, v[16:17], off offset:1536
	s_mov_b32 s98, s64
	s_mov_b32 s99, 0
	v_lshl_add_u64 v[16:17], v[24:25], 0, s[98:99]
	v_readlane_b32 s85, v241, 23
	s_nop 0
	s_mov_b32 s98, s65
	s_mov_b32 s99, 0
	v_lshl_add_u64 v[26:27], v[24:25], 0, s[98:99]
	v_readlane_b32 s86, v241, 24
	s_nop 0
	v_add_co_u32_e32 v28, vcc, 0xc000, v24
	global_load_dword v20, v[16:17], off
	global_load_dword v21, v[16:17], off offset:512
	global_load_dword v22, v[16:17], off offset:1024
	global_load_dword v23, v[16:17], off offset:1536
	s_nop 0
	global_load_dword v16, v[26:27], off
	global_load_dword v17, v[26:27], off offset:512
	global_load_dword v18, v[26:27], off offset:1024
	global_load_dword v19, v[26:27], off offset:1536
	v_addc_co_u32_e32 v29, vcc, 0, v25, vcc
	v_add_co_u32_e32 v36, vcc, 0xe000, v24
	v_readlane_b32 s87, v241, 25
	s_nop 0
	v_addc_co_u32_e32 v37, vcc, 0, v25, vcc
	global_load_dword v24, v[28:29], off
	global_load_dword v25, v[28:29], off offset:512
	global_load_dword v26, v[28:29], off offset:1024
	global_load_dword v27, v[28:29], off offset:1536
	s_nop 0
	global_load_dword v28, v[36:37], off
	global_load_dword v29, v[36:37], off offset:512
	global_load_dword v30, v[36:37], off offset:1024
	global_load_dword v31, v[36:37], off offset:1536
	v_readlane_b32 s88, v241, 26
	v_readlane_b32 s89, v241, 27
	v_readlane_b32 s92, v241, 30
	v_readlane_b32 s93, v241, 31
	v_readlane_b32 s94, v241, 32
	v_readlane_b32 s95, v241, 33
	v_readlane_b32 s80, v241, 37
	v_readlane_b32 s92, v241, 49
	v_readlane_b32 s93, v241, 50
	v_readlane_b32 s94, v241, 51
	v_readlane_b32 s95, v241, 52
	v_readlane_b32 s81, v241, 38
	v_readlane_b32 s82, v241, 39
	v_readlane_b32 s83, v241, 40
	v_readlane_b32 s84, v241, 41
	v_readlane_b32 s85, v241, 42
	v_readlane_b32 s86, v241, 43
	v_readlane_b32 s87, v241, 44
	v_readlane_b32 s88, v241, 45
	v_readlane_b32 s89, v241, 46
	v_readlane_b32 s90, v241, 47
	v_readlane_b32 s91, v241, 48
.LBB0_1505:
	s_or_b64 exec, exec, s[56:57]
	v_ashrrev_i32_e32 v33, 31, v32
	v_lshlrev_b64 v[36:37], 11, v[32:33]
	s_mov_b64 s[56:57], 0x2000
	v_lshl_add_u64 v[36:37], v[36:37], 0, s[56:57]
	v_lshlrev_b64 v[32:33], 8, v[32:33]
	v_cndmask_b32_e64 v33, v37, v33, s[40:41]
	v_cndmask_b32_e64 v32, v36, v32, s[40:41]
	v_lshlrev_b64 v[32:33], 11, v[32:33]
	v_lshl_add_u64 v[36:37], s[68:69], 0, v[32:33]
	v_lshlrev_b32_e32 v70, 8, v34
	v_lshl_add_u64 v[38:39], s[46:47], 0, v[32:33]
	v_lshl_add_u64 v[34:35], v[36:37], 0, v[70:71]
	v_lshl_add_u64 v[36:37], s[44:45], 0, v[32:33]
	v_lshl_add_u64 v[38:39], v[38:39], 0, v[70:71]
	v_lshlrev_b64 v[40:41], 1, v[74:75]
	v_lshl_add_u64 v[32:33], s[48:49], 0, v[32:33]
	v_lshl_add_u64 v[36:37], v[36:37], 0, v[70:71]
	v_lshl_add_u64 v[38:39], v[38:39], 0, v[40:41]
	v_lshl_add_u64 v[32:33], v[32:33], 0, v[70:71]
	v_lshlrev_b32_e32 v70, 2, v102
	v_mov_b32_e32 v65, v71
	v_lshl_add_u64 v[34:35], v[34:35], 0, v[70:71]
	v_lshl_add_u64 v[36:37], v[36:37], 0, v[70:71]
	v_lshl_add_u64 v[38:39], v[38:39], 0, v[64:65]
	v_mov_b64_e32 v[42:43], v[38:39]
	v_mov_b64_e32 v[44:45], v[36:37]
	v_mov_b64_e32 v[46:47], v[34:35]
	global_load_dword v65, v[46:47], off
	global_load_dword v67, v[46:47], off offset:2048
	global_load_dword v69, v[44:45], off
	global_load_dword v73, v[44:45], off offset:2048
	s_mov_b32 s98, s66
	s_mov_b32 s99, 0
	v_lshl_add_u64 v[48:49], v[46:47], 0, s[98:99]
	v_lshl_add_u64 v[32:33], v[32:33], 0, v[40:41]
	s_mov_b32 s98, s66
	s_mov_b32 s99, 0
	v_lshl_add_u64 v[50:51], v[44:45], 0, s[98:99]
	v_lshlrev_b32_e32 v70, 1, v112
	global_load_dword v96, v[48:49], off
	global_load_dword v97, v[48:49], off offset:2048
	global_load_dword v98, v[50:51], off
	global_load_dword v122, v[50:51], off offset:2048
	s_mov_b32 s98, s61
	s_mov_b32 s99, 0
	v_lshl_add_u64 v[48:49], v[46:47], 0, s[98:99]
	v_cndmask_b32_e64 v133, 32, 4, s[40:41]
	s_mov_b32 s98, s61
	s_mov_b32 s99, 0
	v_lshl_add_u64 v[50:51], v[44:45], 0, s[98:99]
	s_mov_b32 s74, 0
	global_load_dword v123, v[48:49], off
	global_load_dword v124, v[48:49], off offset:2048
	global_load_dword v125, v[50:51], off
	global_load_dword v126, v[50:51], off offset:2048
	s_mov_b32 s98, s67
	s_mov_b32 s99, 0
	v_lshl_add_u64 v[48:49], v[46:47], 0, s[98:99]
	v_lshl_add_u64 v[78:79], v[32:33], 0, v[70:71]
	s_mov_b32 s98, s67
	s_mov_b32 s99, 0
	v_lshl_add_u64 v[50:51], v[44:45], 0, s[98:99]
	v_lshl_add_u64 v[80:81], v[38:39], 0, s[54:55]
	global_load_dword v127, v[48:49], off
	global_load_dword v128, v[48:49], off offset:2048
	global_load_dword v129, v[50:51], off
	global_load_dword v130, v[50:51], off offset:2048
	s_mov_b32 s98, s62
	s_mov_b32 s99, 0
	v_lshl_add_u64 v[48:49], v[46:47], 0, s[98:99]
	v_lshl_add_u64 v[82:83], v[36:37], 0, s[54:55]
	s_mov_b32 s98, s62
	s_mov_b32 s99, 0
	v_lshl_add_u64 v[50:51], v[44:45], 0, s[98:99]
	v_lshl_add_u64 v[84:85], v[34:35], 0, s[54:55]
	global_load_dword v131, v[48:49], off
	global_load_dword v132, v[48:49], off offset:2048
	global_load_dword v134, v[50:51], off
	global_load_dword v135, v[50:51], off offset:2048
	s_mov_b32 s98, s72
	s_mov_b32 s99, 0
	v_lshl_add_u64 v[48:49], v[46:47], 0, s[98:99]
	s_mov_b64 s[56:57], 0
	s_mov_b32 s98, s72
	s_mov_b32 s99, 0
	v_lshl_add_u64 v[50:51], v[44:45], 0, s[98:99]
	v_mov_b32_e32 v70, v90
	global_load_dword v136, v[48:49], off
	global_load_dword v137, v[48:49], off offset:2048
	global_load_dword v138, v[50:51], off
	global_load_dword v139, v[50:51], off offset:2048
	s_mov_b32 s98, s63
	s_mov_b32 s99, 0
	v_lshl_add_u64 v[48:49], v[46:47], 0, s[98:99]
	s_mov_b32 s98, s63
	s_mov_b32 s99, 0
	v_lshl_add_u64 v[50:51], v[44:45], 0, s[98:99]
	s_mov_b32 s98, s73
	s_mov_b32 s99, 0
	v_lshl_add_u64 v[46:47], v[46:47], 0, s[98:99]
	global_load_dword v140, v[48:49], off
	global_load_dword v141, v[48:49], off offset:2048
	global_load_dword v142, v[50:51], off
	global_load_dword v143, v[50:51], off offset:2048
	s_mov_b32 s98, s73
	s_mov_b32 s99, 0
	v_lshl_add_u64 v[44:45], v[44:45], 0, s[98:99]
	global_load_dword v144, v[46:47], off
	global_load_dword v145, v[46:47], off offset:2048
	global_load_dword v146, v[44:45], off
	global_load_dword v147, v[44:45], off offset:2048
	global_load_dword v148, v[42:43], off
	global_load_dword v149, v[42:43], off offset:2048
	s_mov_b32 s98, s66
	s_mov_b32 s99, 0
	v_lshl_add_u64 v[44:45], v[42:43], 0, s[98:99]
	s_mov_b32 s98, s61
	s_mov_b32 s99, 0
	v_lshl_add_u64 v[46:47], v[42:43], 0, s[98:99]
	v_add_co_u32_e32 v42, vcc, 0x3000, v42
	s_nop 1
	v_addc_co_u32_e32 v43, vcc, 0, v43, vcc
	global_load_dword v150, v[44:45], off
	global_load_dword v151, v[44:45], off offset:2048
	global_load_dword v152, v[46:47], off
	global_load_dword v153, v[46:47], off offset:2048
	global_load_dword v154, v[42:43], off
	global_load_dword v155, v[42:43], off offset:2048
	s_waitcnt vmcnt(0)
	s_branch .LBB0_1507

.LBB0_1509:
	s_or_b64 exec, exec, s[58:59]
	v_lshlrev_b32_e32 v32, 16, v151
	v_lshlrev_b32_e32 v34, 16, v149
	v_lshlrev_b32_e32 v160, 16, v155
	v_lshlrev_b32_e32 v162, 16, v153
	v_or_b32_sdwa v159, v150, v32 dst_sel:DWORD dst_unused:UNUSED_PAD src0_sel:WORD_0 src1_sel:DWORD
	v_or_b32_sdwa v158, v148, v34 dst_sel:DWORD dst_unused:UNUSED_PAD src0_sel:WORD_0 src1_sel:DWORD
	v_add_u32_e32 v32, v108, v109
	v_or_b32_sdwa v161, v154, v160 dst_sel:DWORD dst_unused:UNUSED_PAD src0_sel:WORD_0 src1_sel:DWORD
	v_or_b32_sdwa v160, v152, v162 dst_sel:DWORD dst_unused:UNUSED_PAD src0_sel:WORD_0 src1_sel:DWORD
	v_and_b32_e32 v34, 0xffff0000, v151
	ds_write_b128 v32, v[158:161] offset:35840
	v_and_b32_e32 v158, 0xffff0000, v149
	v_or_b32_sdwa v159, v150, v34 dst_sel:DWORD dst_unused:UNUSED_PAD src0_sel:WORD_1 src1_sel:DWORD
	v_and_b32_e32 v34, 0xffff0000, v155
	v_and_b32_e32 v160, 0xffff0000, v153
	s_add_i32 s74, s74, 1
	v_or_b32_sdwa v158, v148, v158 dst_sel:DWORD dst_unused:UNUSED_PAD src0_sel:WORD_1 src1_sel:DWORD
	v_or_b32_sdwa v161, v154, v34 dst_sel:DWORD dst_unused:UNUSED_PAD src0_sel:WORD_1 src1_sel:DWORD
	v_or_b32_sdwa v160, v152, v160 dst_sel:DWORD dst_unused:UNUSED_PAD src0_sel:WORD_1 src1_sel:DWORD
	v_cmp_lt_u32_e32 vcc, s74, v133
	ds_write_b128 v32, v[158:161] offset:35984
	s_and_saveexec_b64 s[58:59], vcc
	s_cbranch_execz .LBB0_1506
	v_mov_b64_e32 v[144:145], v[82:83]
	v_mov_b64_e32 v[146:147], v[84:85]
	v_mov_b64_e32 v[150:151], v[80:81]
	global_load_dword v65, v[146:147], off
	global_load_dword v67, v[146:147], off offset:2048
	global_load_dword v69, v[144:145], off
	global_load_dword v73, v[144:145], off offset:2048
	s_mov_b64 s[98:99], 0x1000
	v_lshl_add_u64 v[122:123], v[146:147], 0, s[98:99]
	s_mov_b64 s[98:99], 0x1000
	v_lshl_add_u64 v[124:125], v[144:145], 0, s[98:99]
	global_load_dword v96, v[122:123], off
	global_load_dword v97, v[122:123], off offset:2048
	global_load_dword v98, v[124:125], off
	s_nop 0
	global_load_dword v122, v[124:125], off offset:2048
	s_mov_b32 s98, s61
	s_mov_b32 s99, 0
	v_lshl_add_u64 v[124:125], v[146:147], 0, s[98:99]
	s_mov_b32 s98, s61
	s_mov_b32 s99, 0
	v_lshl_add_u64 v[126:127], v[144:145], 0, s[98:99]
	s_mov_b32 s98, s67
	s_mov_b32 s99, 0
	v_lshl_add_u64 v[128:129], v[146:147], 0, s[98:99]
	global_load_dword v123, v[124:125], off
	global_load_dword v124, v[124:125], off offset:2048
	global_load_dword v125, v[126:127], off
	global_load_dword v126, v[126:127], off offset:2048
	s_mov_b32 s98, s67
	s_mov_b32 s99, 0
	v_lshl_add_u64 v[130:131], v[144:145], 0, s[98:99]
	s_mov_b32 s98, s62
	s_mov_b32 s99, 0
	v_lshl_add_u64 v[134:135], v[146:147], 0, s[98:99]
	global_load_dword v127, v[128:129], off
	global_load_dword v128, v[128:129], off offset:2048
	global_load_dword v129, v[130:131], off
	global_load_dword v130, v[130:131], off offset:2048
	s_mov_b32 s98, s62
	s_mov_b32 s99, 0
	v_lshl_add_u64 v[136:137], v[144:145], 0, s[98:99]
	s_mov_b32 s98, s72
	s_mov_b32 s99, 0
	v_lshl_add_u64 v[138:139], v[146:147], 0, s[98:99]
	global_load_dword v131, v[134:135], off
	global_load_dword v132, v[134:135], off offset:2048
	global_load_dword v134, v[136:137], off
	global_load_dword v135, v[136:137], off offset:2048
	s_mov_b32 s98, s72
	s_mov_b32 s99, 0
	v_lshl_add_u64 v[140:141], v[144:145], 0, s[98:99]
	s_mov_b32 s98, s63
	s_mov_b32 s99, 0
	v_lshl_add_u64 v[142:143], v[146:147], 0, s[98:99]
	global_load_dword v136, v[138:139], off
	global_load_dword v137, v[138:139], off offset:2048
	global_load_dword v138, v[140:141], off
	global_load_dword v139, v[140:141], off offset:2048
	s_mov_b32 s98, s63
	s_mov_b32 s99, 0
	v_lshl_add_u64 v[148:149], v[144:145], 0, s[98:99]
	s_mov_b64 s[98:99], 0x7000
	v_lshl_add_u64 v[146:147], v[146:147], 0, s[98:99]
	global_load_dword v140, v[142:143], off
	global_load_dword v141, v[142:143], off offset:2048
	global_load_dword v142, v[148:149], off
	global_load_dword v143, v[148:149], off offset:2048
	s_mov_b64 s[98:99], 0x7000
	v_lshl_add_u64 v[148:149], v[144:145], 0, s[98:99]
	v_add_co_u32_e32 v152, vcc, 0x1000, v150
	global_load_dword v144, v[146:147], off
	global_load_dword v145, v[146:147], off offset:2048
	s_nop 0
	global_load_dword v146, v[148:149], off
	global_load_dword v147, v[148:149], off offset:2048
	s_nop 0
	global_load_dword v148, v[150:151], off
	global_load_dword v149, v[150:151], off offset:2048
	v_addc_co_u32_e32 v153, vcc, 0, v151, vcc
	s_mov_b64 s[98:99], 0x2000
	v_lshl_add_u64 v[154:155], v[150:151], 0, s[98:99]
	v_add_co_u32_e32 v158, vcc, 0x3000, v150
	s_nop 1
	v_addc_co_u32_e32 v159, vcc, 0, v151, vcc
	global_load_dword v150, v[152:153], off
	global_load_dword v151, v[152:153], off offset:2048
	s_nop 0
	global_load_dword v152, v[154:155], off
	global_load_dword v153, v[154:155], off offset:2048
	s_nop 0
	global_load_dword v154, v[158:159], off
	global_load_dword v155, v[158:159], off offset:2048
	s_branch .LBB0_1506
.LBB0_1511:
	s_or_b64 exec, exec, s[56:57]
	s_and_saveexec_b64 s[56:57], s[40:41]
	s_cbranch_execz .LBB0_1502
	v_lshlrev_b64 v[32:33], 16, v[76:77]
	v_lshl_add_u64 v[32:33], s[50:51], 0, v[32:33]
	v_lshl_add_u64 v[32:33], v[74:75], 2, v[32:33]
	s_waitcnt vmcnt(0)
	v_mov_b32_e32 v67, v71
	v_lshl_add_u64 v[32:33], v[32:33], 0, v[66:67]
	v_mov_b32_e32 v69, v71
	v_lshl_add_u64 v[32:33], v[32:33], 0, v[68:69]
	v_mov_b32_e32 v73, v71
	v_lshl_add_u64 v[32:33], v[32:33], 0, v[72:73]
	global_store_dword v[32:33], v12, off
	global_store_dword v[32:33], v13, off offset:512
	global_store_dword v[32:33], v14, off offset:1024
	global_store_dword v[32:33], v15, off offset:1536
	s_mov_b32 s98, s61
	s_mov_b32 s99, 0
	v_lshl_add_u64 v[12:13], v[32:33], 0, s[98:99]
	global_store_dword v[12:13], v0, off
	global_store_dword v[12:13], v1, off offset:512
	global_store_dword v[12:13], v2, off offset:1024
	global_store_dword v[12:13], v3, off offset:1536
	s_mov_b32 s98, s62
	s_mov_b32 s99, 0
	v_lshl_add_u64 v[0:1], v[32:33], 0, s[98:99]
	global_store_dword v[0:1], v8, off
	global_store_dword v[0:1], v9, off offset:512
	global_store_dword v[0:1], v10, off offset:1024
	global_store_dword v[0:1], v11, off offset:1536
	s_mov_b32 s98, s63
	s_mov_b32 s99, 0
	v_lshl_add_u64 v[0:1], v[32:33], 0, s[98:99]
	global_store_dword v[0:1], v4, off
	global_store_dword v[0:1], v5, off offset:512
	global_store_dword v[0:1], v6, off offset:1024
	global_store_dword v[0:1], v7, off offset:1536
	s_mov_b32 s98, s64
	s_mov_b32 s99, 0
	v_lshl_add_u64 v[0:1], v[32:33], 0, s[98:99]
	global_store_dword v[0:1], v20, off
	global_store_dword v[0:1], v21, off offset:512
	global_store_dword v[0:1], v22, off offset:1024
	global_store_dword v[0:1], v23, off offset:1536
	s_mov_b32 s98, s65
	s_mov_b32 s99, 0
	v_lshl_add_u64 v[0:1], v[32:33], 0, s[98:99]
	global_store_dword v[0:1], v16, off
	global_store_dword v[0:1], v17, off offset:512
	global_store_dword v[0:1], v18, off offset:1024
	global_store_dword v[0:1], v19, off offset:1536
	s_mov_b64 s[98:99], 0xc000
	v_lshl_add_u64 v[0:1], v[32:33], 0, s[98:99]
	global_store_dword v[0:1], v24, off
	global_store_dword v[0:1], v25, off offset:512
	global_store_dword v[0:1], v26, off offset:1024
	global_store_dword v[0:1], v27, off offset:1536
	v_add_co_u32_e32 v0, vcc, 0xe000, v32
	s_nop 1
	v_addc_co_u32_e32 v1, vcc, 0, v33, vcc
	global_store_dword v[0:1], v28, off
	global_store_dword v[0:1], v29, off offset:512
	global_store_dword v[0:1], v30, off offset:1024
	global_store_dword v[0:1], v31, off offset:1536
	s_branch .LBB0_1502
